# pb2 + code-placement pin: every K-loop MFMA block starts on an 8-byte boundary (31 s_nop 0 in free load-segment slots)
# speedup vs baseline: 1.0110x; 1.0039x over previous
.Lmy_sk1_pk:
	s_waitcnt lgkmcnt(0)
	s_setprio 1
	s_barrier
	v_mfma_f32_16x16x32_bf16 v[128:131], v[132:135], v[184:187], 0
	v_mfma_f32_16x16x32_bf16 v[124:127], v[140:143], v[184:187], 0
	v_mfma_f32_16x16x32_bf16 v[120:123], v[132:135], v[192:195], 0
	v_mfma_f32_16x16x32_bf16 v[112:115], v[140:143], v[192:195], 0
	v_mfma_f32_16x16x32_bf16 v[104:107], v[132:135], v[208:211], 0
	v_mfma_f32_16x16x32_bf16 v[94:97], v[140:143], v[208:211], 0
	v_mfma_f32_16x16x32_bf16 v[86:89], v[132:135], v[216:219], 0
	v_mfma_f32_16x16x32_bf16 v[78:81], v[140:143], v[216:219], 0
	v_mfma_f32_16x16x32_bf16 v[128:131], v[136:139], v[188:191], v[128:131]
	v_mfma_f32_16x16x32_bf16 v[124:127], v[144:147], v[188:191], v[124:127]
	v_mfma_f32_16x16x32_bf16 v[120:123], v[136:139], v[204:207], v[120:123]
	v_mfma_f32_16x16x32_bf16 v[112:115], v[144:147], v[204:207], v[112:115]
	v_mfma_f32_16x16x32_bf16 v[104:107], v[136:139], v[212:215], v[104:107]
	v_mfma_f32_16x16x32_bf16 v[94:97], v[144:147], v[212:215], v[94:97]
	v_mfma_f32_16x16x32_bf16 v[86:89], v[136:139], v[220:223], v[86:89]
	v_mfma_f32_16x16x32_bf16 v[78:81], v[144:147], v[220:223], v[78:81]
	s_setprio 0
	s_setprio 1
	v_mfma_f32_16x16x32_bf16 v[116:119], v[156:159], v[184:187], 0
	v_mfma_f32_16x16x32_bf16 v[108:111], v[164:167], v[184:187], 0
	v_mfma_f32_16x16x32_bf16 v[100:103], v[156:159], v[192:195], 0
	v_mfma_f32_16x16x32_bf16 v[90:93], v[164:167], v[192:195], 0
	v_mfma_f32_16x16x32_bf16 v[82:85], v[156:159], v[208:211], 0
	v_mfma_f32_16x16x32_bf16 v[74:77], v[164:167], v[208:211], 0
	v_mfma_f32_16x16x32_bf16 v[70:73], v[156:159], v[216:219], 0
	v_mfma_f32_16x16x32_bf16 v[66:69], v[164:167], v[216:219], 0
	v_mfma_f32_16x16x32_bf16 v[116:119], v[160:163], v[188:191], v[116:119]
	v_mfma_f32_16x16x32_bf16 v[108:111], v[180:183], v[188:191], v[108:111]
	v_mfma_f32_16x16x32_bf16 v[100:103], v[160:163], v[204:207], v[100:103]
	v_mfma_f32_16x16x32_bf16 v[90:93], v[180:183], v[204:207], v[90:93]
	v_mfma_f32_16x16x32_bf16 v[82:85], v[160:163], v[212:215], v[82:85]
	v_mfma_f32_16x16x32_bf16 v[74:77], v[180:183], v[212:215], v[74:77]
	v_mfma_f32_16x16x32_bf16 v[70:73], v[160:163], v[220:223], v[70:73]
	v_mfma_f32_16x16x32_bf16 v[66:69], v[180:183], v[220:223], v[66:69]
	s_setprio 0
	s_barrier
	s_add_i32 s5, s44, s77
	v_lshl_add_u64 v[168:169], s[68:69], 0, v[148:149]
	s_mov_b32 m0, s5
	ds_read_b128 v[184:187], v179 offset:16384
	ds_read_b128 v[188:191], v179 offset:17408
	ds_read_b128 v[192:195], v179 offset:18432
	ds_read_b128 v[204:207], v179 offset:19456
	ds_read_b128 v[208:211], v179 offset:20480
	ds_read_b128 v[212:215], v179 offset:21504
	ds_read_b128 v[216:219], v179 offset:22528
	ds_read_b128 v[220:223], v179 offset:23552
	global_load_lds_dwordx4 v[168:169], off
	s_add_i32 m0, s5, 0x2000
	s_add_u32 s44, s68, 0x40000
	v_lshl_add_u64 v[172:173], s[68:69], 0, v[152:153]
	s_addc_u32 s45, s69, 0
	s_add_i32 s4, s4, s77
	global_load_lds_dwordx4 v[172:173], off
	v_lshl_add_u64 v[176:177], s[44:45], 0, v[148:149]
	s_mov_b32 m0, s4
	v_lshl_add_u64 v[200:201], s[70:71], 0, v[150:151]
	global_load_lds_dwordx4 v[176:177], off
	v_lshl_add_u64 v[176:177], s[44:45], 0, v[152:153]
	s_add_i32 m0, s4, 0x2000
	s_nop 0
	global_load_lds_dwordx4 v[176:177], off
	v_lshl_add_u64 v[176:177], s[70:71], 0, v[98:99]
	s_mov_b32 m0, s94
	s_nop 0
	global_load_lds_dwordx4 v[176:177], off
	s_add_i32 m0, s94, 0x2000
	s_nop 0
	global_load_lds_dwordx4 v[200:201], off
	s_nop 0
	s_cmp_eq_u32 s100, 1
	s_cbranch_scc1 .Lmy_sk2_pk
	s_waitcnt vmcnt(8)
.Lmy_sk2_pk:
	s_waitcnt lgkmcnt(0)
	s_setprio 1
	s_barrier
	v_mfma_f32_16x16x32_bf16 v[62:65], v[132:135], v[184:187], 0
	v_mfma_f32_16x16x32_bf16 v[58:61], v[140:143], v[184:187], 0
	v_mfma_f32_16x16x32_bf16 v[54:57], v[132:135], v[192:195], 0
	v_mfma_f32_16x16x32_bf16 v[46:49], v[140:143], v[192:195], 0
	v_mfma_f32_16x16x32_bf16 v[38:41], v[132:135], v[208:211], 0
	v_mfma_f32_16x16x32_bf16 v[30:33], v[140:143], v[208:211], 0
	v_mfma_f32_16x16x32_bf16 v[22:25], v[132:135], v[216:219], 0
	v_mfma_f32_16x16x32_bf16 v[14:17], v[140:143], v[216:219], 0
	v_mfma_f32_16x16x32_bf16 v[62:65], v[136:139], v[188:191], v[62:65]
	v_mfma_f32_16x16x32_bf16 v[58:61], v[144:147], v[188:191], v[58:61]
	v_mfma_f32_16x16x32_bf16 v[54:57], v[136:139], v[204:207], v[54:57]
	v_mfma_f32_16x16x32_bf16 v[46:49], v[144:147], v[204:207], v[46:49]
	v_mfma_f32_16x16x32_bf16 v[38:41], v[136:139], v[212:215], v[38:41]
	v_mfma_f32_16x16x32_bf16 v[30:33], v[144:147], v[212:215], v[30:33]
	v_mfma_f32_16x16x32_bf16 v[22:25], v[136:139], v[220:223], v[22:25]
	v_mfma_f32_16x16x32_bf16 v[14:17], v[144:147], v[220:223], v[14:17]
	s_setprio 0
	s_setprio 1
	v_mfma_f32_16x16x32_bf16 v[50:53], v[156:159], v[184:187], 0
	v_mfma_f32_16x16x32_bf16 v[42:45], v[164:167], v[184:187], 0
	v_mfma_f32_16x16x32_bf16 v[34:37], v[156:159], v[192:195], 0
	v_mfma_f32_16x16x32_bf16 v[26:29], v[164:167], v[192:195], 0
	v_mfma_f32_16x16x32_bf16 v[18:21], v[156:159], v[208:211], 0
	v_mfma_f32_16x16x32_bf16 v[10:13], v[164:167], v[208:211], 0
	v_mfma_f32_16x16x32_bf16 v[6:9], v[156:159], v[216:219], 0
	v_mfma_f32_16x16x32_bf16 v[2:5], v[164:167], v[216:219], 0
	v_mfma_f32_16x16x32_bf16 v[50:53], v[160:163], v[188:191], v[50:53]
	v_mfma_f32_16x16x32_bf16 v[42:45], v[180:183], v[188:191], v[42:45]
	v_mfma_f32_16x16x32_bf16 v[34:37], v[160:163], v[204:207], v[34:37]
	v_mfma_f32_16x16x32_bf16 v[26:29], v[180:183], v[204:207], v[26:29]
	v_mfma_f32_16x16x32_bf16 v[18:21], v[160:163], v[212:215], v[18:21]
	v_mfma_f32_16x16x32_bf16 v[10:13], v[180:183], v[212:215], v[10:13]
	v_mfma_f32_16x16x32_bf16 v[6:9], v[160:163], v[220:223], v[6:9]
	v_mfma_f32_16x16x32_bf16 v[2:5], v[180:183], v[220:223], v[2:5]
	s_setprio 0
	s_barrier
	s_add_i32 s4, 0, 0x18000
	s_add_i32 s5, 0, 0x1c000
	v_add_u32_e32 v144, s4, v175
	v_add_u32_e32 v170, s5, v175
	ds_read_b128 v[132:135], v144
	ds_read_b128 v[136:139], v144 offset:1024
	ds_read_b128 v[140:143], v144 offset:2048
	ds_read_b128 v[144:147], v144 offset:3072
	ds_read_b128 v[156:159], v170
	ds_read_b128 v[160:163], v170 offset:1024
	ds_read_b128 v[164:167], v170 offset:2048
	ds_read_b128 v[180:183], v170 offset:3072
	s_add_u32 s44, s70, 0x40000
	s_addc_u32 s45, s71, 0
	v_lshl_add_u64 v[202:203], s[44:45], 0, v[98:99]
	s_add_i32 m0, s94, 0x4000
	ds_read_b128 v[184:187], v179 offset:32768
	ds_read_b128 v[188:191], v179 offset:33792
	ds_read_b128 v[192:195], v179 offset:34816
	ds_read_b128 v[204:207], v179 offset:35840
	ds_read_b128 v[208:211], v179 offset:36864
	ds_read_b128 v[212:215], v179 offset:37888
	ds_read_b128 v[216:219], v179 offset:38912
	ds_read_b128 v[220:223], v179 offset:39936
	global_load_lds_dwordx4 v[202:203], off
	v_lshl_add_u64 v[202:203], s[44:45], 0, v[150:151]
	s_add_i32 m0, s94, 0x6000
	s_nop 0
	global_load_lds_dwordx4 v[202:203], off
	s_waitcnt vmcnt(8)
	s_waitcnt lgkmcnt(0)
	s_setprio 1
	s_barrier
	v_mfma_f32_16x16x32_bf16 v[128:131], v[132:135], v[184:187], v[128:131]
	v_mfma_f32_16x16x32_bf16 v[124:127], v[140:143], v[184:187], v[124:127]
	v_mfma_f32_16x16x32_bf16 v[120:123], v[132:135], v[192:195], v[120:123]
	v_mfma_f32_16x16x32_bf16 v[112:115], v[140:143], v[192:195], v[112:115]
	v_mfma_f32_16x16x32_bf16 v[104:107], v[132:135], v[208:211], v[104:107]
	v_mfma_f32_16x16x32_bf16 v[94:97], v[140:143], v[208:211], v[94:97]
	v_mfma_f32_16x16x32_bf16 v[86:89], v[132:135], v[216:219], v[86:89]
	v_mfma_f32_16x16x32_bf16 v[78:81], v[140:143], v[216:219], v[78:81]
	v_mfma_f32_16x16x32_bf16 v[128:131], v[136:139], v[188:191], v[128:131]
	v_mfma_f32_16x16x32_bf16 v[124:127], v[144:147], v[188:191], v[124:127]
	v_mfma_f32_16x16x32_bf16 v[120:123], v[136:139], v[204:207], v[120:123]
	v_mfma_f32_16x16x32_bf16 v[112:115], v[144:147], v[204:207], v[112:115]
	v_mfma_f32_16x16x32_bf16 v[104:107], v[136:139], v[212:215], v[104:107]
	v_mfma_f32_16x16x32_bf16 v[94:97], v[144:147], v[212:215], v[94:97]
	v_mfma_f32_16x16x32_bf16 v[86:89], v[136:139], v[220:223], v[86:89]
	v_mfma_f32_16x16x32_bf16 v[78:81], v[144:147], v[220:223], v[78:81]
	s_setprio 0
	s_setprio 1
	v_mfma_f32_16x16x32_bf16 v[116:119], v[156:159], v[184:187], v[116:119]
	v_mfma_f32_16x16x32_bf16 v[108:111], v[164:167], v[184:187], v[108:111]
	v_mfma_f32_16x16x32_bf16 v[100:103], v[156:159], v[192:195], v[100:103]
	v_mfma_f32_16x16x32_bf16 v[90:93], v[164:167], v[192:195], v[90:93]
	v_mfma_f32_16x16x32_bf16 v[82:85], v[156:159], v[208:211], v[82:85]
	v_mfma_f32_16x16x32_bf16 v[74:77], v[164:167], v[208:211], v[74:77]
	v_mfma_f32_16x16x32_bf16 v[70:73], v[156:159], v[216:219], v[70:73]
	v_mfma_f32_16x16x32_bf16 v[66:69], v[164:167], v[216:219], v[66:69]
	v_mfma_f32_16x16x32_bf16 v[116:119], v[160:163], v[188:191], v[116:119]
	v_mfma_f32_16x16x32_bf16 v[108:111], v[180:183], v[188:191], v[108:111]
	v_mfma_f32_16x16x32_bf16 v[100:103], v[160:163], v[204:207], v[100:103]
	v_mfma_f32_16x16x32_bf16 v[90:93], v[180:183], v[204:207], v[90:93]
	v_mfma_f32_16x16x32_bf16 v[82:85], v[160:163], v[212:215], v[82:85]
	v_mfma_f32_16x16x32_bf16 v[74:77], v[180:183], v[212:215], v[74:77]
	v_mfma_f32_16x16x32_bf16 v[70:73], v[160:163], v[220:223], v[70:73]
	v_mfma_f32_16x16x32_bf16 v[66:69], v[180:183], v[220:223], v[66:69]
	s_setprio 0
	s_barrier
	s_add_i32 s4, s4, s77
	v_lshl_add_u64 v[168:169], v[168:169], 0, s[42:43]
	s_mov_b32 m0, s4
	ds_read_b128 v[184:187], v179 offset:49152
	ds_read_b128 v[188:191], v179 offset:50176
	ds_read_b128 v[192:195], v179 offset:51200
	ds_read_b128 v[204:207], v179 offset:52224
	ds_read_b128 v[208:211], v179 offset:53248
	ds_read_b128 v[212:215], v179 offset:54272
	ds_read_b128 v[216:219], v179 offset:55296
	ds_read_b128 v[220:223], v179 offset:56320
	global_load_lds_dwordx4 v[168:169], off
	s_add_i32 m0, s4, 0x2000
	s_add_u32 s44, s68, 0x40080
	v_lshl_add_u64 v[168:169], v[172:173], 0, s[42:43]
	s_addc_u32 s45, s69, 0
	s_add_i32 s4, s5, s77
	global_load_lds_dwordx4 v[168:169], off
	v_lshl_add_u64 v[168:169], s[44:45], 0, v[148:149]
	s_mov_b32 m0, s4
	s_nop 0
	global_load_lds_dwordx4 v[168:169], off
	v_lshl_add_u64 v[168:169], s[44:45], 0, v[152:153]
	s_add_i32 m0, s4, 0x2000
	s_nop 0
	global_load_lds_dwordx4 v[168:169], off
	v_lshl_add_u64 v[168:169], v[176:177], 0, s[42:43]
	s_add_i32 m0, s94, 0x8000
	s_nop 0
	global_load_lds_dwordx4 v[168:169], off
	v_lshl_add_u64 v[168:169], v[200:201], 0, s[42:43]
	s_add_i32 m0, s94, 0xa000
	s_nop 0
	global_load_lds_dwordx4 v[168:169], off
	s_nop 0
	s_waitcnt vmcnt(8)
	s_waitcnt lgkmcnt(0)
	s_setprio 1
	s_barrier
	v_mfma_f32_16x16x32_bf16 v[62:65], v[132:135], v[184:187], v[62:65]
	v_mfma_f32_16x16x32_bf16 v[58:61], v[140:143], v[184:187], v[58:61]
	v_mfma_f32_16x16x32_bf16 v[54:57], v[132:135], v[192:195], v[54:57]
	v_mfma_f32_16x16x32_bf16 v[46:49], v[140:143], v[192:195], v[46:49]
	v_mfma_f32_16x16x32_bf16 v[38:41], v[132:135], v[208:211], v[38:41]
	v_mfma_f32_16x16x32_bf16 v[30:33], v[140:143], v[208:211], v[30:33]
	v_mfma_f32_16x16x32_bf16 v[22:25], v[132:135], v[216:219], v[22:25]
	v_mfma_f32_16x16x32_bf16 v[14:17], v[140:143], v[216:219], v[14:17]
	v_mfma_f32_16x16x32_bf16 v[62:65], v[136:139], v[188:191], v[62:65]
	v_mfma_f32_16x16x32_bf16 v[58:61], v[144:147], v[188:191], v[58:61]
	v_mfma_f32_16x16x32_bf16 v[54:57], v[136:139], v[204:207], v[54:57]
	v_mfma_f32_16x16x32_bf16 v[46:49], v[144:147], v[204:207], v[46:49]
	v_mfma_f32_16x16x32_bf16 v[38:41], v[136:139], v[212:215], v[38:41]
	v_mfma_f32_16x16x32_bf16 v[30:33], v[144:147], v[212:215], v[30:33]
	v_mfma_f32_16x16x32_bf16 v[22:25], v[136:139], v[220:223], v[22:25]
	v_mfma_f32_16x16x32_bf16 v[14:17], v[144:147], v[220:223], v[14:17]
	s_setprio 0
	s_setprio 1
	v_mfma_f32_16x16x32_bf16 v[50:53], v[156:159], v[184:187], v[50:53]
	v_mfma_f32_16x16x32_bf16 v[42:45], v[164:167], v[184:187], v[42:45]
	v_mfma_f32_16x16x32_bf16 v[34:37], v[156:159], v[192:195], v[34:37]
	v_mfma_f32_16x16x32_bf16 v[26:29], v[164:167], v[192:195], v[26:29]
	v_mfma_f32_16x16x32_bf16 v[18:21], v[156:159], v[208:211], v[18:21]
	v_mfma_f32_16x16x32_bf16 v[10:13], v[164:167], v[208:211], v[10:13]
	v_mfma_f32_16x16x32_bf16 v[6:9], v[156:159], v[216:219], v[6:9]
	v_mfma_f32_16x16x32_bf16 v[2:5], v[164:167], v[216:219], v[2:5]
	v_mfma_f32_16x16x32_bf16 v[50:53], v[160:163], v[188:191], v[50:53]
	v_mfma_f32_16x16x32_bf16 v[42:45], v[180:183], v[188:191], v[42:45]
	v_mfma_f32_16x16x32_bf16 v[34:37], v[160:163], v[204:207], v[34:37]
	v_mfma_f32_16x16x32_bf16 v[26:29], v[180:183], v[204:207], v[26:29]
	v_mfma_f32_16x16x32_bf16 v[18:21], v[160:163], v[212:215], v[18:21]
	v_mfma_f32_16x16x32_bf16 v[10:13], v[180:183], v[212:215], v[10:13]
	v_mfma_f32_16x16x32_bf16 v[6:9], v[160:163], v[220:223], v[6:9]
	v_mfma_f32_16x16x32_bf16 v[2:5], v[180:183], v[220:223], v[2:5]
	s_setprio 0
	s_barrier
	s_mov_b32 s100, 0
	s_add_i32 s93, s93, 2
	s_add_u32 s0, s0, 0x100
	s_addc_u32 s1, s1, 0
	s_add_u32 s91, s91, 0x100
	s_addc_u32 s92, s92, 0
	s_cmp_gt_u32 s93, 13
.LBB0_322:
	s_add_u32 s4, s0, 0xfffc0080
	s_addc_u32 s5, s1, -1
	s_add_i32 s44, 0, 0x10000
	s_cmp_eq_u32 s93, 12
	s_cselect_b32 s71, s31, s5
	s_cselect_b32 s70, s39, s4
	s_cselect_b32 s69, s41, s92
	s_cselect_b32 s68, s40, s91
	s_add_i32 s4, 0, 0x14000
	v_add_u32_e32 v144, s44, v175
	v_add_u32_e32 v168, s4, v175
	ds_read_b128 v[132:135], v144
	ds_read_b128 v[136:139], v144 offset:1024
	ds_read_b128 v[140:143], v144 offset:2048
	ds_read_b128 v[144:147], v144 offset:3072
	ds_read_b128 v[156:159], v168
	ds_read_b128 v[160:163], v168 offset:1024
	ds_read_b128 v[164:167], v168 offset:2048
	ds_read_b128 v[180:183], v168 offset:3072
	s_add_i32 s94, s77, 0
	v_lshl_add_u64 v[168:169], s[0:1], 0, v[98:99]
	s_add_i32 m0, s94, 0xc000
	ds_read_b128 v[184:187], v179
	ds_read_b128 v[188:191], v179 offset:1024
	ds_read_b128 v[192:195], v179 offset:2048
	ds_read_b128 v[204:207], v179 offset:3072
	ds_read_b128 v[208:211], v179 offset:4096
	ds_read_b128 v[212:215], v179 offset:5120
	ds_read_b128 v[216:219], v179 offset:6144
	ds_read_b128 v[220:223], v179 offset:7168
	global_load_lds_dwordx4 v[168:169], off
	v_lshl_add_u64 v[168:169], s[0:1], 0, v[150:151]
	s_add_i32 m0, s94, 0xe000
	s_nop 0
	global_load_lds_dwordx4 v[168:169], off
	s_nop 0
	s_waitcnt vmcnt(8)
	s_waitcnt lgkmcnt(0)
	s_setprio 1
	s_barrier
	v_mfma_f32_16x16x32_bf16 v[128:131], v[132:135], v[184:187], v[128:131]
	v_mfma_f32_16x16x32_bf16 v[124:127], v[140:143], v[184:187], v[124:127]
	v_mfma_f32_16x16x32_bf16 v[120:123], v[132:135], v[192:195], v[120:123]
	v_mfma_f32_16x16x32_bf16 v[112:115], v[140:143], v[192:195], v[112:115]
	v_mfma_f32_16x16x32_bf16 v[104:107], v[132:135], v[208:211], v[104:107]
	v_mfma_f32_16x16x32_bf16 v[94:97], v[140:143], v[208:211], v[94:97]
	v_mfma_f32_16x16x32_bf16 v[86:89], v[132:135], v[216:219], v[86:89]
	v_mfma_f32_16x16x32_bf16 v[78:81], v[140:143], v[216:219], v[78:81]
	v_mfma_f32_16x16x32_bf16 v[128:131], v[136:139], v[188:191], v[128:131]
	v_mfma_f32_16x16x32_bf16 v[124:127], v[144:147], v[188:191], v[124:127]
	v_mfma_f32_16x16x32_bf16 v[120:123], v[136:139], v[204:207], v[120:123]
	v_mfma_f32_16x16x32_bf16 v[112:115], v[144:147], v[204:207], v[112:115]
	v_mfma_f32_16x16x32_bf16 v[104:107], v[136:139], v[212:215], v[104:107]
	v_mfma_f32_16x16x32_bf16 v[94:97], v[144:147], v[212:215], v[94:97]
	v_mfma_f32_16x16x32_bf16 v[86:89], v[136:139], v[220:223], v[86:89]
	v_mfma_f32_16x16x32_bf16 v[78:81], v[144:147], v[220:223], v[78:81]
	s_setprio 0
	s_setprio 1
	v_mfma_f32_16x16x32_bf16 v[116:119], v[156:159], v[184:187], v[116:119]
	v_mfma_f32_16x16x32_bf16 v[108:111], v[164:167], v[184:187], v[108:111]
	v_mfma_f32_16x16x32_bf16 v[100:103], v[156:159], v[192:195], v[100:103]
	v_mfma_f32_16x16x32_bf16 v[90:93], v[164:167], v[192:195], v[90:93]
	v_mfma_f32_16x16x32_bf16 v[82:85], v[156:159], v[208:211], v[82:85]
	v_mfma_f32_16x16x32_bf16 v[74:77], v[164:167], v[208:211], v[74:77]
	v_mfma_f32_16x16x32_bf16 v[70:73], v[156:159], v[216:219], v[70:73]
	v_mfma_f32_16x16x32_bf16 v[66:69], v[164:167], v[216:219], v[66:69]
	v_mfma_f32_16x16x32_bf16 v[116:119], v[160:163], v[188:191], v[116:119]
	v_mfma_f32_16x16x32_bf16 v[108:111], v[180:183], v[188:191], v[108:111]
	v_mfma_f32_16x16x32_bf16 v[100:103], v[160:163], v[204:207], v[100:103]
	v_mfma_f32_16x16x32_bf16 v[90:93], v[180:183], v[204:207], v[90:93]
	v_mfma_f32_16x16x32_bf16 v[82:85], v[160:163], v[212:215], v[82:85]
	v_mfma_f32_16x16x32_bf16 v[74:77], v[180:183], v[212:215], v[74:77]
	v_mfma_f32_16x16x32_bf16 v[70:73], v[160:163], v[220:223], v[70:73]
	v_mfma_f32_16x16x32_bf16 v[66:69], v[180:183], v[220:223], v[66:69]
	s_setprio 0
	s_barrier
	s_add_i32 s5, s44, s77
	v_lshl_add_u64 v[168:169], s[68:69], 0, v[148:149]
	s_mov_b32 m0, s5
	ds_read_b128 v[184:187], v179 offset:16384
	ds_read_b128 v[188:191], v179 offset:17408
	ds_read_b128 v[192:195], v179 offset:18432
	ds_read_b128 v[204:207], v179 offset:19456
	ds_read_b128 v[208:211], v179 offset:20480
	ds_read_b128 v[212:215], v179 offset:21504
	ds_read_b128 v[216:219], v179 offset:22528
	ds_read_b128 v[220:223], v179 offset:23552
	global_load_lds_dwordx4 v[168:169], off
	s_add_i32 m0, s5, 0x2000
	s_add_u32 s44, s68, 0x40000
	v_lshl_add_u64 v[172:173], s[68:69], 0, v[152:153]
	s_addc_u32 s45, s69, 0
	s_add_i32 s4, s4, s77
	global_load_lds_dwordx4 v[172:173], off
	v_lshl_add_u64 v[176:177], s[44:45], 0, v[148:149]
	s_mov_b32 m0, s4
	v_lshl_add_u64 v[200:201], s[70:71], 0, v[150:151]
	global_load_lds_dwordx4 v[176:177], off
	v_lshl_add_u64 v[176:177], s[44:45], 0, v[152:153]
	s_add_i32 m0, s4, 0x2000
	s_nop 0
	global_load_lds_dwordx4 v[176:177], off
	v_lshl_add_u64 v[176:177], s[70:71], 0, v[98:99]
	s_mov_b32 m0, s94
	s_nop 0
	global_load_lds_dwordx4 v[176:177], off
	s_add_i32 m0, s94, 0x2000
	s_nop 0
	global_load_lds_dwordx4 v[200:201], off
	s_nop 0
	s_waitcnt vmcnt(8)
	s_waitcnt lgkmcnt(0)
	s_setprio 1
	s_barrier
	v_mfma_f32_16x16x32_bf16 v[62:65], v[132:135], v[184:187], v[62:65]
	v_mfma_f32_16x16x32_bf16 v[58:61], v[140:143], v[184:187], v[58:61]
	v_mfma_f32_16x16x32_bf16 v[54:57], v[132:135], v[192:195], v[54:57]
	v_mfma_f32_16x16x32_bf16 v[46:49], v[140:143], v[192:195], v[46:49]
	v_mfma_f32_16x16x32_bf16 v[38:41], v[132:135], v[208:211], v[38:41]
	v_mfma_f32_16x16x32_bf16 v[30:33], v[140:143], v[208:211], v[30:33]
	v_mfma_f32_16x16x32_bf16 v[22:25], v[132:135], v[216:219], v[22:25]
	v_mfma_f32_16x16x32_bf16 v[14:17], v[140:143], v[216:219], v[14:17]
	v_mfma_f32_16x16x32_bf16 v[62:65], v[136:139], v[188:191], v[62:65]
	v_mfma_f32_16x16x32_bf16 v[58:61], v[144:147], v[188:191], v[58:61]
	v_mfma_f32_16x16x32_bf16 v[54:57], v[136:139], v[204:207], v[54:57]
	v_mfma_f32_16x16x32_bf16 v[46:49], v[144:147], v[204:207], v[46:49]
	v_mfma_f32_16x16x32_bf16 v[38:41], v[136:139], v[212:215], v[38:41]
	v_mfma_f32_16x16x32_bf16 v[30:33], v[144:147], v[212:215], v[30:33]
	v_mfma_f32_16x16x32_bf16 v[22:25], v[136:139], v[220:223], v[22:25]
	v_mfma_f32_16x16x32_bf16 v[14:17], v[144:147], v[220:223], v[14:17]
	s_setprio 0
	s_setprio 1
	v_mfma_f32_16x16x32_bf16 v[50:53], v[156:159], v[184:187], v[50:53]
	v_mfma_f32_16x16x32_bf16 v[42:45], v[164:167], v[184:187], v[42:45]
	v_mfma_f32_16x16x32_bf16 v[34:37], v[156:159], v[192:195], v[34:37]
	v_mfma_f32_16x16x32_bf16 v[26:29], v[164:167], v[192:195], v[26:29]
	v_mfma_f32_16x16x32_bf16 v[18:21], v[156:159], v[208:211], v[18:21]
	v_mfma_f32_16x16x32_bf16 v[10:13], v[164:167], v[208:211], v[10:13]
	v_mfma_f32_16x16x32_bf16 v[6:9], v[156:159], v[216:219], v[6:9]
	v_mfma_f32_16x16x32_bf16 v[2:5], v[164:167], v[216:219], v[2:5]
	v_mfma_f32_16x16x32_bf16 v[50:53], v[160:163], v[188:191], v[50:53]
	v_mfma_f32_16x16x32_bf16 v[42:45], v[180:183], v[188:191], v[42:45]
	v_mfma_f32_16x16x32_bf16 v[34:37], v[160:163], v[204:207], v[34:37]
	v_mfma_f32_16x16x32_bf16 v[26:29], v[180:183], v[204:207], v[26:29]
	v_mfma_f32_16x16x32_bf16 v[18:21], v[160:163], v[212:215], v[18:21]
	v_mfma_f32_16x16x32_bf16 v[10:13], v[180:183], v[212:215], v[10:13]
	v_mfma_f32_16x16x32_bf16 v[6:9], v[160:163], v[220:223], v[6:9]
	v_mfma_f32_16x16x32_bf16 v[2:5], v[180:183], v[220:223], v[2:5]
	s_setprio 0
	s_barrier
	s_add_i32 s4, 0, 0x18000
	s_add_i32 s5, 0, 0x1c000
	v_add_u32_e32 v144, s4, v175
	v_add_u32_e32 v170, s5, v175
	ds_read_b128 v[132:135], v144
	ds_read_b128 v[136:139], v144 offset:1024
	ds_read_b128 v[140:143], v144 offset:2048
	ds_read_b128 v[144:147], v144 offset:3072
	ds_read_b128 v[156:159], v170
	ds_read_b128 v[160:163], v170 offset:1024
	ds_read_b128 v[164:167], v170 offset:2048
	ds_read_b128 v[180:183], v170 offset:3072
	s_add_u32 s44, s70, 0x40000
	s_addc_u32 s45, s71, 0
	v_lshl_add_u64 v[202:203], s[44:45], 0, v[98:99]
	s_add_i32 m0, s94, 0x4000
	ds_read_b128 v[184:187], v179 offset:32768
	ds_read_b128 v[188:191], v179 offset:33792
	ds_read_b128 v[192:195], v179 offset:34816
	ds_read_b128 v[204:207], v179 offset:35840
	ds_read_b128 v[208:211], v179 offset:36864
	ds_read_b128 v[212:215], v179 offset:37888
	ds_read_b128 v[216:219], v179 offset:38912
	ds_read_b128 v[220:223], v179 offset:39936
	global_load_lds_dwordx4 v[202:203], off
	v_lshl_add_u64 v[202:203], s[44:45], 0, v[150:151]
	s_add_i32 m0, s94, 0x6000
	s_nop 0
	global_load_lds_dwordx4 v[202:203], off
	s_waitcnt vmcnt(8)
	s_waitcnt lgkmcnt(0)
	s_setprio 1
	s_barrier
	v_mfma_f32_16x16x32_bf16 v[128:131], v[132:135], v[184:187], v[128:131]
	v_mfma_f32_16x16x32_bf16 v[124:127], v[140:143], v[184:187], v[124:127]
	v_mfma_f32_16x16x32_bf16 v[120:123], v[132:135], v[192:195], v[120:123]
	v_mfma_f32_16x16x32_bf16 v[112:115], v[140:143], v[192:195], v[112:115]
	v_mfma_f32_16x16x32_bf16 v[104:107], v[132:135], v[208:211], v[104:107]
	v_mfma_f32_16x16x32_bf16 v[94:97], v[140:143], v[208:211], v[94:97]
	v_mfma_f32_16x16x32_bf16 v[86:89], v[132:135], v[216:219], v[86:89]
	v_mfma_f32_16x16x32_bf16 v[78:81], v[140:143], v[216:219], v[78:81]
	v_mfma_f32_16x16x32_bf16 v[128:131], v[136:139], v[188:191], v[128:131]
	v_mfma_f32_16x16x32_bf16 v[124:127], v[144:147], v[188:191], v[124:127]
	v_mfma_f32_16x16x32_bf16 v[120:123], v[136:139], v[204:207], v[120:123]
	v_mfma_f32_16x16x32_bf16 v[112:115], v[144:147], v[204:207], v[112:115]
	v_mfma_f32_16x16x32_bf16 v[104:107], v[136:139], v[212:215], v[104:107]
	v_mfma_f32_16x16x32_bf16 v[94:97], v[144:147], v[212:215], v[94:97]
	v_mfma_f32_16x16x32_bf16 v[86:89], v[136:139], v[220:223], v[86:89]
	v_mfma_f32_16x16x32_bf16 v[78:81], v[144:147], v[220:223], v[78:81]
	s_setprio 0
	s_setprio 1
	v_mfma_f32_16x16x32_bf16 v[116:119], v[156:159], v[184:187], v[116:119]
	v_mfma_f32_16x16x32_bf16 v[108:111], v[164:167], v[184:187], v[108:111]
	v_mfma_f32_16x16x32_bf16 v[100:103], v[156:159], v[192:195], v[100:103]
	v_mfma_f32_16x16x32_bf16 v[90:93], v[164:167], v[192:195], v[90:93]
	v_mfma_f32_16x16x32_bf16 v[82:85], v[156:159], v[208:211], v[82:85]
	v_mfma_f32_16x16x32_bf16 v[74:77], v[164:167], v[208:211], v[74:77]
	v_mfma_f32_16x16x32_bf16 v[70:73], v[156:159], v[216:219], v[70:73]
	v_mfma_f32_16x16x32_bf16 v[66:69], v[164:167], v[216:219], v[66:69]
	v_mfma_f32_16x16x32_bf16 v[116:119], v[160:163], v[188:191], v[116:119]
	v_mfma_f32_16x16x32_bf16 v[108:111], v[180:183], v[188:191], v[108:111]
	v_mfma_f32_16x16x32_bf16 v[100:103], v[160:163], v[204:207], v[100:103]
	v_mfma_f32_16x16x32_bf16 v[90:93], v[180:183], v[204:207], v[90:93]
	v_mfma_f32_16x16x32_bf16 v[82:85], v[160:163], v[212:215], v[82:85]
	v_mfma_f32_16x16x32_bf16 v[74:77], v[180:183], v[212:215], v[74:77]
	v_mfma_f32_16x16x32_bf16 v[70:73], v[160:163], v[220:223], v[70:73]
	v_mfma_f32_16x16x32_bf16 v[66:69], v[180:183], v[220:223], v[66:69]
	s_setprio 0
	s_barrier
	s_add_i32 s4, s4, s77
	v_lshl_add_u64 v[168:169], v[168:169], 0, s[42:43]
	s_mov_b32 m0, s4
	ds_read_b128 v[184:187], v179 offset:49152
	ds_read_b128 v[188:191], v179 offset:50176
	ds_read_b128 v[192:195], v179 offset:51200
	ds_read_b128 v[204:207], v179 offset:52224
	ds_read_b128 v[208:211], v179 offset:53248
	ds_read_b128 v[212:215], v179 offset:54272
	ds_read_b128 v[216:219], v179 offset:55296
	ds_read_b128 v[220:223], v179 offset:56320
	global_load_lds_dwordx4 v[168:169], off
	s_add_i32 m0, s4, 0x2000
	s_add_u32 s44, s68, 0x40080
	v_lshl_add_u64 v[168:169], v[172:173], 0, s[42:43]
	s_addc_u32 s45, s69, 0
	s_add_i32 s4, s5, s77
	global_load_lds_dwordx4 v[168:169], off
	v_lshl_add_u64 v[168:169], s[44:45], 0, v[148:149]
	s_mov_b32 m0, s4
	s_nop 0
	global_load_lds_dwordx4 v[168:169], off
	v_lshl_add_u64 v[168:169], s[44:45], 0, v[152:153]
	s_add_i32 m0, s4, 0x2000
	s_nop 0
	global_load_lds_dwordx4 v[168:169], off
	v_lshl_add_u64 v[168:169], v[176:177], 0, s[42:43]
	s_add_i32 m0, s94, 0x8000
	s_nop 0
	global_load_lds_dwordx4 v[168:169], off
	v_lshl_add_u64 v[168:169], v[200:201], 0, s[42:43]
	s_add_i32 m0, s94, 0xa000
	s_nop 0
	global_load_lds_dwordx4 v[168:169], off
	s_nop 0
	s_waitcnt vmcnt(8)
	s_waitcnt lgkmcnt(0)
	s_setprio 1
	s_barrier
	v_mfma_f32_16x16x32_bf16 v[62:65], v[132:135], v[184:187], v[62:65]
	v_mfma_f32_16x16x32_bf16 v[58:61], v[140:143], v[184:187], v[58:61]
	v_mfma_f32_16x16x32_bf16 v[54:57], v[132:135], v[192:195], v[54:57]
	v_mfma_f32_16x16x32_bf16 v[46:49], v[140:143], v[192:195], v[46:49]
	v_mfma_f32_16x16x32_bf16 v[38:41], v[132:135], v[208:211], v[38:41]
	v_mfma_f32_16x16x32_bf16 v[30:33], v[140:143], v[208:211], v[30:33]
	v_mfma_f32_16x16x32_bf16 v[22:25], v[132:135], v[216:219], v[22:25]
	v_mfma_f32_16x16x32_bf16 v[14:17], v[140:143], v[216:219], v[14:17]
	v_mfma_f32_16x16x32_bf16 v[62:65], v[136:139], v[188:191], v[62:65]
	v_mfma_f32_16x16x32_bf16 v[58:61], v[144:147], v[188:191], v[58:61]
	v_mfma_f32_16x16x32_bf16 v[54:57], v[136:139], v[204:207], v[54:57]
	v_mfma_f32_16x16x32_bf16 v[46:49], v[144:147], v[204:207], v[46:49]
	v_mfma_f32_16x16x32_bf16 v[38:41], v[136:139], v[212:215], v[38:41]
	v_mfma_f32_16x16x32_bf16 v[30:33], v[144:147], v[212:215], v[30:33]
	v_mfma_f32_16x16x32_bf16 v[22:25], v[136:139], v[220:223], v[22:25]
	v_mfma_f32_16x16x32_bf16 v[14:17], v[144:147], v[220:223], v[14:17]
	s_setprio 0
	s_setprio 1
	v_mfma_f32_16x16x32_bf16 v[50:53], v[156:159], v[184:187], v[50:53]
	v_mfma_f32_16x16x32_bf16 v[42:45], v[164:167], v[184:187], v[42:45]
	v_mfma_f32_16x16x32_bf16 v[34:37], v[156:159], v[192:195], v[34:37]
	v_mfma_f32_16x16x32_bf16 v[26:29], v[164:167], v[192:195], v[26:29]
	v_mfma_f32_16x16x32_bf16 v[18:21], v[156:159], v[208:211], v[18:21]
	v_mfma_f32_16x16x32_bf16 v[10:13], v[164:167], v[208:211], v[10:13]
	v_mfma_f32_16x16x32_bf16 v[6:9], v[156:159], v[216:219], v[6:9]
	v_mfma_f32_16x16x32_bf16 v[2:5], v[164:167], v[216:219], v[2:5]
	v_mfma_f32_16x16x32_bf16 v[50:53], v[160:163], v[188:191], v[50:53]
	v_mfma_f32_16x16x32_bf16 v[42:45], v[180:183], v[188:191], v[42:45]
	v_mfma_f32_16x16x32_bf16 v[34:37], v[160:163], v[204:207], v[34:37]
	v_mfma_f32_16x16x32_bf16 v[26:29], v[180:183], v[204:207], v[26:29]
	v_mfma_f32_16x16x32_bf16 v[18:21], v[160:163], v[212:215], v[18:21]
	v_mfma_f32_16x16x32_bf16 v[10:13], v[180:183], v[212:215], v[10:13]
	v_mfma_f32_16x16x32_bf16 v[6:9], v[160:163], v[220:223], v[6:9]
	v_mfma_f32_16x16x32_bf16 v[2:5], v[180:183], v[220:223], v[2:5]
	s_setprio 0
	s_barrier
	s_add_i32 s93, s93, 2
	s_add_u32 s0, s0, 0x100
	s_addc_u32 s1, s1, 0
	s_add_u32 s91, s91, 0x100
	s_addc_u32 s92, s92, 0
	s_cmp_gt_u32 s93, 13
	s_cbranch_scc0 .LBB0_322
	s_mov_b32 s100, 1
	s_and_b64 vcc, exec, s[14:15]
	s_cbranch_vccz .LBB0_325
	s_lshl_b32 s0, s89, 8
	v_add_u32_e32 v176, s0, v171
	v_ashrrev_i32_e32 v177, 31, v176
	v_or_b32_e32 v172, 16, v176
	v_lshlrev_b64 v[132:133], 6, v[176:177]
	v_ashrrev_i32_e32 v173, 31, v172
	v_or_b32_e32 v168, 32, v176
	v_lshl_add_u64 v[132:133], v[154:155], 0, v[132:133]
	v_lshlrev_b64 v[134:135], 6, v[172:173]
	v_ashrrev_i32_e32 v169, 31, v168
	v_lshl_add_u64 v[134:135], v[154:155], 0, v[134:135]
	global_load_dwordx4 v[180:183], v[132:133], off
	global_load_dwordx4 v[184:187], v[134:135], off
	v_lshlrev_b64 v[132:133], 6, v[168:169]
	v_lshl_add_u64 v[132:133], v[154:155], 0, v[132:133]
	global_load_dwordx4 v[188:191], v[132:133], off
	v_or_b32_e32 v166, 48, v176
	v_ashrrev_i32_e32 v167, 31, v166
	v_lshlrev_b64 v[132:133], 6, v[166:167]
	v_lshl_add_u64 v[132:133], v[154:155], 0, v[132:133]
	global_load_dwordx4 v[192:195], v[132:133], off
	v_add_u32_e32 v162, 0x80, v176
	v_ashrrev_i32_e32 v163, 31, v162
	v_lshlrev_b64 v[132:133], 6, v[162:163]
	v_lshl_add_u64 v[132:133], v[154:155], 0, v[132:133]
	global_load_dwordx4 v[204:207], v[132:133], off
	s_addk_i32 s0, 0xc000
	s_lshr_b32 s0, s0, 12
	v_add_u32_e32 v164, 0x90, v176
	s_ashr_i32 s1, s89, 5
	v_and_b32_e32 v132, 64, v229
	v_ashrrev_i32_e32 v165, 31, v164
	s_add_i32 s0, s0, 2
	v_add_u32_e32 v136, 64, v132
	v_lshlrev_b64 v[132:133], 6, v[164:165]
	v_add_u32_e32 v160, 0xa0, v176
	s_cmp_lt_i32 s89, 64
	v_lshl_add_u64 v[132:133], v[154:155], 0, v[132:133]
	v_ashrrev_i32_e32 v161, 31, v160
	s_cselect_b32 s0, s1, s0
	v_xor_b32_e32 v134, 16, v229
	global_load_dwordx4 v[208:211], v[132:133], off
	v_add_u32_e32 v158, 0xb0, v176
	v_lshlrev_b64 v[132:133], 6, v[160:161]
	s_mul_hi_i32 s1, s0, 0x1800
	s_mulk_i32 s0, 0x1800
	v_lshl_or_b32 v156, s90, 8, v178
	v_xor_b32_e32 v135, 32, v229
	v_cmp_lt_i32_e32 vcc, v134, v136
	v_ashrrev_i32_e32 v159, 31, v158
	v_lshl_add_u64 v[132:133], v[154:155], 0, v[132:133]
	s_add_u32 s0, s78, s0
	v_ashrrev_i32_e32 v157, 31, v156
	v_cndmask_b32_e32 v134, v229, v134, vcc
	v_cmp_lt_i32_e32 vcc, v135, v136
	global_load_dwordx4 v[212:215], v[132:133], off
	v_lshlrev_b64 v[132:133], 6, v[158:159]
	s_addc_u32 s1, s79, s1
	v_cndmask_b32_e32 v135, v229, v135, vcc
	v_lshl_add_u64 v[132:133], v[154:155], 0, v[132:133]
	v_lshl_add_u64 v[136:137], v[156:157], 2, s[0:1]
	v_lshlrev_b32_e32 v161, 2, v134
	v_lshlrev_b32_e32 v163, 2, v135
	global_load_dwordx4 v[216:219], v[132:133], off
	global_load_dwordx4 v[140:143], v[136:137], off offset:16
	global_load_dwordx4 v[144:147], v[136:137], off
	s_nop 0
	global_load_dwordx4 v[132:135], v[136:137], off offset:528
	s_nop 0
	global_load_dwordx4 v[136:139], v[136:137], off offset:512
	s_barrier
	s_branch .Lmy_g1_afterload

.Lmy_sk3_pk:
	s_waitcnt lgkmcnt(0)
	s_setprio 1
	s_barrier
	v_mfma_f32_16x16x32_bf16 v[160:163], v[90:93], v[164:167], 0
	v_mfma_f32_16x16x32_bf16 v[156:159], v[100:103], v[164:167], 0
	v_mfma_f32_16x16x32_bf16 v[144:147], v[90:93], v[172:175], 0
	v_mfma_f32_16x16x32_bf16 v[140:143], v[100:103], v[172:175], 0
	v_mfma_f32_16x16x32_bf16 v[124:127], v[90:93], v[180:183], 0
	v_mfma_f32_16x16x32_bf16 v[116:119], v[100:103], v[180:183], 0
	v_mfma_f32_16x16x32_bf16 v[78:81], v[90:93], v[188:191], 0
	v_mfma_f32_16x16x32_bf16 v[74:77], v[100:103], v[188:191], 0
	v_mfma_f32_16x16x32_bf16 v[160:163], v[94:97], v[168:171], v[160:163]
	v_mfma_f32_16x16x32_bf16 v[156:159], v[104:107], v[168:171], v[156:159]
	v_mfma_f32_16x16x32_bf16 v[144:147], v[94:97], v[176:179], v[144:147]
	v_mfma_f32_16x16x32_bf16 v[140:143], v[104:107], v[176:179], v[140:143]
	v_mfma_f32_16x16x32_bf16 v[124:127], v[94:97], v[184:187], v[124:127]
	v_mfma_f32_16x16x32_bf16 v[116:119], v[104:107], v[184:187], v[116:119]
	v_mfma_f32_16x16x32_bf16 v[78:81], v[94:97], v[192:195], v[78:81]
	v_mfma_f32_16x16x32_bf16 v[74:77], v[104:107], v[192:195], v[74:77]
	s_setprio 0
	s_setprio 1
	v_mfma_f32_16x16x32_bf16 v[152:155], v[108:111], v[164:167], 0
	v_mfma_f32_16x16x32_bf16 v[148:151], v[120:123], v[164:167], 0
	v_mfma_f32_16x16x32_bf16 v[136:139], v[108:111], v[172:175], 0
	v_mfma_f32_16x16x32_bf16 v[132:135], v[120:123], v[172:175], 0
	v_mfma_f32_16x16x32_bf16 v[86:89], v[108:111], v[180:183], 0
	v_mfma_f32_16x16x32_bf16 v[82:85], v[120:123], v[180:183], 0
	v_mfma_f32_16x16x32_bf16 v[70:73], v[108:111], v[188:191], 0
	v_mfma_f32_16x16x32_bf16 v[66:69], v[120:123], v[188:191], 0
	v_mfma_f32_16x16x32_bf16 v[152:155], v[112:115], v[168:171], v[152:155]
	v_mfma_f32_16x16x32_bf16 v[148:151], v[128:131], v[168:171], v[148:151]
	v_mfma_f32_16x16x32_bf16 v[136:139], v[112:115], v[176:179], v[136:139]
	v_mfma_f32_16x16x32_bf16 v[132:135], v[128:131], v[176:179], v[132:135]
	v_mfma_f32_16x16x32_bf16 v[86:89], v[112:115], v[184:187], v[86:89]
	v_mfma_f32_16x16x32_bf16 v[82:85], v[128:131], v[184:187], v[82:85]
	v_mfma_f32_16x16x32_bf16 v[70:73], v[112:115], v[192:195], v[70:73]
	v_mfma_f32_16x16x32_bf16 v[66:69], v[128:131], v[192:195], v[66:69]
	s_setprio 0
	s_barrier
	s_add_i32 s4, s45, s91
	v_lshl_add_u64 v[200:201], s[70:71], 0, v[204:205]
	s_mov_b32 m0, s4
	ds_read_b128 v[164:167], v241 offset:16384
	ds_read_b128 v[168:171], v241 offset:17408
	ds_read_b128 v[172:175], v241 offset:18432
	ds_read_b128 v[176:179], v241 offset:19456
	ds_read_b128 v[180:183], v241 offset:20480
	ds_read_b128 v[184:187], v241 offset:21504
	ds_read_b128 v[188:191], v241 offset:22528
	ds_read_b128 v[192:195], v241 offset:23552
	global_load_lds_dwordx4 v[200:201], off
	s_add_i32 m0, s4, 0x2000
	s_add_u32 s4, s70, 0x40000
	v_lshl_add_u64 v[202:203], s[70:71], 0, v[208:209]
	s_addc_u32 s5, s71, 0
	s_add_i32 s6, s6, s91
	global_load_lds_dwordx4 v[202:203], off
	v_lshl_add_u64 v[210:211], s[4:5], 0, v[204:205]
	s_mov_b32 m0, s6
	v_lshl_add_u64 v[212:213], s[74:75], 0, v[206:207]
	global_load_lds_dwordx4 v[210:211], off
	v_lshl_add_u64 v[210:211], s[4:5], 0, v[208:209]
	s_add_i32 m0, s6, 0x2000
	s_nop 0
	global_load_lds_dwordx4 v[210:211], off
	v_lshl_add_u64 v[210:211], s[74:75], 0, v[98:99]
	s_mov_b32 m0, s44
	s_nop 0
	global_load_lds_dwordx4 v[210:211], off
	s_add_i32 m0, s44, 0x2000
	s_nop 0
	global_load_lds_dwordx4 v[212:213], off
	s_nop 0
	s_cmp_eq_u32 s100, 1
	s_cbranch_scc1 .Lmy_sk4_pk
	s_waitcnt vmcnt(8)
.Lmy_sk4_pk:
	s_waitcnt lgkmcnt(0)
	s_setprio 1
	s_barrier
	v_mfma_f32_16x16x32_bf16 v[62:65], v[90:93], v[164:167], 0
	v_mfma_f32_16x16x32_bf16 v[58:61], v[100:103], v[164:167], 0
	v_mfma_f32_16x16x32_bf16 v[46:49], v[90:93], v[172:175], 0
	v_mfma_f32_16x16x32_bf16 v[42:45], v[100:103], v[172:175], 0
	v_mfma_f32_16x16x32_bf16 v[30:33], v[90:93], v[180:183], 0
	v_mfma_f32_16x16x32_bf16 v[26:29], v[100:103], v[180:183], 0
	v_mfma_f32_16x16x32_bf16 v[14:17], v[90:93], v[188:191], 0
	v_mfma_f32_16x16x32_bf16 v[10:13], v[100:103], v[188:191], 0
	v_mfma_f32_16x16x32_bf16 v[62:65], v[94:97], v[168:171], v[62:65]
	v_mfma_f32_16x16x32_bf16 v[58:61], v[104:107], v[168:171], v[58:61]
	v_mfma_f32_16x16x32_bf16 v[46:49], v[94:97], v[176:179], v[46:49]
	v_mfma_f32_16x16x32_bf16 v[42:45], v[104:107], v[176:179], v[42:45]
	v_mfma_f32_16x16x32_bf16 v[30:33], v[94:97], v[184:187], v[30:33]
	v_mfma_f32_16x16x32_bf16 v[26:29], v[104:107], v[184:187], v[26:29]
	v_mfma_f32_16x16x32_bf16 v[14:17], v[94:97], v[192:195], v[14:17]
	v_mfma_f32_16x16x32_bf16 v[10:13], v[104:107], v[192:195], v[10:13]
	s_setprio 0
	s_setprio 1
	v_mfma_f32_16x16x32_bf16 v[54:57], v[108:111], v[164:167], 0
	v_mfma_f32_16x16x32_bf16 v[50:53], v[120:123], v[164:167], 0
	v_mfma_f32_16x16x32_bf16 v[38:41], v[108:111], v[172:175], 0
	v_mfma_f32_16x16x32_bf16 v[34:37], v[120:123], v[172:175], 0
	v_mfma_f32_16x16x32_bf16 v[22:25], v[108:111], v[180:183], 0
	v_mfma_f32_16x16x32_bf16 v[18:21], v[120:123], v[180:183], 0
	v_mfma_f32_16x16x32_bf16 v[6:9], v[108:111], v[188:191], 0
	v_mfma_f32_16x16x32_bf16 v[2:5], v[120:123], v[188:191], 0
	v_mfma_f32_16x16x32_bf16 v[54:57], v[112:115], v[168:171], v[54:57]
	v_mfma_f32_16x16x32_bf16 v[50:53], v[128:131], v[168:171], v[50:53]
	v_mfma_f32_16x16x32_bf16 v[38:41], v[112:115], v[176:179], v[38:41]
	v_mfma_f32_16x16x32_bf16 v[34:37], v[128:131], v[176:179], v[34:37]
	v_mfma_f32_16x16x32_bf16 v[22:25], v[112:115], v[184:187], v[22:25]
	v_mfma_f32_16x16x32_bf16 v[18:21], v[128:131], v[184:187], v[18:21]
	v_mfma_f32_16x16x32_bf16 v[6:9], v[112:115], v[192:195], v[6:9]
	v_mfma_f32_16x16x32_bf16 v[2:5], v[128:131], v[192:195], v[2:5]
	s_setprio 0
	s_barrier
	s_add_i32 s6, 0, 0x18000
	s_add_i32 s7, 0, 0x1c000
	v_add_u32_e32 v104, s6, v239
	v_add_u32_e32 v128, s7, v239
	ds_read_b128 v[90:93], v104
	ds_read_b128 v[94:97], v104 offset:1024
	ds_read_b128 v[100:103], v104 offset:2048
	ds_read_b128 v[104:107], v104 offset:3072
	ds_read_b128 v[108:111], v128
	ds_read_b128 v[112:115], v128 offset:1024
	ds_read_b128 v[120:123], v128 offset:2048
	ds_read_b128 v[128:131], v128 offset:3072
	s_add_u32 s4, s74, 0x40000
	s_addc_u32 s5, s75, 0
	v_lshl_add_u64 v[214:215], s[4:5], 0, v[98:99]
	s_add_i32 m0, s44, 0x4000
	ds_read_b128 v[164:167], v241 offset:32768
	ds_read_b128 v[168:171], v241 offset:33792
	ds_read_b128 v[172:175], v241 offset:34816
	ds_read_b128 v[176:179], v241 offset:35840
	ds_read_b128 v[180:183], v241 offset:36864
	ds_read_b128 v[184:187], v241 offset:37888
	ds_read_b128 v[188:191], v241 offset:38912
	ds_read_b128 v[192:195], v241 offset:39936
	global_load_lds_dwordx4 v[214:215], off
	v_lshl_add_u64 v[214:215], s[4:5], 0, v[206:207]
	s_add_i32 m0, s44, 0x6000
	s_nop 0
	global_load_lds_dwordx4 v[214:215], off
	s_waitcnt vmcnt(8)
	s_waitcnt lgkmcnt(0)
	s_setprio 1
	s_barrier
	v_mfma_f32_16x16x32_bf16 v[160:163], v[90:93], v[164:167], v[160:163]
	v_mfma_f32_16x16x32_bf16 v[156:159], v[100:103], v[164:167], v[156:159]
	v_mfma_f32_16x16x32_bf16 v[144:147], v[90:93], v[172:175], v[144:147]
	v_mfma_f32_16x16x32_bf16 v[140:143], v[100:103], v[172:175], v[140:143]
	v_mfma_f32_16x16x32_bf16 v[124:127], v[90:93], v[180:183], v[124:127]
	v_mfma_f32_16x16x32_bf16 v[116:119], v[100:103], v[180:183], v[116:119]
	v_mfma_f32_16x16x32_bf16 v[78:81], v[90:93], v[188:191], v[78:81]
	v_mfma_f32_16x16x32_bf16 v[74:77], v[100:103], v[188:191], v[74:77]
	v_mfma_f32_16x16x32_bf16 v[160:163], v[94:97], v[168:171], v[160:163]
	v_mfma_f32_16x16x32_bf16 v[156:159], v[104:107], v[168:171], v[156:159]
	v_mfma_f32_16x16x32_bf16 v[144:147], v[94:97], v[176:179], v[144:147]
	v_mfma_f32_16x16x32_bf16 v[140:143], v[104:107], v[176:179], v[140:143]
	v_mfma_f32_16x16x32_bf16 v[124:127], v[94:97], v[184:187], v[124:127]
	v_mfma_f32_16x16x32_bf16 v[116:119], v[104:107], v[184:187], v[116:119]
	v_mfma_f32_16x16x32_bf16 v[78:81], v[94:97], v[192:195], v[78:81]
	v_mfma_f32_16x16x32_bf16 v[74:77], v[104:107], v[192:195], v[74:77]
	s_setprio 0
	s_setprio 1
	v_mfma_f32_16x16x32_bf16 v[152:155], v[108:111], v[164:167], v[152:155]
	v_mfma_f32_16x16x32_bf16 v[148:151], v[120:123], v[164:167], v[148:151]
	v_mfma_f32_16x16x32_bf16 v[136:139], v[108:111], v[172:175], v[136:139]
	v_mfma_f32_16x16x32_bf16 v[132:135], v[120:123], v[172:175], v[132:135]
	v_mfma_f32_16x16x32_bf16 v[86:89], v[108:111], v[180:183], v[86:89]
	v_mfma_f32_16x16x32_bf16 v[82:85], v[120:123], v[180:183], v[82:85]
	v_mfma_f32_16x16x32_bf16 v[70:73], v[108:111], v[188:191], v[70:73]
	v_mfma_f32_16x16x32_bf16 v[66:69], v[120:123], v[188:191], v[66:69]
	v_mfma_f32_16x16x32_bf16 v[152:155], v[112:115], v[168:171], v[152:155]
	v_mfma_f32_16x16x32_bf16 v[148:151], v[128:131], v[168:171], v[148:151]
	v_mfma_f32_16x16x32_bf16 v[136:139], v[112:115], v[176:179], v[136:139]
	v_mfma_f32_16x16x32_bf16 v[132:135], v[128:131], v[176:179], v[132:135]
	v_mfma_f32_16x16x32_bf16 v[86:89], v[112:115], v[184:187], v[86:89]
	v_mfma_f32_16x16x32_bf16 v[82:85], v[128:131], v[184:187], v[82:85]
	v_mfma_f32_16x16x32_bf16 v[70:73], v[112:115], v[192:195], v[70:73]
	v_mfma_f32_16x16x32_bf16 v[66:69], v[128:131], v[192:195], v[66:69]
	s_setprio 0
	s_barrier
	s_add_i32 s4, s6, s91
	v_lshl_add_u64 v[200:201], v[200:201], 0, s[42:43]
	s_mov_b32 m0, s4
	ds_read_b128 v[164:167], v241 offset:49152
	ds_read_b128 v[168:171], v241 offset:50176
	ds_read_b128 v[172:175], v241 offset:51200
	ds_read_b128 v[176:179], v241 offset:52224
	ds_read_b128 v[180:183], v241 offset:53248
	ds_read_b128 v[184:187], v241 offset:54272
	ds_read_b128 v[188:191], v241 offset:55296
	ds_read_b128 v[192:195], v241 offset:56320
	global_load_lds_dwordx4 v[200:201], off
	s_add_i32 m0, s4, 0x2000
	s_add_u32 s4, s70, 0x40080
	v_lshl_add_u64 v[200:201], v[202:203], 0, s[42:43]
	s_addc_u32 s5, s71, 0
	s_add_i32 s6, s7, s91
	global_load_lds_dwordx4 v[200:201], off
	v_lshl_add_u64 v[200:201], s[4:5], 0, v[204:205]
	s_mov_b32 m0, s6
	s_nop 0
	global_load_lds_dwordx4 v[200:201], off
	v_lshl_add_u64 v[200:201], s[4:5], 0, v[208:209]
	s_add_i32 m0, s6, 0x2000
	s_nop 0
	global_load_lds_dwordx4 v[200:201], off
	v_lshl_add_u64 v[200:201], v[210:211], 0, s[42:43]
	s_add_i32 m0, s44, 0x8000
	s_nop 0
	global_load_lds_dwordx4 v[200:201], off
	v_lshl_add_u64 v[200:201], v[212:213], 0, s[42:43]
	s_add_i32 m0, s44, 0xa000
	s_nop 0
	global_load_lds_dwordx4 v[200:201], off
	s_nop 0
	s_waitcnt vmcnt(8)
	s_waitcnt lgkmcnt(0)
	s_setprio 1
	s_barrier
	v_mfma_f32_16x16x32_bf16 v[62:65], v[90:93], v[164:167], v[62:65]
	v_mfma_f32_16x16x32_bf16 v[58:61], v[100:103], v[164:167], v[58:61]
	v_mfma_f32_16x16x32_bf16 v[46:49], v[90:93], v[172:175], v[46:49]
	v_mfma_f32_16x16x32_bf16 v[42:45], v[100:103], v[172:175], v[42:45]
	v_mfma_f32_16x16x32_bf16 v[30:33], v[90:93], v[180:183], v[30:33]
	v_mfma_f32_16x16x32_bf16 v[26:29], v[100:103], v[180:183], v[26:29]
	v_mfma_f32_16x16x32_bf16 v[14:17], v[90:93], v[188:191], v[14:17]
	v_mfma_f32_16x16x32_bf16 v[10:13], v[100:103], v[188:191], v[10:13]
	v_mfma_f32_16x16x32_bf16 v[62:65], v[94:97], v[168:171], v[62:65]
	v_mfma_f32_16x16x32_bf16 v[58:61], v[104:107], v[168:171], v[58:61]
	v_mfma_f32_16x16x32_bf16 v[46:49], v[94:97], v[176:179], v[46:49]
	v_mfma_f32_16x16x32_bf16 v[42:45], v[104:107], v[176:179], v[42:45]
	v_mfma_f32_16x16x32_bf16 v[30:33], v[94:97], v[184:187], v[30:33]
	v_mfma_f32_16x16x32_bf16 v[26:29], v[104:107], v[184:187], v[26:29]
	v_mfma_f32_16x16x32_bf16 v[14:17], v[94:97], v[192:195], v[14:17]
	v_mfma_f32_16x16x32_bf16 v[10:13], v[104:107], v[192:195], v[10:13]
	s_setprio 0
	s_setprio 1
	v_mfma_f32_16x16x32_bf16 v[54:57], v[108:111], v[164:167], v[54:57]
	v_mfma_f32_16x16x32_bf16 v[50:53], v[120:123], v[164:167], v[50:53]
	v_mfma_f32_16x16x32_bf16 v[38:41], v[108:111], v[172:175], v[38:41]
	v_mfma_f32_16x16x32_bf16 v[34:37], v[120:123], v[172:175], v[34:37]
	v_mfma_f32_16x16x32_bf16 v[22:25], v[108:111], v[180:183], v[22:25]
	v_mfma_f32_16x16x32_bf16 v[18:21], v[120:123], v[180:183], v[18:21]
	v_mfma_f32_16x16x32_bf16 v[6:9], v[108:111], v[188:191], v[6:9]
	v_mfma_f32_16x16x32_bf16 v[2:5], v[120:123], v[188:191], v[2:5]
	v_mfma_f32_16x16x32_bf16 v[54:57], v[112:115], v[168:171], v[54:57]
	v_mfma_f32_16x16x32_bf16 v[50:53], v[128:131], v[168:171], v[50:53]
	v_mfma_f32_16x16x32_bf16 v[38:41], v[112:115], v[176:179], v[38:41]
	v_mfma_f32_16x16x32_bf16 v[34:37], v[128:131], v[176:179], v[34:37]
	v_mfma_f32_16x16x32_bf16 v[22:25], v[112:115], v[184:187], v[22:25]
	v_mfma_f32_16x16x32_bf16 v[18:21], v[128:131], v[184:187], v[18:21]
	v_mfma_f32_16x16x32_bf16 v[6:9], v[112:115], v[192:195], v[6:9]
	v_mfma_f32_16x16x32_bf16 v[2:5], v[128:131], v[192:195], v[2:5]
	s_setprio 0
	s_barrier
	s_mov_b32 s100, 0
	s_add_i32 s97, s97, 2
	s_add_u32 s68, s68, 0x100
	s_addc_u32 s69, s69, 0
	s_add_u32 vcc_hi, vcc_hi, 0x100
	s_addc_u32 s96, s96, 0
	s_cmp_gt_u32 s97, 13
.LBB0_864:
	s_add_u32 s4, s68, 0xfffc0080
	s_addc_u32 s5, s69, -1
	s_add_i32 s45, 0, 0x10000
	s_cmp_eq_u32 s97, 12
	s_cselect_b32 s75, s57, s5
	s_cselect_b32 s74, s95, s4
	s_cselect_b32 s71, s31, s96
	s_cselect_b32 s70, vcc_lo, vcc_hi
	s_add_i32 s6, 0, 0x14000
	v_add_u32_e32 v104, s45, v239
	v_add_u32_e32 v128, s6, v239
	ds_read_b128 v[90:93], v104
	ds_read_b128 v[94:97], v104 offset:1024
	ds_read_b128 v[100:103], v104 offset:2048
	ds_read_b128 v[104:107], v104 offset:3072
	ds_read_b128 v[108:111], v128
	ds_read_b128 v[112:115], v128 offset:1024
	ds_read_b128 v[120:123], v128 offset:2048
	ds_read_b128 v[128:131], v128 offset:3072
	s_add_i32 s44, s91, 0
	v_lshl_add_u64 v[200:201], s[68:69], 0, v[98:99]
	s_add_i32 m0, s44, 0xc000
	ds_read_b128 v[164:167], v241
	ds_read_b128 v[168:171], v241 offset:1024
	ds_read_b128 v[172:175], v241 offset:2048
	ds_read_b128 v[176:179], v241 offset:3072
	ds_read_b128 v[180:183], v241 offset:4096
	ds_read_b128 v[184:187], v241 offset:5120
	ds_read_b128 v[188:191], v241 offset:6144
	ds_read_b128 v[192:195], v241 offset:7168
	global_load_lds_dwordx4 v[200:201], off
	v_lshl_add_u64 v[200:201], s[68:69], 0, v[206:207]
	s_add_i32 m0, s44, 0xe000
	s_nop 0
	global_load_lds_dwordx4 v[200:201], off
	s_nop 0
	s_waitcnt vmcnt(8)
	s_waitcnt lgkmcnt(0)
	s_setprio 1
	s_barrier
	v_mfma_f32_16x16x32_bf16 v[160:163], v[90:93], v[164:167], v[160:163]
	v_mfma_f32_16x16x32_bf16 v[156:159], v[100:103], v[164:167], v[156:159]
	v_mfma_f32_16x16x32_bf16 v[144:147], v[90:93], v[172:175], v[144:147]
	v_mfma_f32_16x16x32_bf16 v[140:143], v[100:103], v[172:175], v[140:143]
	v_mfma_f32_16x16x32_bf16 v[124:127], v[90:93], v[180:183], v[124:127]
	v_mfma_f32_16x16x32_bf16 v[116:119], v[100:103], v[180:183], v[116:119]
	v_mfma_f32_16x16x32_bf16 v[78:81], v[90:93], v[188:191], v[78:81]
	v_mfma_f32_16x16x32_bf16 v[74:77], v[100:103], v[188:191], v[74:77]
	v_mfma_f32_16x16x32_bf16 v[160:163], v[94:97], v[168:171], v[160:163]
	v_mfma_f32_16x16x32_bf16 v[156:159], v[104:107], v[168:171], v[156:159]
	v_mfma_f32_16x16x32_bf16 v[144:147], v[94:97], v[176:179], v[144:147]
	v_mfma_f32_16x16x32_bf16 v[140:143], v[104:107], v[176:179], v[140:143]
	v_mfma_f32_16x16x32_bf16 v[124:127], v[94:97], v[184:187], v[124:127]
	v_mfma_f32_16x16x32_bf16 v[116:119], v[104:107], v[184:187], v[116:119]
	v_mfma_f32_16x16x32_bf16 v[78:81], v[94:97], v[192:195], v[78:81]
	v_mfma_f32_16x16x32_bf16 v[74:77], v[104:107], v[192:195], v[74:77]
	s_setprio 0
	s_setprio 1
	v_mfma_f32_16x16x32_bf16 v[152:155], v[108:111], v[164:167], v[152:155]
	v_mfma_f32_16x16x32_bf16 v[148:151], v[120:123], v[164:167], v[148:151]
	v_mfma_f32_16x16x32_bf16 v[136:139], v[108:111], v[172:175], v[136:139]
	v_mfma_f32_16x16x32_bf16 v[132:135], v[120:123], v[172:175], v[132:135]
	v_mfma_f32_16x16x32_bf16 v[86:89], v[108:111], v[180:183], v[86:89]
	v_mfma_f32_16x16x32_bf16 v[82:85], v[120:123], v[180:183], v[82:85]
	v_mfma_f32_16x16x32_bf16 v[70:73], v[108:111], v[188:191], v[70:73]
	v_mfma_f32_16x16x32_bf16 v[66:69], v[120:123], v[188:191], v[66:69]
	v_mfma_f32_16x16x32_bf16 v[152:155], v[112:115], v[168:171], v[152:155]
	v_mfma_f32_16x16x32_bf16 v[148:151], v[128:131], v[168:171], v[148:151]
	v_mfma_f32_16x16x32_bf16 v[136:139], v[112:115], v[176:179], v[136:139]
	v_mfma_f32_16x16x32_bf16 v[132:135], v[128:131], v[176:179], v[132:135]
	v_mfma_f32_16x16x32_bf16 v[86:89], v[112:115], v[184:187], v[86:89]
	v_mfma_f32_16x16x32_bf16 v[82:85], v[128:131], v[184:187], v[82:85]
	v_mfma_f32_16x16x32_bf16 v[70:73], v[112:115], v[192:195], v[70:73]
	v_mfma_f32_16x16x32_bf16 v[66:69], v[128:131], v[192:195], v[66:69]
	s_setprio 0
	s_barrier
	s_add_i32 s4, s45, s91
	v_lshl_add_u64 v[200:201], s[70:71], 0, v[204:205]
	s_mov_b32 m0, s4
	ds_read_b128 v[164:167], v241 offset:16384
	ds_read_b128 v[168:171], v241 offset:17408
	ds_read_b128 v[172:175], v241 offset:18432
	ds_read_b128 v[176:179], v241 offset:19456
	ds_read_b128 v[180:183], v241 offset:20480
	ds_read_b128 v[184:187], v241 offset:21504
	ds_read_b128 v[188:191], v241 offset:22528
	ds_read_b128 v[192:195], v241 offset:23552
	global_load_lds_dwordx4 v[200:201], off
	s_add_i32 m0, s4, 0x2000
	s_add_u32 s4, s70, 0x40000
	v_lshl_add_u64 v[202:203], s[70:71], 0, v[208:209]
	s_addc_u32 s5, s71, 0
	s_add_i32 s6, s6, s91
	global_load_lds_dwordx4 v[202:203], off
	v_lshl_add_u64 v[210:211], s[4:5], 0, v[204:205]
	s_mov_b32 m0, s6
	v_lshl_add_u64 v[212:213], s[74:75], 0, v[206:207]
	global_load_lds_dwordx4 v[210:211], off
	v_lshl_add_u64 v[210:211], s[4:5], 0, v[208:209]
	s_add_i32 m0, s6, 0x2000
	s_nop 0
	global_load_lds_dwordx4 v[210:211], off
	v_lshl_add_u64 v[210:211], s[74:75], 0, v[98:99]
	s_mov_b32 m0, s44
	s_nop 0
	global_load_lds_dwordx4 v[210:211], off
	s_add_i32 m0, s44, 0x2000
	s_nop 0
	global_load_lds_dwordx4 v[212:213], off
	s_nop 0
	s_waitcnt vmcnt(8)
	s_waitcnt lgkmcnt(0)
	s_setprio 1
	s_barrier
	v_mfma_f32_16x16x32_bf16 v[62:65], v[90:93], v[164:167], v[62:65]
	v_mfma_f32_16x16x32_bf16 v[58:61], v[100:103], v[164:167], v[58:61]
	v_mfma_f32_16x16x32_bf16 v[46:49], v[90:93], v[172:175], v[46:49]
	v_mfma_f32_16x16x32_bf16 v[42:45], v[100:103], v[172:175], v[42:45]
	v_mfma_f32_16x16x32_bf16 v[30:33], v[90:93], v[180:183], v[30:33]
	v_mfma_f32_16x16x32_bf16 v[26:29], v[100:103], v[180:183], v[26:29]
	v_mfma_f32_16x16x32_bf16 v[14:17], v[90:93], v[188:191], v[14:17]
	v_mfma_f32_16x16x32_bf16 v[10:13], v[100:103], v[188:191], v[10:13]
	v_mfma_f32_16x16x32_bf16 v[62:65], v[94:97], v[168:171], v[62:65]
	v_mfma_f32_16x16x32_bf16 v[58:61], v[104:107], v[168:171], v[58:61]
	v_mfma_f32_16x16x32_bf16 v[46:49], v[94:97], v[176:179], v[46:49]
	v_mfma_f32_16x16x32_bf16 v[42:45], v[104:107], v[176:179], v[42:45]
	v_mfma_f32_16x16x32_bf16 v[30:33], v[94:97], v[184:187], v[30:33]
	v_mfma_f32_16x16x32_bf16 v[26:29], v[104:107], v[184:187], v[26:29]
	v_mfma_f32_16x16x32_bf16 v[14:17], v[94:97], v[192:195], v[14:17]
	v_mfma_f32_16x16x32_bf16 v[10:13], v[104:107], v[192:195], v[10:13]
	s_setprio 0
	s_setprio 1
	v_mfma_f32_16x16x32_bf16 v[54:57], v[108:111], v[164:167], v[54:57]
	v_mfma_f32_16x16x32_bf16 v[50:53], v[120:123], v[164:167], v[50:53]
	v_mfma_f32_16x16x32_bf16 v[38:41], v[108:111], v[172:175], v[38:41]
	v_mfma_f32_16x16x32_bf16 v[34:37], v[120:123], v[172:175], v[34:37]
	v_mfma_f32_16x16x32_bf16 v[22:25], v[108:111], v[180:183], v[22:25]
	v_mfma_f32_16x16x32_bf16 v[18:21], v[120:123], v[180:183], v[18:21]
	v_mfma_f32_16x16x32_bf16 v[6:9], v[108:111], v[188:191], v[6:9]
	v_mfma_f32_16x16x32_bf16 v[2:5], v[120:123], v[188:191], v[2:5]
	v_mfma_f32_16x16x32_bf16 v[54:57], v[112:115], v[168:171], v[54:57]
	v_mfma_f32_16x16x32_bf16 v[50:53], v[128:131], v[168:171], v[50:53]
	v_mfma_f32_16x16x32_bf16 v[38:41], v[112:115], v[176:179], v[38:41]
	v_mfma_f32_16x16x32_bf16 v[34:37], v[128:131], v[176:179], v[34:37]
	v_mfma_f32_16x16x32_bf16 v[22:25], v[112:115], v[184:187], v[22:25]
	v_mfma_f32_16x16x32_bf16 v[18:21], v[128:131], v[184:187], v[18:21]
	v_mfma_f32_16x16x32_bf16 v[6:9], v[112:115], v[192:195], v[6:9]
	v_mfma_f32_16x16x32_bf16 v[2:5], v[128:131], v[192:195], v[2:5]
	s_setprio 0
	s_barrier
	s_add_i32 s6, 0, 0x18000
	s_add_i32 s7, 0, 0x1c000
	v_add_u32_e32 v104, s6, v239
	v_add_u32_e32 v128, s7, v239
	ds_read_b128 v[90:93], v104
	ds_read_b128 v[94:97], v104 offset:1024
	ds_read_b128 v[100:103], v104 offset:2048
	ds_read_b128 v[104:107], v104 offset:3072
	ds_read_b128 v[108:111], v128
	ds_read_b128 v[112:115], v128 offset:1024
	ds_read_b128 v[120:123], v128 offset:2048
	ds_read_b128 v[128:131], v128 offset:3072
	s_add_u32 s4, s74, 0x40000
	s_addc_u32 s5, s75, 0
	v_lshl_add_u64 v[214:215], s[4:5], 0, v[98:99]
	s_add_i32 m0, s44, 0x4000
	ds_read_b128 v[164:167], v241 offset:32768
	ds_read_b128 v[168:171], v241 offset:33792
	ds_read_b128 v[172:175], v241 offset:34816
	ds_read_b128 v[176:179], v241 offset:35840
	ds_read_b128 v[180:183], v241 offset:36864
	ds_read_b128 v[184:187], v241 offset:37888
	ds_read_b128 v[188:191], v241 offset:38912
	ds_read_b128 v[192:195], v241 offset:39936
	global_load_lds_dwordx4 v[214:215], off
	v_lshl_add_u64 v[214:215], s[4:5], 0, v[206:207]
	s_add_i32 m0, s44, 0x6000
	s_nop 0
	global_load_lds_dwordx4 v[214:215], off
	s_waitcnt vmcnt(8)
	s_waitcnt lgkmcnt(0)
	s_setprio 1
	s_barrier
	v_mfma_f32_16x16x32_bf16 v[160:163], v[90:93], v[164:167], v[160:163]
	v_mfma_f32_16x16x32_bf16 v[156:159], v[100:103], v[164:167], v[156:159]
	v_mfma_f32_16x16x32_bf16 v[144:147], v[90:93], v[172:175], v[144:147]
	v_mfma_f32_16x16x32_bf16 v[140:143], v[100:103], v[172:175], v[140:143]
	v_mfma_f32_16x16x32_bf16 v[124:127], v[90:93], v[180:183], v[124:127]
	v_mfma_f32_16x16x32_bf16 v[116:119], v[100:103], v[180:183], v[116:119]
	v_mfma_f32_16x16x32_bf16 v[78:81], v[90:93], v[188:191], v[78:81]
	v_mfma_f32_16x16x32_bf16 v[74:77], v[100:103], v[188:191], v[74:77]
	v_mfma_f32_16x16x32_bf16 v[160:163], v[94:97], v[168:171], v[160:163]
	v_mfma_f32_16x16x32_bf16 v[156:159], v[104:107], v[168:171], v[156:159]
	v_mfma_f32_16x16x32_bf16 v[144:147], v[94:97], v[176:179], v[144:147]
	v_mfma_f32_16x16x32_bf16 v[140:143], v[104:107], v[176:179], v[140:143]
	v_mfma_f32_16x16x32_bf16 v[124:127], v[94:97], v[184:187], v[124:127]
	v_mfma_f32_16x16x32_bf16 v[116:119], v[104:107], v[184:187], v[116:119]
	v_mfma_f32_16x16x32_bf16 v[78:81], v[94:97], v[192:195], v[78:81]
	v_mfma_f32_16x16x32_bf16 v[74:77], v[104:107], v[192:195], v[74:77]
	s_setprio 0
	s_setprio 1
	v_mfma_f32_16x16x32_bf16 v[152:155], v[108:111], v[164:167], v[152:155]
	v_mfma_f32_16x16x32_bf16 v[148:151], v[120:123], v[164:167], v[148:151]
	v_mfma_f32_16x16x32_bf16 v[136:139], v[108:111], v[172:175], v[136:139]
	v_mfma_f32_16x16x32_bf16 v[132:135], v[120:123], v[172:175], v[132:135]
	v_mfma_f32_16x16x32_bf16 v[86:89], v[108:111], v[180:183], v[86:89]
	v_mfma_f32_16x16x32_bf16 v[82:85], v[120:123], v[180:183], v[82:85]
	v_mfma_f32_16x16x32_bf16 v[70:73], v[108:111], v[188:191], v[70:73]
	v_mfma_f32_16x16x32_bf16 v[66:69], v[120:123], v[188:191], v[66:69]
	v_mfma_f32_16x16x32_bf16 v[152:155], v[112:115], v[168:171], v[152:155]
	v_mfma_f32_16x16x32_bf16 v[148:151], v[128:131], v[168:171], v[148:151]
	v_mfma_f32_16x16x32_bf16 v[136:139], v[112:115], v[176:179], v[136:139]
	v_mfma_f32_16x16x32_bf16 v[132:135], v[128:131], v[176:179], v[132:135]
	v_mfma_f32_16x16x32_bf16 v[86:89], v[112:115], v[184:187], v[86:89]
	v_mfma_f32_16x16x32_bf16 v[82:85], v[128:131], v[184:187], v[82:85]
	v_mfma_f32_16x16x32_bf16 v[70:73], v[112:115], v[192:195], v[70:73]
	v_mfma_f32_16x16x32_bf16 v[66:69], v[128:131], v[192:195], v[66:69]
	s_setprio 0
	s_barrier
	s_add_i32 s4, s6, s91
	v_lshl_add_u64 v[200:201], v[200:201], 0, s[42:43]
	s_mov_b32 m0, s4
	ds_read_b128 v[164:167], v241 offset:49152
	ds_read_b128 v[168:171], v241 offset:50176
	ds_read_b128 v[172:175], v241 offset:51200
	ds_read_b128 v[176:179], v241 offset:52224
	ds_read_b128 v[180:183], v241 offset:53248
	ds_read_b128 v[184:187], v241 offset:54272
	ds_read_b128 v[188:191], v241 offset:55296
	ds_read_b128 v[192:195], v241 offset:56320
	global_load_lds_dwordx4 v[200:201], off
	s_add_i32 m0, s4, 0x2000
	s_add_u32 s4, s70, 0x40080
	v_lshl_add_u64 v[200:201], v[202:203], 0, s[42:43]
	s_addc_u32 s5, s71, 0
	s_add_i32 s6, s7, s91
	global_load_lds_dwordx4 v[200:201], off
	v_lshl_add_u64 v[200:201], s[4:5], 0, v[204:205]
	s_mov_b32 m0, s6
	s_nop 0
	global_load_lds_dwordx4 v[200:201], off
	v_lshl_add_u64 v[200:201], s[4:5], 0, v[208:209]
	s_add_i32 m0, s6, 0x2000
	s_nop 0
	global_load_lds_dwordx4 v[200:201], off
	v_lshl_add_u64 v[200:201], v[210:211], 0, s[42:43]
	s_add_i32 m0, s44, 0x8000
	s_nop 0
	global_load_lds_dwordx4 v[200:201], off
	v_lshl_add_u64 v[200:201], v[212:213], 0, s[42:43]
	s_add_i32 m0, s44, 0xa000
	s_nop 0
	global_load_lds_dwordx4 v[200:201], off
	s_nop 0
	s_waitcnt vmcnt(8)
	s_waitcnt lgkmcnt(0)
	s_setprio 1
	s_barrier
	v_mfma_f32_16x16x32_bf16 v[62:65], v[90:93], v[164:167], v[62:65]
	v_mfma_f32_16x16x32_bf16 v[58:61], v[100:103], v[164:167], v[58:61]
	v_mfma_f32_16x16x32_bf16 v[46:49], v[90:93], v[172:175], v[46:49]
	v_mfma_f32_16x16x32_bf16 v[42:45], v[100:103], v[172:175], v[42:45]
	v_mfma_f32_16x16x32_bf16 v[30:33], v[90:93], v[180:183], v[30:33]
	v_mfma_f32_16x16x32_bf16 v[26:29], v[100:103], v[180:183], v[26:29]
	v_mfma_f32_16x16x32_bf16 v[14:17], v[90:93], v[188:191], v[14:17]
	v_mfma_f32_16x16x32_bf16 v[10:13], v[100:103], v[188:191], v[10:13]
	v_mfma_f32_16x16x32_bf16 v[62:65], v[94:97], v[168:171], v[62:65]
	v_mfma_f32_16x16x32_bf16 v[58:61], v[104:107], v[168:171], v[58:61]
	v_mfma_f32_16x16x32_bf16 v[46:49], v[94:97], v[176:179], v[46:49]
	v_mfma_f32_16x16x32_bf16 v[42:45], v[104:107], v[176:179], v[42:45]
	v_mfma_f32_16x16x32_bf16 v[30:33], v[94:97], v[184:187], v[30:33]
	v_mfma_f32_16x16x32_bf16 v[26:29], v[104:107], v[184:187], v[26:29]
	v_mfma_f32_16x16x32_bf16 v[14:17], v[94:97], v[192:195], v[14:17]
	v_mfma_f32_16x16x32_bf16 v[10:13], v[104:107], v[192:195], v[10:13]
	s_setprio 0
	s_setprio 1
	v_mfma_f32_16x16x32_bf16 v[54:57], v[108:111], v[164:167], v[54:57]
	v_mfma_f32_16x16x32_bf16 v[50:53], v[120:123], v[164:167], v[50:53]
	v_mfma_f32_16x16x32_bf16 v[38:41], v[108:111], v[172:175], v[38:41]
	v_mfma_f32_16x16x32_bf16 v[34:37], v[120:123], v[172:175], v[34:37]
	v_mfma_f32_16x16x32_bf16 v[22:25], v[108:111], v[180:183], v[22:25]
	v_mfma_f32_16x16x32_bf16 v[18:21], v[120:123], v[180:183], v[18:21]
	v_mfma_f32_16x16x32_bf16 v[6:9], v[108:111], v[188:191], v[6:9]
	v_mfma_f32_16x16x32_bf16 v[2:5], v[120:123], v[188:191], v[2:5]
	v_mfma_f32_16x16x32_bf16 v[54:57], v[112:115], v[168:171], v[54:57]
	v_mfma_f32_16x16x32_bf16 v[50:53], v[128:131], v[168:171], v[50:53]
	v_mfma_f32_16x16x32_bf16 v[38:41], v[112:115], v[176:179], v[38:41]
	v_mfma_f32_16x16x32_bf16 v[34:37], v[128:131], v[176:179], v[34:37]
	v_mfma_f32_16x16x32_bf16 v[22:25], v[112:115], v[184:187], v[22:25]
	v_mfma_f32_16x16x32_bf16 v[18:21], v[128:131], v[184:187], v[18:21]
	v_mfma_f32_16x16x32_bf16 v[6:9], v[112:115], v[192:195], v[6:9]
	v_mfma_f32_16x16x32_bf16 v[2:5], v[128:131], v[192:195], v[2:5]
	s_setprio 0
	s_barrier
	s_add_i32 s97, s97, 2
	s_add_u32 s68, s68, 0x100
	s_addc_u32 s69, s69, 0
	s_add_u32 vcc_hi, vcc_hi, 0x100
	s_addc_u32 s96, s96, 0
	s_cmp_gt_u32 s97, 13
	s_cbranch_scc0 .LBB0_864
	s_mov_b32 s100, 1
	s_and_b64 vcc, exec, s[12:13]
	s_cbranch_vccz .LBB0_867
	s_lshl_b32 s6, s94, 8
	s_add_i32 s5, s6, 0xffffc000
	s_lshr_b32 s5, s5, 12
	s_ashr_i32 s4, s94, 5
	s_add_i32 s5, s5, 2
	s_cmp_lt_i32 s94, 64
	s_cselect_b32 s4, s4, s5
	s_ashr_i32 s5, s4, 31
	s_lshl_b64 s[4:5], s[4:5], 14
	v_lshl_or_b32 v164, s18, 8, v240
	s_add_u32 s44, s79, s4
	s_addc_u32 s45, s88, s5
	v_ashrrev_i32_e32 v165, 31, v164
	v_add_u32_e32 v222, s6, v238
	s_add_u32 s4, s89, s4
	v_lshlrev_b64 v[210:211], 1, v[164:165]
	v_ashrrev_i32_e32 v223, 31, v222
	v_lshlrev_b64 v[90:91], 2, v[164:165]
	s_addc_u32 s5, s90, s5
	v_lshl_add_u64 v[164:165], s[82:83], 0, v[210:211]
	v_lshlrev_b64 v[226:227], 11, v[222:223]
	v_lshl_add_u64 v[92:93], s[44:45], 0, v[90:91]
	v_lshl_add_u64 v[94:95], s[4:5], 0, v[90:91]
	v_lshl_add_u64 v[166:167], v[164:165], 0, v[226:227]
	global_load_dwordx4 v[120:123], v[92:93], off offset:16
	global_load_dwordx4 v[128:131], v[92:93], off
	global_load_dwordx4 v[108:111], v[94:95], off offset:16
	global_load_dwordx4 v[112:115], v[94:95], off
	global_load_dwordx4 v[100:103], v[92:93], off offset:528
	global_load_dwordx4 v[104:107], v[92:93], off offset:512
	s_nop 0
	global_load_dwordx4 v[90:93], v[94:95], off offset:528
	s_nop 0
	global_load_dwordx4 v[94:97], v[94:95], off offset:512
	s_nop 0
	global_load_dwordx4 v[192:195], v[166:167], off
	global_load_dwordx4 v[188:191], v[166:167], off offset:256
	v_or_b32_e32 v220, 16, v222
	v_ashrrev_i32_e32 v221, 31, v220
	v_or_b32_e32 v216, 32, v222
	v_or_b32_e32 v212, 48, v222
	v_lshlrev_b64 v[224:225], 11, v[220:221]
	v_ashrrev_i32_e32 v217, 31, v216
	v_ashrrev_i32_e32 v213, 31, v212
	v_lshl_add_u64 v[166:167], v[164:165], 0, v[224:225]
	v_lshlrev_b64 v[218:219], 11, v[216:217]
	v_lshlrev_b64 v[214:215], 11, v[212:213]
	global_load_dwordx4 v[184:187], v[166:167], off
	global_load_dwordx4 v[180:183], v[166:167], off offset:256
	v_lshl_add_u64 v[166:167], v[164:165], 0, v[218:219]
	v_lshl_add_u64 v[164:165], v[164:165], 0, v[214:215]
	global_load_dwordx4 v[176:179], v[166:167], off
	global_load_dwordx4 v[172:175], v[166:167], off offset:256
	global_load_dwordx4 v[168:171], v[164:165], off
	s_nop 0
	global_load_dwordx4 v[164:167], v[164:165], off offset:256
	s_barrier
	s_branch .Lmy_g2a_afterload

.LBB0_907:
	s_ashr_i32 s21, s20, 31
	s_lshl_b64 s[30:31], s[20:21], 19
	v_readlane_b32 s2, v254, 23
	s_add_u32 s30, s2, s30
	v_readlane_b32 s2, v254, 24
	s_addc_u32 s31, s2, s31
	s_and_b64 s[40:41], s[38:39], exec
	s_cselect_b32 s21, s31, s57
	s_cselect_b32 s93, s30, s56
	s_ashr_i32 s53, s52, 31
	s_lshl_b64 s[40:41], s[52:53], 19
	s_add_u32 s40, s27, s40
	s_addc_u32 s41, s77, s41
	s_and_b64 s[44:45], s[38:39], exec
	s_cselect_b32 s15, s41, s69
	s_cselect_b32 s94, s40, s68
	s_add_u32 s56, s56, 0x40080
	s_addc_u32 s57, s57, 0
	s_add_u32 s95, s68, 0x100
	s_addc_u32 vcc_lo, s69, 0
	s_mov_b32 s96, -2
	s_add_u32 s4, s56, 0xfffc0080
	s_addc_u32 s5, s57, -1
	s_add_i32 s45, 0, 0x10000
	s_cmp_eq_u32 s96, 12
	s_cselect_b32 s71, s21, s5
	s_cselect_b32 s70, s93, s4
	s_cselect_b32 s69, s15, vcc_lo
	s_cselect_b32 s68, s94, s95
	s_add_i32 s97, 0, 0x14000
	v_add_u32_e32 v104, s45, v223
	v_add_u32_e32 v124, s97, v223
	ds_read_b128 v[86:89], v104
	ds_read_b128 v[90:93], v104 offset:1024
	ds_read_b128 v[100:103], v104 offset:2048
	ds_read_b128 v[104:107], v104 offset:3072
	ds_read_b128 v[108:111], v124
	ds_read_b128 v[112:115], v124 offset:1024
	ds_read_b128 v[116:119], v124 offset:2048
	ds_read_b128 v[124:127], v124 offset:3072
	s_add_i32 s44, s74, 0
	v_lshl_add_u64 v[200:201], s[56:57], 0, v[98:99]
	s_add_i32 m0, s44, 0xc000
	ds_read_b128 v[164:167], v225
	ds_read_b128 v[168:171], v225 offset:1024
	ds_read_b128 v[172:175], v225 offset:2048
	ds_read_b128 v[176:179], v225 offset:3072
	ds_read_b128 v[180:183], v225 offset:4096
	ds_read_b128 v[184:187], v225 offset:5120
	ds_read_b128 v[188:191], v225 offset:6144
	ds_read_b128 v[192:195], v225 offset:7168
	global_load_lds_dwordx4 v[200:201], off
	v_lshl_add_u64 v[200:201], s[56:57], 0, v[206:207]
	s_add_i32 m0, s44, 0xe000
	s_nop 0
	global_load_lds_dwordx4 v[200:201], off
	s_nop 0
	s_cmp_eq_u32 s100, 1
	s_cbranch_scc1 .Lmy_sk5_pk
	s_waitcnt vmcnt(8)
.Lmy_sk5_pk:
	s_waitcnt lgkmcnt(0)
	s_setprio 1
	s_barrier
	v_mfma_f32_16x16x32_bf16 v[160:163], v[86:89], v[164:167], 0
	v_mfma_f32_16x16x32_bf16 v[156:159], v[100:103], v[164:167], 0
	v_mfma_f32_16x16x32_bf16 v[144:147], v[86:89], v[172:175], 0
	v_mfma_f32_16x16x32_bf16 v[140:143], v[100:103], v[172:175], 0
	v_mfma_f32_16x16x32_bf16 v[128:131], v[86:89], v[180:183], 0
	v_mfma_f32_16x16x32_bf16 v[120:123], v[100:103], v[180:183], 0
	v_mfma_f32_16x16x32_bf16 v[78:81], v[86:89], v[188:191], 0
	v_mfma_f32_16x16x32_bf16 v[74:77], v[100:103], v[188:191], 0
	v_mfma_f32_16x16x32_bf16 v[160:163], v[90:93], v[168:171], v[160:163]
	v_mfma_f32_16x16x32_bf16 v[156:159], v[104:107], v[168:171], v[156:159]
	v_mfma_f32_16x16x32_bf16 v[144:147], v[90:93], v[176:179], v[144:147]
	v_mfma_f32_16x16x32_bf16 v[140:143], v[104:107], v[176:179], v[140:143]
	v_mfma_f32_16x16x32_bf16 v[128:131], v[90:93], v[184:187], v[128:131]
	v_mfma_f32_16x16x32_bf16 v[120:123], v[104:107], v[184:187], v[120:123]
	v_mfma_f32_16x16x32_bf16 v[78:81], v[90:93], v[192:195], v[78:81]
	v_mfma_f32_16x16x32_bf16 v[74:77], v[104:107], v[192:195], v[74:77]
	s_setprio 0
	s_setprio 1
	v_mfma_f32_16x16x32_bf16 v[152:155], v[108:111], v[164:167], 0
	v_mfma_f32_16x16x32_bf16 v[148:151], v[116:119], v[164:167], 0
	v_mfma_f32_16x16x32_bf16 v[136:139], v[108:111], v[172:175], 0
	v_mfma_f32_16x16x32_bf16 v[132:135], v[116:119], v[172:175], 0
	v_mfma_f32_16x16x32_bf16 v[94:97], v[108:111], v[180:183], 0
	v_mfma_f32_16x16x32_bf16 v[82:85], v[116:119], v[180:183], 0
	v_mfma_f32_16x16x32_bf16 v[70:73], v[108:111], v[188:191], 0
	v_mfma_f32_16x16x32_bf16 v[66:69], v[116:119], v[188:191], 0
	v_mfma_f32_16x16x32_bf16 v[152:155], v[112:115], v[168:171], v[152:155]
	v_mfma_f32_16x16x32_bf16 v[148:151], v[124:127], v[168:171], v[148:151]
	v_mfma_f32_16x16x32_bf16 v[136:139], v[112:115], v[176:179], v[136:139]
	v_mfma_f32_16x16x32_bf16 v[132:135], v[124:127], v[176:179], v[132:135]
	v_mfma_f32_16x16x32_bf16 v[94:97], v[112:115], v[184:187], v[94:97]
	v_mfma_f32_16x16x32_bf16 v[82:85], v[124:127], v[184:187], v[82:85]
	v_mfma_f32_16x16x32_bf16 v[70:73], v[112:115], v[192:195], v[70:73]
	v_mfma_f32_16x16x32_bf16 v[66:69], v[124:127], v[192:195], v[66:69]
	s_setprio 0
	s_barrier
	s_add_i32 s4, s45, s74
	v_lshl_add_u64 v[200:201], s[68:69], 0, v[204:205]
	s_mov_b32 m0, s4
	ds_read_b128 v[164:167], v225 offset:16384
	ds_read_b128 v[168:171], v225 offset:17408
	ds_read_b128 v[172:175], v225 offset:18432
	ds_read_b128 v[176:179], v225 offset:19456
	ds_read_b128 v[180:183], v225 offset:20480
	ds_read_b128 v[184:187], v225 offset:21504
	ds_read_b128 v[188:191], v225 offset:22528
	ds_read_b128 v[192:195], v225 offset:23552
	global_load_lds_dwordx4 v[200:201], off
	s_add_i32 m0, s4, 0x2000
	s_add_u32 s4, s68, 0x40000
	v_lshl_add_u64 v[202:203], s[68:69], 0, v[208:209]
	s_addc_u32 s5, s69, 0
	s_add_i32 s45, s97, s74
	global_load_lds_dwordx4 v[202:203], off
	v_lshl_add_u64 v[210:211], s[4:5], 0, v[204:205]
	s_mov_b32 m0, s45
	v_lshl_add_u64 v[212:213], s[70:71], 0, v[206:207]
	global_load_lds_dwordx4 v[210:211], off
	v_lshl_add_u64 v[210:211], s[4:5], 0, v[208:209]
	s_add_i32 m0, s45, 0x2000
	s_nop 0
	global_load_lds_dwordx4 v[210:211], off
	v_lshl_add_u64 v[210:211], s[70:71], 0, v[98:99]
	s_mov_b32 m0, s44
	s_nop 0
	global_load_lds_dwordx4 v[210:211], off
	s_add_i32 m0, s44, 0x2000
	s_nop 0
	global_load_lds_dwordx4 v[212:213], off
	s_nop 0
	s_cmp_eq_u32 s100, 1
	s_cbranch_scc1 .Lmy_sk6_pk
	s_waitcnt vmcnt(8)
.Lmy_sk6_pk:
	s_waitcnt lgkmcnt(0)
	s_setprio 1
	s_barrier
	v_mfma_f32_16x16x32_bf16 v[62:65], v[86:89], v[164:167], 0
	v_mfma_f32_16x16x32_bf16 v[58:61], v[100:103], v[164:167], 0
	v_mfma_f32_16x16x32_bf16 v[46:49], v[86:89], v[172:175], 0
	v_mfma_f32_16x16x32_bf16 v[42:45], v[100:103], v[172:175], 0
	v_mfma_f32_16x16x32_bf16 v[30:33], v[86:89], v[180:183], 0
	v_mfma_f32_16x16x32_bf16 v[26:29], v[100:103], v[180:183], 0
	v_mfma_f32_16x16x32_bf16 v[14:17], v[86:89], v[188:191], 0
	v_mfma_f32_16x16x32_bf16 v[10:13], v[100:103], v[188:191], 0
	v_mfma_f32_16x16x32_bf16 v[62:65], v[90:93], v[168:171], v[62:65]
	v_mfma_f32_16x16x32_bf16 v[58:61], v[104:107], v[168:171], v[58:61]
	v_mfma_f32_16x16x32_bf16 v[46:49], v[90:93], v[176:179], v[46:49]
	v_mfma_f32_16x16x32_bf16 v[42:45], v[104:107], v[176:179], v[42:45]
	v_mfma_f32_16x16x32_bf16 v[30:33], v[90:93], v[184:187], v[30:33]
	v_mfma_f32_16x16x32_bf16 v[26:29], v[104:107], v[184:187], v[26:29]
	v_mfma_f32_16x16x32_bf16 v[14:17], v[90:93], v[192:195], v[14:17]
	v_mfma_f32_16x16x32_bf16 v[10:13], v[104:107], v[192:195], v[10:13]
	s_setprio 0
	s_setprio 1
	v_mfma_f32_16x16x32_bf16 v[54:57], v[108:111], v[164:167], 0
	v_mfma_f32_16x16x32_bf16 v[50:53], v[116:119], v[164:167], 0
	v_mfma_f32_16x16x32_bf16 v[38:41], v[108:111], v[172:175], 0
	v_mfma_f32_16x16x32_bf16 v[34:37], v[116:119], v[172:175], 0
	v_mfma_f32_16x16x32_bf16 v[22:25], v[108:111], v[180:183], 0
	v_mfma_f32_16x16x32_bf16 v[18:21], v[116:119], v[180:183], 0
	v_mfma_f32_16x16x32_bf16 v[6:9], v[108:111], v[188:191], 0
	v_mfma_f32_16x16x32_bf16 v[2:5], v[116:119], v[188:191], 0
	v_mfma_f32_16x16x32_bf16 v[54:57], v[112:115], v[168:171], v[54:57]
	v_mfma_f32_16x16x32_bf16 v[50:53], v[124:127], v[168:171], v[50:53]
	v_mfma_f32_16x16x32_bf16 v[38:41], v[112:115], v[176:179], v[38:41]
	v_mfma_f32_16x16x32_bf16 v[34:37], v[124:127], v[176:179], v[34:37]
	v_mfma_f32_16x16x32_bf16 v[22:25], v[112:115], v[184:187], v[22:25]
	v_mfma_f32_16x16x32_bf16 v[18:21], v[124:127], v[184:187], v[18:21]
	v_mfma_f32_16x16x32_bf16 v[6:9], v[112:115], v[192:195], v[6:9]
	v_mfma_f32_16x16x32_bf16 v[2:5], v[124:127], v[192:195], v[2:5]
	s_setprio 0
	s_barrier
	s_add_i32 s45, 0, 0x18000
	s_add_i32 s97, 0, 0x1c000
	v_add_u32_e32 v104, s45, v223
	v_add_u32_e32 v124, s97, v223
	ds_read_b128 v[86:89], v104
	ds_read_b128 v[90:93], v104 offset:1024
	ds_read_b128 v[100:103], v104 offset:2048
	ds_read_b128 v[104:107], v104 offset:3072
	ds_read_b128 v[108:111], v124
	ds_read_b128 v[112:115], v124 offset:1024
	ds_read_b128 v[116:119], v124 offset:2048
	ds_read_b128 v[124:127], v124 offset:3072
	s_add_u32 s4, s70, 0x40000
	s_addc_u32 s5, s71, 0
	v_lshl_add_u64 v[214:215], s[4:5], 0, v[98:99]
	s_add_i32 m0, s44, 0x4000
	ds_read_b128 v[164:167], v225 offset:32768
	ds_read_b128 v[168:171], v225 offset:33792
	ds_read_b128 v[172:175], v225 offset:34816
	ds_read_b128 v[176:179], v225 offset:35840
	ds_read_b128 v[180:183], v225 offset:36864
	ds_read_b128 v[184:187], v225 offset:37888
	ds_read_b128 v[188:191], v225 offset:38912
	ds_read_b128 v[192:195], v225 offset:39936
	global_load_lds_dwordx4 v[214:215], off
	v_lshl_add_u64 v[214:215], s[4:5], 0, v[206:207]
	s_add_i32 m0, s44, 0x6000
	s_nop 0
	global_load_lds_dwordx4 v[214:215], off
	s_waitcnt vmcnt(8)
	s_waitcnt lgkmcnt(0)
	s_setprio 1
	s_barrier
	v_mfma_f32_16x16x32_bf16 v[160:163], v[86:89], v[164:167], v[160:163]
	v_mfma_f32_16x16x32_bf16 v[156:159], v[100:103], v[164:167], v[156:159]
	v_mfma_f32_16x16x32_bf16 v[144:147], v[86:89], v[172:175], v[144:147]
	v_mfma_f32_16x16x32_bf16 v[140:143], v[100:103], v[172:175], v[140:143]
	v_mfma_f32_16x16x32_bf16 v[128:131], v[86:89], v[180:183], v[128:131]
	v_mfma_f32_16x16x32_bf16 v[120:123], v[100:103], v[180:183], v[120:123]
	v_mfma_f32_16x16x32_bf16 v[78:81], v[86:89], v[188:191], v[78:81]
	v_mfma_f32_16x16x32_bf16 v[74:77], v[100:103], v[188:191], v[74:77]
	v_mfma_f32_16x16x32_bf16 v[160:163], v[90:93], v[168:171], v[160:163]
	v_mfma_f32_16x16x32_bf16 v[156:159], v[104:107], v[168:171], v[156:159]
	v_mfma_f32_16x16x32_bf16 v[144:147], v[90:93], v[176:179], v[144:147]
	v_mfma_f32_16x16x32_bf16 v[140:143], v[104:107], v[176:179], v[140:143]
	v_mfma_f32_16x16x32_bf16 v[128:131], v[90:93], v[184:187], v[128:131]
	v_mfma_f32_16x16x32_bf16 v[120:123], v[104:107], v[184:187], v[120:123]
	v_mfma_f32_16x16x32_bf16 v[78:81], v[90:93], v[192:195], v[78:81]
	v_mfma_f32_16x16x32_bf16 v[74:77], v[104:107], v[192:195], v[74:77]
	s_setprio 0
	s_setprio 1
	v_mfma_f32_16x16x32_bf16 v[152:155], v[108:111], v[164:167], v[152:155]
	v_mfma_f32_16x16x32_bf16 v[148:151], v[116:119], v[164:167], v[148:151]
	v_mfma_f32_16x16x32_bf16 v[136:139], v[108:111], v[172:175], v[136:139]
	v_mfma_f32_16x16x32_bf16 v[132:135], v[116:119], v[172:175], v[132:135]
	v_mfma_f32_16x16x32_bf16 v[94:97], v[108:111], v[180:183], v[94:97]
	v_mfma_f32_16x16x32_bf16 v[82:85], v[116:119], v[180:183], v[82:85]
	v_mfma_f32_16x16x32_bf16 v[70:73], v[108:111], v[188:191], v[70:73]
	v_mfma_f32_16x16x32_bf16 v[66:69], v[116:119], v[188:191], v[66:69]
	v_mfma_f32_16x16x32_bf16 v[152:155], v[112:115], v[168:171], v[152:155]
	v_mfma_f32_16x16x32_bf16 v[148:151], v[124:127], v[168:171], v[148:151]
	v_mfma_f32_16x16x32_bf16 v[136:139], v[112:115], v[176:179], v[136:139]
	v_mfma_f32_16x16x32_bf16 v[132:135], v[124:127], v[176:179], v[132:135]
	v_mfma_f32_16x16x32_bf16 v[94:97], v[112:115], v[184:187], v[94:97]
	v_mfma_f32_16x16x32_bf16 v[82:85], v[124:127], v[184:187], v[82:85]
	v_mfma_f32_16x16x32_bf16 v[70:73], v[112:115], v[192:195], v[70:73]
	v_mfma_f32_16x16x32_bf16 v[66:69], v[124:127], v[192:195], v[66:69]
	s_setprio 0
	s_barrier
	s_add_i32 s4, s45, s74
	v_lshl_add_u64 v[200:201], v[200:201], 0, s[42:43]
	s_mov_b32 m0, s4
	ds_read_b128 v[164:167], v225 offset:49152
	ds_read_b128 v[168:171], v225 offset:50176
	ds_read_b128 v[172:175], v225 offset:51200
	ds_read_b128 v[176:179], v225 offset:52224
	ds_read_b128 v[180:183], v225 offset:53248
	ds_read_b128 v[184:187], v225 offset:54272
	ds_read_b128 v[188:191], v225 offset:55296
	ds_read_b128 v[192:195], v225 offset:56320
	global_load_lds_dwordx4 v[200:201], off
	s_add_i32 m0, s4, 0x2000
	s_add_u32 s4, s68, 0x40080
	v_lshl_add_u64 v[200:201], v[202:203], 0, s[42:43]
	s_addc_u32 s5, s69, 0
	s_add_i32 s45, s97, s74
	global_load_lds_dwordx4 v[200:201], off
	v_lshl_add_u64 v[200:201], s[4:5], 0, v[204:205]
	s_mov_b32 m0, s45
	s_nop 0
	global_load_lds_dwordx4 v[200:201], off
	v_lshl_add_u64 v[200:201], s[4:5], 0, v[208:209]
	s_add_i32 m0, s45, 0x2000
	s_nop 0
	global_load_lds_dwordx4 v[200:201], off
	v_lshl_add_u64 v[200:201], v[210:211], 0, s[42:43]
	s_add_i32 m0, s44, 0x8000
	s_nop 0
	global_load_lds_dwordx4 v[200:201], off
	v_lshl_add_u64 v[200:201], v[212:213], 0, s[42:43]
	s_add_i32 m0, s44, 0xa000
	s_nop 0
	global_load_lds_dwordx4 v[200:201], off
	s_nop 0
	s_waitcnt vmcnt(8)
	s_waitcnt lgkmcnt(0)
	s_setprio 1
	s_barrier
	v_mfma_f32_16x16x32_bf16 v[62:65], v[86:89], v[164:167], v[62:65]
	v_mfma_f32_16x16x32_bf16 v[58:61], v[100:103], v[164:167], v[58:61]
	v_mfma_f32_16x16x32_bf16 v[46:49], v[86:89], v[172:175], v[46:49]
	v_mfma_f32_16x16x32_bf16 v[42:45], v[100:103], v[172:175], v[42:45]
	v_mfma_f32_16x16x32_bf16 v[30:33], v[86:89], v[180:183], v[30:33]
	v_mfma_f32_16x16x32_bf16 v[26:29], v[100:103], v[180:183], v[26:29]
	v_mfma_f32_16x16x32_bf16 v[14:17], v[86:89], v[188:191], v[14:17]
	v_mfma_f32_16x16x32_bf16 v[10:13], v[100:103], v[188:191], v[10:13]
	v_mfma_f32_16x16x32_bf16 v[62:65], v[90:93], v[168:171], v[62:65]
	v_mfma_f32_16x16x32_bf16 v[58:61], v[104:107], v[168:171], v[58:61]
	v_mfma_f32_16x16x32_bf16 v[46:49], v[90:93], v[176:179], v[46:49]
	v_mfma_f32_16x16x32_bf16 v[42:45], v[104:107], v[176:179], v[42:45]
	v_mfma_f32_16x16x32_bf16 v[30:33], v[90:93], v[184:187], v[30:33]
	v_mfma_f32_16x16x32_bf16 v[26:29], v[104:107], v[184:187], v[26:29]
	v_mfma_f32_16x16x32_bf16 v[14:17], v[90:93], v[192:195], v[14:17]
	v_mfma_f32_16x16x32_bf16 v[10:13], v[104:107], v[192:195], v[10:13]
	s_setprio 0
	s_setprio 1
	v_mfma_f32_16x16x32_bf16 v[54:57], v[108:111], v[164:167], v[54:57]
	v_mfma_f32_16x16x32_bf16 v[50:53], v[116:119], v[164:167], v[50:53]
	v_mfma_f32_16x16x32_bf16 v[38:41], v[108:111], v[172:175], v[38:41]
	v_mfma_f32_16x16x32_bf16 v[34:37], v[116:119], v[172:175], v[34:37]
	v_mfma_f32_16x16x32_bf16 v[22:25], v[108:111], v[180:183], v[22:25]
	v_mfma_f32_16x16x32_bf16 v[18:21], v[116:119], v[180:183], v[18:21]
	v_mfma_f32_16x16x32_bf16 v[6:9], v[108:111], v[188:191], v[6:9]
	v_mfma_f32_16x16x32_bf16 v[2:5], v[116:119], v[188:191], v[2:5]
	v_mfma_f32_16x16x32_bf16 v[54:57], v[112:115], v[168:171], v[54:57]
	v_mfma_f32_16x16x32_bf16 v[50:53], v[124:127], v[168:171], v[50:53]
	v_mfma_f32_16x16x32_bf16 v[38:41], v[112:115], v[176:179], v[38:41]
	v_mfma_f32_16x16x32_bf16 v[34:37], v[124:127], v[176:179], v[34:37]
	v_mfma_f32_16x16x32_bf16 v[22:25], v[112:115], v[184:187], v[22:25]
	v_mfma_f32_16x16x32_bf16 v[18:21], v[124:127], v[184:187], v[18:21]
	v_mfma_f32_16x16x32_bf16 v[6:9], v[112:115], v[192:195], v[6:9]
	v_mfma_f32_16x16x32_bf16 v[2:5], v[124:127], v[192:195], v[2:5]
	s_setprio 0
	s_barrier
	s_mov_b32 s100, 0
	s_add_i32 s96, s96, 2
	s_add_u32 s56, s56, 0x100
	s_addc_u32 s57, s57, 0
	s_add_u32 s95, s95, 0x100
	s_addc_u32 vcc_lo, vcc_lo, 0
	s_cmp_gt_u32 s96, 13
.LBB0_908:
	s_add_u32 s4, s56, 0xfffc0080
	s_addc_u32 s5, s57, -1
	s_add_i32 s45, 0, 0x10000
	s_cmp_eq_u32 s96, 12
	s_cselect_b32 s71, s21, s5
	s_cselect_b32 s70, s93, s4
	s_cselect_b32 s69, s15, vcc_lo
	s_cselect_b32 s68, s94, s95
	s_add_i32 s97, 0, 0x14000
	v_add_u32_e32 v104, s45, v223
	v_add_u32_e32 v124, s97, v223
	ds_read_b128 v[86:89], v104
	ds_read_b128 v[90:93], v104 offset:1024
	ds_read_b128 v[100:103], v104 offset:2048
	ds_read_b128 v[104:107], v104 offset:3072
	ds_read_b128 v[108:111], v124
	ds_read_b128 v[112:115], v124 offset:1024
	ds_read_b128 v[116:119], v124 offset:2048
	ds_read_b128 v[124:127], v124 offset:3072
	s_add_i32 s44, s74, 0
	v_lshl_add_u64 v[200:201], s[56:57], 0, v[98:99]
	s_add_i32 m0, s44, 0xc000
	ds_read_b128 v[164:167], v225
	ds_read_b128 v[168:171], v225 offset:1024
	ds_read_b128 v[172:175], v225 offset:2048
	ds_read_b128 v[176:179], v225 offset:3072
	ds_read_b128 v[180:183], v225 offset:4096
	ds_read_b128 v[184:187], v225 offset:5120
	ds_read_b128 v[188:191], v225 offset:6144
	ds_read_b128 v[192:195], v225 offset:7168
	global_load_lds_dwordx4 v[200:201], off
	v_lshl_add_u64 v[200:201], s[56:57], 0, v[206:207]
	s_add_i32 m0, s44, 0xe000
	s_nop 0
	global_load_lds_dwordx4 v[200:201], off
	s_nop 0
	s_waitcnt vmcnt(8)
	s_waitcnt lgkmcnt(0)
	s_setprio 1
	s_barrier
	v_mfma_f32_16x16x32_bf16 v[160:163], v[86:89], v[164:167], v[160:163]
	v_mfma_f32_16x16x32_bf16 v[156:159], v[100:103], v[164:167], v[156:159]
	v_mfma_f32_16x16x32_bf16 v[144:147], v[86:89], v[172:175], v[144:147]
	v_mfma_f32_16x16x32_bf16 v[140:143], v[100:103], v[172:175], v[140:143]
	v_mfma_f32_16x16x32_bf16 v[128:131], v[86:89], v[180:183], v[128:131]
	v_mfma_f32_16x16x32_bf16 v[120:123], v[100:103], v[180:183], v[120:123]
	v_mfma_f32_16x16x32_bf16 v[78:81], v[86:89], v[188:191], v[78:81]
	v_mfma_f32_16x16x32_bf16 v[74:77], v[100:103], v[188:191], v[74:77]
	v_mfma_f32_16x16x32_bf16 v[160:163], v[90:93], v[168:171], v[160:163]
	v_mfma_f32_16x16x32_bf16 v[156:159], v[104:107], v[168:171], v[156:159]
	v_mfma_f32_16x16x32_bf16 v[144:147], v[90:93], v[176:179], v[144:147]
	v_mfma_f32_16x16x32_bf16 v[140:143], v[104:107], v[176:179], v[140:143]
	v_mfma_f32_16x16x32_bf16 v[128:131], v[90:93], v[184:187], v[128:131]
	v_mfma_f32_16x16x32_bf16 v[120:123], v[104:107], v[184:187], v[120:123]
	v_mfma_f32_16x16x32_bf16 v[78:81], v[90:93], v[192:195], v[78:81]
	v_mfma_f32_16x16x32_bf16 v[74:77], v[104:107], v[192:195], v[74:77]
	s_setprio 0
	s_setprio 1
	v_mfma_f32_16x16x32_bf16 v[152:155], v[108:111], v[164:167], v[152:155]
	v_mfma_f32_16x16x32_bf16 v[148:151], v[116:119], v[164:167], v[148:151]
	v_mfma_f32_16x16x32_bf16 v[136:139], v[108:111], v[172:175], v[136:139]
	v_mfma_f32_16x16x32_bf16 v[132:135], v[116:119], v[172:175], v[132:135]
	v_mfma_f32_16x16x32_bf16 v[94:97], v[108:111], v[180:183], v[94:97]
	v_mfma_f32_16x16x32_bf16 v[82:85], v[116:119], v[180:183], v[82:85]
	v_mfma_f32_16x16x32_bf16 v[70:73], v[108:111], v[188:191], v[70:73]
	v_mfma_f32_16x16x32_bf16 v[66:69], v[116:119], v[188:191], v[66:69]
	v_mfma_f32_16x16x32_bf16 v[152:155], v[112:115], v[168:171], v[152:155]
	v_mfma_f32_16x16x32_bf16 v[148:151], v[124:127], v[168:171], v[148:151]
	v_mfma_f32_16x16x32_bf16 v[136:139], v[112:115], v[176:179], v[136:139]
	v_mfma_f32_16x16x32_bf16 v[132:135], v[124:127], v[176:179], v[132:135]
	v_mfma_f32_16x16x32_bf16 v[94:97], v[112:115], v[184:187], v[94:97]
	v_mfma_f32_16x16x32_bf16 v[82:85], v[124:127], v[184:187], v[82:85]
	v_mfma_f32_16x16x32_bf16 v[70:73], v[112:115], v[192:195], v[70:73]
	v_mfma_f32_16x16x32_bf16 v[66:69], v[124:127], v[192:195], v[66:69]
	s_setprio 0
	s_barrier
	s_add_i32 s4, s45, s74
	v_lshl_add_u64 v[200:201], s[68:69], 0, v[204:205]
	s_mov_b32 m0, s4
	ds_read_b128 v[164:167], v225 offset:16384
	ds_read_b128 v[168:171], v225 offset:17408
	ds_read_b128 v[172:175], v225 offset:18432
	ds_read_b128 v[176:179], v225 offset:19456
	ds_read_b128 v[180:183], v225 offset:20480
	ds_read_b128 v[184:187], v225 offset:21504
	ds_read_b128 v[188:191], v225 offset:22528
	ds_read_b128 v[192:195], v225 offset:23552
	global_load_lds_dwordx4 v[200:201], off
	s_add_i32 m0, s4, 0x2000
	s_add_u32 s4, s68, 0x40000
	v_lshl_add_u64 v[202:203], s[68:69], 0, v[208:209]
	s_addc_u32 s5, s69, 0
	s_add_i32 s45, s97, s74
	global_load_lds_dwordx4 v[202:203], off
	v_lshl_add_u64 v[210:211], s[4:5], 0, v[204:205]
	s_mov_b32 m0, s45
	v_lshl_add_u64 v[212:213], s[70:71], 0, v[206:207]
	global_load_lds_dwordx4 v[210:211], off
	v_lshl_add_u64 v[210:211], s[4:5], 0, v[208:209]
	s_add_i32 m0, s45, 0x2000
	s_nop 0
	global_load_lds_dwordx4 v[210:211], off
	v_lshl_add_u64 v[210:211], s[70:71], 0, v[98:99]
	s_mov_b32 m0, s44
	s_nop 0
	global_load_lds_dwordx4 v[210:211], off
	s_add_i32 m0, s44, 0x2000
	s_nop 0
	global_load_lds_dwordx4 v[212:213], off
	s_nop 0
	s_waitcnt vmcnt(8)
	s_waitcnt lgkmcnt(0)
	s_setprio 1
	s_barrier
	v_mfma_f32_16x16x32_bf16 v[62:65], v[86:89], v[164:167], v[62:65]
	v_mfma_f32_16x16x32_bf16 v[58:61], v[100:103], v[164:167], v[58:61]
	v_mfma_f32_16x16x32_bf16 v[46:49], v[86:89], v[172:175], v[46:49]
	v_mfma_f32_16x16x32_bf16 v[42:45], v[100:103], v[172:175], v[42:45]
	v_mfma_f32_16x16x32_bf16 v[30:33], v[86:89], v[180:183], v[30:33]
	v_mfma_f32_16x16x32_bf16 v[26:29], v[100:103], v[180:183], v[26:29]
	v_mfma_f32_16x16x32_bf16 v[14:17], v[86:89], v[188:191], v[14:17]
	v_mfma_f32_16x16x32_bf16 v[10:13], v[100:103], v[188:191], v[10:13]
	v_mfma_f32_16x16x32_bf16 v[62:65], v[90:93], v[168:171], v[62:65]
	v_mfma_f32_16x16x32_bf16 v[58:61], v[104:107], v[168:171], v[58:61]
	v_mfma_f32_16x16x32_bf16 v[46:49], v[90:93], v[176:179], v[46:49]
	v_mfma_f32_16x16x32_bf16 v[42:45], v[104:107], v[176:179], v[42:45]
	v_mfma_f32_16x16x32_bf16 v[30:33], v[90:93], v[184:187], v[30:33]
	v_mfma_f32_16x16x32_bf16 v[26:29], v[104:107], v[184:187], v[26:29]
	v_mfma_f32_16x16x32_bf16 v[14:17], v[90:93], v[192:195], v[14:17]
	v_mfma_f32_16x16x32_bf16 v[10:13], v[104:107], v[192:195], v[10:13]
	s_setprio 0
	s_setprio 1
	v_mfma_f32_16x16x32_bf16 v[54:57], v[108:111], v[164:167], v[54:57]
	v_mfma_f32_16x16x32_bf16 v[50:53], v[116:119], v[164:167], v[50:53]
	v_mfma_f32_16x16x32_bf16 v[38:41], v[108:111], v[172:175], v[38:41]
	v_mfma_f32_16x16x32_bf16 v[34:37], v[116:119], v[172:175], v[34:37]
	v_mfma_f32_16x16x32_bf16 v[22:25], v[108:111], v[180:183], v[22:25]
	v_mfma_f32_16x16x32_bf16 v[18:21], v[116:119], v[180:183], v[18:21]
	v_mfma_f32_16x16x32_bf16 v[6:9], v[108:111], v[188:191], v[6:9]
	v_mfma_f32_16x16x32_bf16 v[2:5], v[116:119], v[188:191], v[2:5]
	v_mfma_f32_16x16x32_bf16 v[54:57], v[112:115], v[168:171], v[54:57]
	v_mfma_f32_16x16x32_bf16 v[50:53], v[124:127], v[168:171], v[50:53]
	v_mfma_f32_16x16x32_bf16 v[38:41], v[112:115], v[176:179], v[38:41]
	v_mfma_f32_16x16x32_bf16 v[34:37], v[124:127], v[176:179], v[34:37]
	v_mfma_f32_16x16x32_bf16 v[22:25], v[112:115], v[184:187], v[22:25]
	v_mfma_f32_16x16x32_bf16 v[18:21], v[124:127], v[184:187], v[18:21]
	v_mfma_f32_16x16x32_bf16 v[6:9], v[112:115], v[192:195], v[6:9]
	v_mfma_f32_16x16x32_bf16 v[2:5], v[124:127], v[192:195], v[2:5]
	s_setprio 0
	s_barrier
	s_add_i32 s45, 0, 0x18000
	s_add_i32 s97, 0, 0x1c000
	v_add_u32_e32 v104, s45, v223
	v_add_u32_e32 v124, s97, v223
	ds_read_b128 v[86:89], v104
	ds_read_b128 v[90:93], v104 offset:1024
	ds_read_b128 v[100:103], v104 offset:2048
	ds_read_b128 v[104:107], v104 offset:3072
	ds_read_b128 v[108:111], v124
	ds_read_b128 v[112:115], v124 offset:1024
	ds_read_b128 v[116:119], v124 offset:2048
	ds_read_b128 v[124:127], v124 offset:3072
	s_add_u32 s4, s70, 0x40000
	s_addc_u32 s5, s71, 0
	v_lshl_add_u64 v[214:215], s[4:5], 0, v[98:99]
	s_add_i32 m0, s44, 0x4000
	ds_read_b128 v[164:167], v225 offset:32768
	ds_read_b128 v[168:171], v225 offset:33792
	ds_read_b128 v[172:175], v225 offset:34816
	ds_read_b128 v[176:179], v225 offset:35840
	ds_read_b128 v[180:183], v225 offset:36864
	ds_read_b128 v[184:187], v225 offset:37888
	ds_read_b128 v[188:191], v225 offset:38912
	ds_read_b128 v[192:195], v225 offset:39936
	global_load_lds_dwordx4 v[214:215], off
	v_lshl_add_u64 v[214:215], s[4:5], 0, v[206:207]
	s_add_i32 m0, s44, 0x6000
	s_nop 0
	global_load_lds_dwordx4 v[214:215], off
	s_waitcnt vmcnt(8)
	s_waitcnt lgkmcnt(0)
	s_setprio 1
	s_barrier
	v_mfma_f32_16x16x32_bf16 v[160:163], v[86:89], v[164:167], v[160:163]
	v_mfma_f32_16x16x32_bf16 v[156:159], v[100:103], v[164:167], v[156:159]
	v_mfma_f32_16x16x32_bf16 v[144:147], v[86:89], v[172:175], v[144:147]
	v_mfma_f32_16x16x32_bf16 v[140:143], v[100:103], v[172:175], v[140:143]
	v_mfma_f32_16x16x32_bf16 v[128:131], v[86:89], v[180:183], v[128:131]
	v_mfma_f32_16x16x32_bf16 v[120:123], v[100:103], v[180:183], v[120:123]
	v_mfma_f32_16x16x32_bf16 v[78:81], v[86:89], v[188:191], v[78:81]
	v_mfma_f32_16x16x32_bf16 v[74:77], v[100:103], v[188:191], v[74:77]
	v_mfma_f32_16x16x32_bf16 v[160:163], v[90:93], v[168:171], v[160:163]
	v_mfma_f32_16x16x32_bf16 v[156:159], v[104:107], v[168:171], v[156:159]
	v_mfma_f32_16x16x32_bf16 v[144:147], v[90:93], v[176:179], v[144:147]
	v_mfma_f32_16x16x32_bf16 v[140:143], v[104:107], v[176:179], v[140:143]
	v_mfma_f32_16x16x32_bf16 v[128:131], v[90:93], v[184:187], v[128:131]
	v_mfma_f32_16x16x32_bf16 v[120:123], v[104:107], v[184:187], v[120:123]
	v_mfma_f32_16x16x32_bf16 v[78:81], v[90:93], v[192:195], v[78:81]
	v_mfma_f32_16x16x32_bf16 v[74:77], v[104:107], v[192:195], v[74:77]
	s_setprio 0
	s_setprio 1
	v_mfma_f32_16x16x32_bf16 v[152:155], v[108:111], v[164:167], v[152:155]
	v_mfma_f32_16x16x32_bf16 v[148:151], v[116:119], v[164:167], v[148:151]
	v_mfma_f32_16x16x32_bf16 v[136:139], v[108:111], v[172:175], v[136:139]
	v_mfma_f32_16x16x32_bf16 v[132:135], v[116:119], v[172:175], v[132:135]
	v_mfma_f32_16x16x32_bf16 v[94:97], v[108:111], v[180:183], v[94:97]
	v_mfma_f32_16x16x32_bf16 v[82:85], v[116:119], v[180:183], v[82:85]
	v_mfma_f32_16x16x32_bf16 v[70:73], v[108:111], v[188:191], v[70:73]
	v_mfma_f32_16x16x32_bf16 v[66:69], v[116:119], v[188:191], v[66:69]
	v_mfma_f32_16x16x32_bf16 v[152:155], v[112:115], v[168:171], v[152:155]
	v_mfma_f32_16x16x32_bf16 v[148:151], v[124:127], v[168:171], v[148:151]
	v_mfma_f32_16x16x32_bf16 v[136:139], v[112:115], v[176:179], v[136:139]
	v_mfma_f32_16x16x32_bf16 v[132:135], v[124:127], v[176:179], v[132:135]
	v_mfma_f32_16x16x32_bf16 v[94:97], v[112:115], v[184:187], v[94:97]
	v_mfma_f32_16x16x32_bf16 v[82:85], v[124:127], v[184:187], v[82:85]
	v_mfma_f32_16x16x32_bf16 v[70:73], v[112:115], v[192:195], v[70:73]
	v_mfma_f32_16x16x32_bf16 v[66:69], v[124:127], v[192:195], v[66:69]
	s_setprio 0
	s_barrier
	s_add_i32 s4, s45, s74
	v_lshl_add_u64 v[200:201], v[200:201], 0, s[42:43]
	s_mov_b32 m0, s4
	ds_read_b128 v[164:167], v225 offset:49152
	ds_read_b128 v[168:171], v225 offset:50176
	ds_read_b128 v[172:175], v225 offset:51200
	ds_read_b128 v[176:179], v225 offset:52224
	ds_read_b128 v[180:183], v225 offset:53248
	ds_read_b128 v[184:187], v225 offset:54272
	ds_read_b128 v[188:191], v225 offset:55296
	ds_read_b128 v[192:195], v225 offset:56320
	global_load_lds_dwordx4 v[200:201], off
	s_add_i32 m0, s4, 0x2000
	s_add_u32 s4, s68, 0x40080
	v_lshl_add_u64 v[200:201], v[202:203], 0, s[42:43]
	s_addc_u32 s5, s69, 0
	s_add_i32 s45, s97, s74
	global_load_lds_dwordx4 v[200:201], off
	v_lshl_add_u64 v[200:201], s[4:5], 0, v[204:205]
	s_mov_b32 m0, s45
	s_nop 0
	global_load_lds_dwordx4 v[200:201], off
	v_lshl_add_u64 v[200:201], s[4:5], 0, v[208:209]
	s_add_i32 m0, s45, 0x2000
	s_nop 0
	global_load_lds_dwordx4 v[200:201], off
	v_lshl_add_u64 v[200:201], v[210:211], 0, s[42:43]
	s_add_i32 m0, s44, 0x8000
	s_nop 0
	global_load_lds_dwordx4 v[200:201], off
	v_lshl_add_u64 v[200:201], v[212:213], 0, s[42:43]
	s_add_i32 m0, s44, 0xa000
	s_nop 0
	global_load_lds_dwordx4 v[200:201], off
	s_nop 0
	s_waitcnt vmcnt(8)
	s_waitcnt lgkmcnt(0)
	s_setprio 1
	s_barrier
	v_mfma_f32_16x16x32_bf16 v[62:65], v[86:89], v[164:167], v[62:65]
	v_mfma_f32_16x16x32_bf16 v[58:61], v[100:103], v[164:167], v[58:61]
	v_mfma_f32_16x16x32_bf16 v[46:49], v[86:89], v[172:175], v[46:49]
	v_mfma_f32_16x16x32_bf16 v[42:45], v[100:103], v[172:175], v[42:45]
	v_mfma_f32_16x16x32_bf16 v[30:33], v[86:89], v[180:183], v[30:33]
	v_mfma_f32_16x16x32_bf16 v[26:29], v[100:103], v[180:183], v[26:29]
	v_mfma_f32_16x16x32_bf16 v[14:17], v[86:89], v[188:191], v[14:17]
	v_mfma_f32_16x16x32_bf16 v[10:13], v[100:103], v[188:191], v[10:13]
	v_mfma_f32_16x16x32_bf16 v[62:65], v[90:93], v[168:171], v[62:65]
	v_mfma_f32_16x16x32_bf16 v[58:61], v[104:107], v[168:171], v[58:61]
	v_mfma_f32_16x16x32_bf16 v[46:49], v[90:93], v[176:179], v[46:49]
	v_mfma_f32_16x16x32_bf16 v[42:45], v[104:107], v[176:179], v[42:45]
	v_mfma_f32_16x16x32_bf16 v[30:33], v[90:93], v[184:187], v[30:33]
	v_mfma_f32_16x16x32_bf16 v[26:29], v[104:107], v[184:187], v[26:29]
	v_mfma_f32_16x16x32_bf16 v[14:17], v[90:93], v[192:195], v[14:17]
	v_mfma_f32_16x16x32_bf16 v[10:13], v[104:107], v[192:195], v[10:13]
	s_setprio 0
	s_setprio 1
	v_mfma_f32_16x16x32_bf16 v[54:57], v[108:111], v[164:167], v[54:57]
	v_mfma_f32_16x16x32_bf16 v[50:53], v[116:119], v[164:167], v[50:53]
	v_mfma_f32_16x16x32_bf16 v[38:41], v[108:111], v[172:175], v[38:41]
	v_mfma_f32_16x16x32_bf16 v[34:37], v[116:119], v[172:175], v[34:37]
	v_mfma_f32_16x16x32_bf16 v[22:25], v[108:111], v[180:183], v[22:25]
	v_mfma_f32_16x16x32_bf16 v[18:21], v[116:119], v[180:183], v[18:21]
	v_mfma_f32_16x16x32_bf16 v[6:9], v[108:111], v[188:191], v[6:9]
	v_mfma_f32_16x16x32_bf16 v[2:5], v[116:119], v[188:191], v[2:5]
	v_mfma_f32_16x16x32_bf16 v[54:57], v[112:115], v[168:171], v[54:57]
	v_mfma_f32_16x16x32_bf16 v[50:53], v[124:127], v[168:171], v[50:53]
	v_mfma_f32_16x16x32_bf16 v[38:41], v[112:115], v[176:179], v[38:41]
	v_mfma_f32_16x16x32_bf16 v[34:37], v[124:127], v[176:179], v[34:37]
	v_mfma_f32_16x16x32_bf16 v[22:25], v[112:115], v[184:187], v[22:25]
	v_mfma_f32_16x16x32_bf16 v[18:21], v[124:127], v[184:187], v[18:21]
	v_mfma_f32_16x16x32_bf16 v[6:9], v[112:115], v[192:195], v[6:9]
	v_mfma_f32_16x16x32_bf16 v[2:5], v[124:127], v[192:195], v[2:5]
	s_setprio 0
	s_barrier
	s_add_i32 s96, s96, 2
	s_add_u32 s56, s56, 0x100
	s_addc_u32 s57, s57, 0
	s_add_u32 s95, s95, 0x100
	s_addc_u32 vcc_lo, vcc_lo, 0
	s_cmp_gt_u32 s96, 13
	s_cbranch_scc0 .LBB0_908
	s_mov_b32 s100, 1
	v_mov_b32_e32 v196, 0x2d00
	v_mov_b32_e32 v231, 0x2400
	v_mov_b32_e32 v228, 0x1b00
	s_and_b64 vcc, exec, s[0:1]
	s_movk_i32 s21, 0x4000
	s_cbranch_vccz .LBB0_911
	s_lshl_b32 s15, s92, 8
	s_add_i32 s5, s15, 0xffffc000
	s_lshr_b32 s5, s5, 12
	s_ashr_i32 s4, s92, 5
	s_add_i32 s5, s5, 2
	s_cmp_lt_i32 s92, 64
	v_add_u32_e32 v214, s15, v222
	v_readlane_b32 s56, v252, 3
	s_cselect_b32 s4, s4, s5
	v_add_u32_e32 v88, 0xffffc000, v214
	v_ashrrev_i32_e32 v215, 31, v214
	v_cmp_gt_i32_e32 vcc, s21, v214
	v_readlane_b32 s57, v252, 4
	v_readlane_b32 s58, v252, 5
	v_readlane_b32 s59, v252, 6
	v_lshl_or_b32 v212, s18, 8, v224
	s_ashr_i32 s5, s4, 31
	v_cndmask_b32_e32 v89, 0, v215, vcc
	v_cndmask_b32_e32 v88, v88, v214, vcc
	v_mov_b32_e32 v170, s59
	v_mov_b32_e32 v171, s57
	v_mov_b32_e32 v172, s58
	v_mov_b32_e32 v173, s56
	s_lshl_b64 s[4:5], s[4:5], 14
	v_ashrrev_i32_e32 v213, 31, v212
	v_cndmask_b32_e32 v91, v170, v171, vcc
	v_cndmask_b32_e32 v90, v172, v173, vcc
	v_lshlrev_b64 v[88:89], 12, v[88:89]
	s_add_u32 s44, s79, s4
	v_lshlrev_b64 v[164:165], 2, v[212:213]
	v_lshl_add_u64 v[88:89], v[90:91], 0, v[88:89]
	s_addc_u32 s45, s88, s5
	v_lshl_add_u64 v[166:167], v[88:89], 0, v[164:165]
	v_lshl_add_u64 v[86:87], s[44:45], 0, v[164:165]
	global_load_dwordx4 v[238:241], v[166:167], off
	global_load_dwordx4 v[124:127], v[86:87], off
	global_load_dwordx4 v[116:119], v[86:87], off offset:16
	global_load_dwordx4 v[242:245], v[166:167], off offset:16
	s_add_u32 s4, s89, s4
	s_addc_u32 s5, s90, s5
	v_lshl_add_u64 v[90:91], s[4:5], 0, v[164:165]
	global_load_dwordx4 v[112:115], v[90:91], off
	global_load_dwordx4 v[108:111], v[90:91], off offset:16
	global_load_dwordx4 v[100:103], v[86:87], off offset:528
	global_load_dwordx4 v[104:107], v[86:87], off offset:512
	s_nop 0
	global_load_dwordx4 v[86:89], v[90:91], off offset:528
	s_nop 0
	global_load_dwordx4 v[90:93], v[90:91], off offset:512
	s_nop 0
	global_load_dwordx4 v[246:249], v[166:167], off offset:528
	global_load_dwordx4 v[200:203], v[166:167], off offset:512
	v_or_b32_e32 v220, 16, v214
	v_ashrrev_i32_e32 v221, 31, v220
	v_add_u32_e32 v166, 0xffffc010, v214
	v_cmp_gt_i32_e32 vcc, s21, v220
	v_or_b32_e32 v216, 32, v214
	v_ashrrev_i32_e32 v217, 31, v216
	v_cndmask_b32_e32 v167, 0, v221, vcc
	v_cndmask_b32_e32 v166, v166, v220, vcc
	v_cndmask_b32_e32 v169, v170, v171, vcc
	v_cndmask_b32_e32 v168, v172, v173, vcc
	v_lshlrev_b64 v[166:167], 12, v[166:167]
	v_lshl_add_u64 v[166:167], v[168:169], 0, v[166:167]
	v_lshl_add_u64 v[166:167], v[166:167], 0, v[164:165]
	global_load_dwordx4 v[188:191], v[166:167], off offset:16
	global_load_dwordx4 v[192:195], v[166:167], off
	global_load_dwordx4 v[180:183], v[166:167], off offset:528
	global_load_dwordx4 v[184:187], v[166:167], off offset:512
	v_add_u32_e32 v166, 0xffffc020, v214
	v_cmp_gt_i32_e32 vcc, s21, v216
	v_and_b32_e32 v211, 64, v229
	v_xor_b32_e32 v210, 16, v229
	v_cndmask_b32_e32 v167, 0, v217, vcc
	v_cndmask_b32_e32 v166, v166, v216, vcc
	v_cndmask_b32_e32 v169, v170, v171, vcc
	v_cndmask_b32_e32 v168, v172, v173, vcc
	v_lshlrev_b64 v[166:167], 12, v[166:167]
	v_lshl_add_u64 v[166:167], v[168:169], 0, v[166:167]
	v_lshl_add_u64 v[168:169], v[166:167], 0, v[164:165]
	global_load_dwordx4 v[172:175], v[168:169], off offset:16
	global_load_dwordx4 v[176:179], v[168:169], off
	global_load_dwordx4 v[164:167], v[168:169], off offset:528
	s_nop 0
	global_load_dwordx4 v[168:171], v[168:169], off offset:512
	s_barrier
	s_branch .Lmy_g2b_afterload

.Lmy_sk7_pk:
	s_waitcnt lgkmcnt(0)
	s_setprio 1
	s_barrier
	v_mfma_f32_16x16x32_bf16 v[128:131], v[132:135], v[204:207], 0
	v_mfma_f32_16x16x32_bf16 v[124:127], v[140:143], v[204:207], 0
	v_mfma_f32_16x16x32_bf16 v[112:115], v[132:135], v[212:215], 0
	v_mfma_f32_16x16x32_bf16 v[108:111], v[140:143], v[212:215], 0
	v_mfma_f32_16x16x32_bf16 v[94:97], v[132:135], v[220:223], 0
	v_mfma_f32_16x16x32_bf16 v[90:93], v[140:143], v[220:223], 0
	v_mfma_f32_16x16x32_bf16 v[78:81], v[132:135], v[238:241], 0
	v_mfma_f32_16x16x32_bf16 v[74:77], v[140:143], v[238:241], 0
	v_mfma_f32_16x16x32_bf16 v[128:131], v[136:139], v[208:211], v[128:131]
	v_mfma_f32_16x16x32_bf16 v[124:127], v[144:147], v[208:211], v[124:127]
	v_mfma_f32_16x16x32_bf16 v[112:115], v[136:139], v[216:219], v[112:115]
	v_mfma_f32_16x16x32_bf16 v[108:111], v[144:147], v[216:219], v[108:111]
	v_mfma_f32_16x16x32_bf16 v[94:97], v[136:139], v[224:227], v[94:97]
	v_mfma_f32_16x16x32_bf16 v[90:93], v[144:147], v[224:227], v[90:93]
	v_mfma_f32_16x16x32_bf16 v[78:81], v[136:139], v[242:245], v[78:81]
	v_mfma_f32_16x16x32_bf16 v[74:77], v[144:147], v[242:245], v[74:77]
	s_setprio 0
	s_setprio 1
	v_mfma_f32_16x16x32_bf16 v[120:123], v[156:159], v[204:207], 0
	v_mfma_f32_16x16x32_bf16 v[116:119], v[192:195], v[204:207], 0
	v_mfma_f32_16x16x32_bf16 v[104:107], v[156:159], v[212:215], 0
	v_mfma_f32_16x16x32_bf16 v[100:103], v[192:195], v[212:215], 0
	v_mfma_f32_16x16x32_bf16 v[86:89], v[156:159], v[220:223], 0
	v_mfma_f32_16x16x32_bf16 v[82:85], v[192:195], v[220:223], 0
	v_mfma_f32_16x16x32_bf16 v[70:73], v[156:159], v[238:241], 0
	v_mfma_f32_16x16x32_bf16 v[66:69], v[192:195], v[238:241], 0
	v_mfma_f32_16x16x32_bf16 v[120:123], v[162:165], v[208:211], v[120:123]
	v_mfma_f32_16x16x32_bf16 v[116:119], v[200:203], v[208:211], v[116:119]
	v_mfma_f32_16x16x32_bf16 v[104:107], v[162:165], v[216:219], v[104:107]
	v_mfma_f32_16x16x32_bf16 v[100:103], v[200:203], v[216:219], v[100:103]
	v_mfma_f32_16x16x32_bf16 v[86:89], v[162:165], v[224:227], v[86:89]
	v_mfma_f32_16x16x32_bf16 v[82:85], v[200:203], v[224:227], v[82:85]
	v_mfma_f32_16x16x32_bf16 v[70:73], v[162:165], v[242:245], v[70:73]
	v_mfma_f32_16x16x32_bf16 v[66:69], v[200:203], v[242:245], v[66:69]
	s_setprio 0
	s_barrier
	s_add_i32 s4, s6, s70
	v_lshl_add_u64 v[166:167], s[56:57], 0, v[148:149]
	s_mov_b32 m0, s4
	ds_read_b128 v[204:207], v191 offset:16384
	ds_read_b128 v[208:211], v191 offset:17408
	ds_read_b128 v[212:215], v191 offset:18432
	ds_read_b128 v[216:219], v191 offset:19456
	ds_read_b128 v[220:223], v191 offset:20480
	ds_read_b128 v[224:227], v191 offset:21504
	ds_read_b128 v[238:241], v191 offset:22528
	ds_read_b128 v[242:245], v191 offset:23552
	global_load_lds_dwordx4 v[166:167], off
	s_add_i32 m0, s4, 0x2000
	s_add_u32 s4, s56, 0x40000
	v_lshl_add_u64 v[170:171], s[56:57], 0, v[152:153]
	s_addc_u32 s5, s57, 0
	s_add_i32 s6, s7, s70
	global_load_lds_dwordx4 v[170:171], off
	v_lshl_add_u64 v[176:177], s[4:5], 0, v[148:149]
	s_mov_b32 m0, s6
	v_lshl_add_u64 v[180:181], s[68:69], 0, v[150:151]
	global_load_lds_dwordx4 v[176:177], off
	v_lshl_add_u64 v[176:177], s[4:5], 0, v[152:153]
	s_add_i32 m0, s6, 0x2000
	s_nop 0
	global_load_lds_dwordx4 v[176:177], off
	v_lshl_add_u64 v[176:177], s[68:69], 0, v[98:99]
	s_mov_b32 m0, s44
	s_nop 0
	global_load_lds_dwordx4 v[176:177], off
	s_add_i32 m0, s44, 0x2000
	s_nop 0
	global_load_lds_dwordx4 v[180:181], off
	s_nop 0
	s_cmp_eq_u32 s100, 1
	s_cbranch_scc1 .Lmy_sk8_pk
	s_waitcnt vmcnt(8)
.Lmy_sk8_pk:
	s_waitcnt lgkmcnt(0)
	s_setprio 1
	s_barrier
	v_mfma_f32_16x16x32_bf16 v[62:65], v[132:135], v[204:207], 0
	v_mfma_f32_16x16x32_bf16 v[58:61], v[140:143], v[204:207], 0
	v_mfma_f32_16x16x32_bf16 v[46:49], v[132:135], v[212:215], 0
	v_mfma_f32_16x16x32_bf16 v[42:45], v[140:143], v[212:215], 0
	v_mfma_f32_16x16x32_bf16 v[30:33], v[132:135], v[220:223], 0
	v_mfma_f32_16x16x32_bf16 v[26:29], v[140:143], v[220:223], 0
	v_mfma_f32_16x16x32_bf16 v[14:17], v[132:135], v[238:241], 0
	v_mfma_f32_16x16x32_bf16 v[10:13], v[140:143], v[238:241], 0
	v_mfma_f32_16x16x32_bf16 v[62:65], v[136:139], v[208:211], v[62:65]
	v_mfma_f32_16x16x32_bf16 v[58:61], v[144:147], v[208:211], v[58:61]
	v_mfma_f32_16x16x32_bf16 v[46:49], v[136:139], v[216:219], v[46:49]
	v_mfma_f32_16x16x32_bf16 v[42:45], v[144:147], v[216:219], v[42:45]
	v_mfma_f32_16x16x32_bf16 v[30:33], v[136:139], v[224:227], v[30:33]
	v_mfma_f32_16x16x32_bf16 v[26:29], v[144:147], v[224:227], v[26:29]
	v_mfma_f32_16x16x32_bf16 v[14:17], v[136:139], v[242:245], v[14:17]
	v_mfma_f32_16x16x32_bf16 v[10:13], v[144:147], v[242:245], v[10:13]
	s_setprio 0
	s_setprio 1
	v_mfma_f32_16x16x32_bf16 v[54:57], v[156:159], v[204:207], 0
	v_mfma_f32_16x16x32_bf16 v[50:53], v[192:195], v[204:207], 0
	v_mfma_f32_16x16x32_bf16 v[38:41], v[156:159], v[212:215], 0
	v_mfma_f32_16x16x32_bf16 v[34:37], v[192:195], v[212:215], 0
	v_mfma_f32_16x16x32_bf16 v[22:25], v[156:159], v[220:223], 0
	v_mfma_f32_16x16x32_bf16 v[18:21], v[192:195], v[220:223], 0
	v_mfma_f32_16x16x32_bf16 v[6:9], v[156:159], v[238:241], 0
	v_mfma_f32_16x16x32_bf16 v[2:5], v[192:195], v[238:241], 0
	v_mfma_f32_16x16x32_bf16 v[54:57], v[162:165], v[208:211], v[54:57]
	v_mfma_f32_16x16x32_bf16 v[50:53], v[200:203], v[208:211], v[50:53]
	v_mfma_f32_16x16x32_bf16 v[38:41], v[162:165], v[216:219], v[38:41]
	v_mfma_f32_16x16x32_bf16 v[34:37], v[200:203], v[216:219], v[34:37]
	v_mfma_f32_16x16x32_bf16 v[22:25], v[162:165], v[224:227], v[22:25]
	v_mfma_f32_16x16x32_bf16 v[18:21], v[200:203], v[224:227], v[18:21]
	v_mfma_f32_16x16x32_bf16 v[6:9], v[162:165], v[242:245], v[6:9]
	v_mfma_f32_16x16x32_bf16 v[2:5], v[200:203], v[242:245], v[2:5]
	s_setprio 0
	s_barrier
	s_add_i32 s6, 0, 0x18000
	s_add_i32 s7, 0, 0x1c000
	v_add_u32_e32 v144, s6, v189
	v_add_u32_e32 v160, s7, v189
	ds_read_b128 v[132:135], v144
	ds_read_b128 v[136:139], v144 offset:1024
	ds_read_b128 v[140:143], v144 offset:2048
	ds_read_b128 v[144:147], v144 offset:3072
	ds_read_b128 v[156:159], v160
	ds_read_b128 v[162:165], v160 offset:1024
	ds_read_b128 v[192:195], v160 offset:2048
	ds_read_b128 v[200:203], v160 offset:3072
	s_add_u32 s4, s68, 0x40000
	s_addc_u32 s5, s69, 0
	v_lshl_add_u64 v[246:247], s[4:5], 0, v[98:99]
	s_add_i32 m0, s44, 0x4000
	ds_read_b128 v[204:207], v191 offset:32768
	ds_read_b128 v[208:211], v191 offset:33792
	ds_read_b128 v[212:215], v191 offset:34816
	ds_read_b128 v[216:219], v191 offset:35840
	ds_read_b128 v[220:223], v191 offset:36864
	ds_read_b128 v[224:227], v191 offset:37888
	ds_read_b128 v[238:241], v191 offset:38912
	ds_read_b128 v[242:245], v191 offset:39936
	global_load_lds_dwordx4 v[246:247], off
	v_lshl_add_u64 v[246:247], s[4:5], 0, v[150:151]
	s_add_i32 m0, s44, 0x6000
	s_nop 0
	global_load_lds_dwordx4 v[246:247], off
	s_waitcnt vmcnt(8)
	s_waitcnt lgkmcnt(0)
	s_setprio 1
	s_barrier
	v_mfma_f32_16x16x32_bf16 v[128:131], v[132:135], v[204:207], v[128:131]
	v_mfma_f32_16x16x32_bf16 v[124:127], v[140:143], v[204:207], v[124:127]
	v_mfma_f32_16x16x32_bf16 v[112:115], v[132:135], v[212:215], v[112:115]
	v_mfma_f32_16x16x32_bf16 v[108:111], v[140:143], v[212:215], v[108:111]
	v_mfma_f32_16x16x32_bf16 v[94:97], v[132:135], v[220:223], v[94:97]
	v_mfma_f32_16x16x32_bf16 v[90:93], v[140:143], v[220:223], v[90:93]
	v_mfma_f32_16x16x32_bf16 v[78:81], v[132:135], v[238:241], v[78:81]
	v_mfma_f32_16x16x32_bf16 v[74:77], v[140:143], v[238:241], v[74:77]
	v_mfma_f32_16x16x32_bf16 v[128:131], v[136:139], v[208:211], v[128:131]
	v_mfma_f32_16x16x32_bf16 v[124:127], v[144:147], v[208:211], v[124:127]
	v_mfma_f32_16x16x32_bf16 v[112:115], v[136:139], v[216:219], v[112:115]
	v_mfma_f32_16x16x32_bf16 v[108:111], v[144:147], v[216:219], v[108:111]
	v_mfma_f32_16x16x32_bf16 v[94:97], v[136:139], v[224:227], v[94:97]
	v_mfma_f32_16x16x32_bf16 v[90:93], v[144:147], v[224:227], v[90:93]
	v_mfma_f32_16x16x32_bf16 v[78:81], v[136:139], v[242:245], v[78:81]
	v_mfma_f32_16x16x32_bf16 v[74:77], v[144:147], v[242:245], v[74:77]
	s_setprio 0
	s_setprio 1
	v_mfma_f32_16x16x32_bf16 v[120:123], v[156:159], v[204:207], v[120:123]
	v_mfma_f32_16x16x32_bf16 v[116:119], v[192:195], v[204:207], v[116:119]
	v_mfma_f32_16x16x32_bf16 v[104:107], v[156:159], v[212:215], v[104:107]
	v_mfma_f32_16x16x32_bf16 v[100:103], v[192:195], v[212:215], v[100:103]
	v_mfma_f32_16x16x32_bf16 v[86:89], v[156:159], v[220:223], v[86:89]
	v_mfma_f32_16x16x32_bf16 v[82:85], v[192:195], v[220:223], v[82:85]
	v_mfma_f32_16x16x32_bf16 v[70:73], v[156:159], v[238:241], v[70:73]
	v_mfma_f32_16x16x32_bf16 v[66:69], v[192:195], v[238:241], v[66:69]
	v_mfma_f32_16x16x32_bf16 v[120:123], v[162:165], v[208:211], v[120:123]
	v_mfma_f32_16x16x32_bf16 v[116:119], v[200:203], v[208:211], v[116:119]
	v_mfma_f32_16x16x32_bf16 v[104:107], v[162:165], v[216:219], v[104:107]
	v_mfma_f32_16x16x32_bf16 v[100:103], v[200:203], v[216:219], v[100:103]
	v_mfma_f32_16x16x32_bf16 v[86:89], v[162:165], v[224:227], v[86:89]
	v_mfma_f32_16x16x32_bf16 v[82:85], v[200:203], v[224:227], v[82:85]
	v_mfma_f32_16x16x32_bf16 v[70:73], v[162:165], v[242:245], v[70:73]
	v_mfma_f32_16x16x32_bf16 v[66:69], v[200:203], v[242:245], v[66:69]
	s_setprio 0
	s_barrier
	s_add_i32 s4, s6, s70
	v_lshl_add_u64 v[166:167], v[166:167], 0, s[42:43]
	s_mov_b32 m0, s4
	ds_read_b128 v[204:207], v191 offset:49152
	ds_read_b128 v[208:211], v191 offset:50176
	ds_read_b128 v[212:215], v191 offset:51200
	ds_read_b128 v[216:219], v191 offset:52224
	ds_read_b128 v[220:223], v191 offset:53248
	ds_read_b128 v[224:227], v191 offset:54272
	ds_read_b128 v[238:241], v191 offset:55296
	ds_read_b128 v[242:245], v191 offset:56320
	global_load_lds_dwordx4 v[166:167], off
	s_add_i32 m0, s4, 0x2000
	s_add_u32 s4, s56, 0x40080
	v_lshl_add_u64 v[166:167], v[170:171], 0, s[42:43]
	s_addc_u32 s5, s57, 0
	s_add_i32 s6, s7, s70
	global_load_lds_dwordx4 v[166:167], off
	v_lshl_add_u64 v[166:167], s[4:5], 0, v[148:149]
	s_mov_b32 m0, s6
	s_nop 0
	global_load_lds_dwordx4 v[166:167], off
	v_lshl_add_u64 v[166:167], s[4:5], 0, v[152:153]
	s_add_i32 m0, s6, 0x2000
	s_nop 0
	global_load_lds_dwordx4 v[166:167], off
	v_lshl_add_u64 v[166:167], v[176:177], 0, s[42:43]
	s_add_i32 m0, s44, 0x8000
	s_nop 0
	global_load_lds_dwordx4 v[166:167], off
	v_lshl_add_u64 v[166:167], v[180:181], 0, s[42:43]
	s_add_i32 m0, s44, 0xa000
	s_nop 0
	global_load_lds_dwordx4 v[166:167], off
	s_nop 0
	s_waitcnt vmcnt(8)
	s_waitcnt lgkmcnt(0)
	s_setprio 1
	s_barrier
	v_mfma_f32_16x16x32_bf16 v[62:65], v[132:135], v[204:207], v[62:65]
	v_mfma_f32_16x16x32_bf16 v[58:61], v[140:143], v[204:207], v[58:61]
	v_mfma_f32_16x16x32_bf16 v[46:49], v[132:135], v[212:215], v[46:49]
	v_mfma_f32_16x16x32_bf16 v[42:45], v[140:143], v[212:215], v[42:45]
	v_mfma_f32_16x16x32_bf16 v[30:33], v[132:135], v[220:223], v[30:33]
	v_mfma_f32_16x16x32_bf16 v[26:29], v[140:143], v[220:223], v[26:29]
	v_mfma_f32_16x16x32_bf16 v[14:17], v[132:135], v[238:241], v[14:17]
	v_mfma_f32_16x16x32_bf16 v[10:13], v[140:143], v[238:241], v[10:13]
	v_mfma_f32_16x16x32_bf16 v[62:65], v[136:139], v[208:211], v[62:65]
	v_mfma_f32_16x16x32_bf16 v[58:61], v[144:147], v[208:211], v[58:61]
	v_mfma_f32_16x16x32_bf16 v[46:49], v[136:139], v[216:219], v[46:49]
	v_mfma_f32_16x16x32_bf16 v[42:45], v[144:147], v[216:219], v[42:45]
	v_mfma_f32_16x16x32_bf16 v[30:33], v[136:139], v[224:227], v[30:33]
	v_mfma_f32_16x16x32_bf16 v[26:29], v[144:147], v[224:227], v[26:29]
	v_mfma_f32_16x16x32_bf16 v[14:17], v[136:139], v[242:245], v[14:17]
	v_mfma_f32_16x16x32_bf16 v[10:13], v[144:147], v[242:245], v[10:13]
	s_setprio 0
	s_setprio 1
	v_mfma_f32_16x16x32_bf16 v[54:57], v[156:159], v[204:207], v[54:57]
	v_mfma_f32_16x16x32_bf16 v[50:53], v[192:195], v[204:207], v[50:53]
	v_mfma_f32_16x16x32_bf16 v[38:41], v[156:159], v[212:215], v[38:41]
	v_mfma_f32_16x16x32_bf16 v[34:37], v[192:195], v[212:215], v[34:37]
	v_mfma_f32_16x16x32_bf16 v[22:25], v[156:159], v[220:223], v[22:25]
	v_mfma_f32_16x16x32_bf16 v[18:21], v[192:195], v[220:223], v[18:21]
	v_mfma_f32_16x16x32_bf16 v[6:9], v[156:159], v[238:241], v[6:9]
	v_mfma_f32_16x16x32_bf16 v[2:5], v[192:195], v[238:241], v[2:5]
	v_mfma_f32_16x16x32_bf16 v[54:57], v[162:165], v[208:211], v[54:57]
	v_mfma_f32_16x16x32_bf16 v[50:53], v[200:203], v[208:211], v[50:53]
	v_mfma_f32_16x16x32_bf16 v[38:41], v[162:165], v[216:219], v[38:41]
	v_mfma_f32_16x16x32_bf16 v[34:37], v[200:203], v[216:219], v[34:37]
	v_mfma_f32_16x16x32_bf16 v[22:25], v[162:165], v[224:227], v[22:25]
	v_mfma_f32_16x16x32_bf16 v[18:21], v[200:203], v[224:227], v[18:21]
	v_mfma_f32_16x16x32_bf16 v[6:9], v[162:165], v[242:245], v[6:9]
	v_mfma_f32_16x16x32_bf16 v[2:5], v[200:203], v[242:245], v[2:5]
	s_setprio 0
	s_barrier
	s_mov_b32 s100, 0
	s_add_i32 s92, s92, 2
	s_add_u32 s40, s40, 0x100
	s_addc_u32 s41, s41, 0
	s_add_u32 s90, s90, 0x100
	s_addc_u32 s91, s91, 0
	s_cmp_gt_u32 s92, 13
.LBB0_1011:
	s_add_u32 s4, s40, 0xfffc0080
	s_addc_u32 s5, s41, -1
	s_add_i32 s6, 0, 0x10000
	s_cmp_eq_u32 s92, 12
	s_cselect_b32 s69, s21, s5
	s_cselect_b32 s68, s88, s4
	s_cselect_b32 s57, s15, s91
	s_cselect_b32 s56, s89, s90
	s_add_i32 s7, 0, 0x14000
	v_add_u32_e32 v144, s6, v189
	v_add_u32_e32 v160, s7, v189
	ds_read_b128 v[132:135], v144
	ds_read_b128 v[136:139], v144 offset:1024
	ds_read_b128 v[140:143], v144 offset:2048
	ds_read_b128 v[144:147], v144 offset:3072
	ds_read_b128 v[156:159], v160
	ds_read_b128 v[162:165], v160 offset:1024
	ds_read_b128 v[192:195], v160 offset:2048
	ds_read_b128 v[200:203], v160 offset:3072
	s_add_i32 s44, s70, 0
	v_lshl_add_u64 v[166:167], s[40:41], 0, v[98:99]
	s_add_i32 m0, s44, 0xc000
	ds_read_b128 v[204:207], v191
	ds_read_b128 v[208:211], v191 offset:1024
	ds_read_b128 v[212:215], v191 offset:2048
	ds_read_b128 v[216:219], v191 offset:3072
	ds_read_b128 v[220:223], v191 offset:4096
	ds_read_b128 v[224:227], v191 offset:5120
	ds_read_b128 v[238:241], v191 offset:6144
	ds_read_b128 v[242:245], v191 offset:7168
	global_load_lds_dwordx4 v[166:167], off
	v_lshl_add_u64 v[166:167], s[40:41], 0, v[150:151]
	s_add_i32 m0, s44, 0xe000
	s_nop 0
	global_load_lds_dwordx4 v[166:167], off
	s_nop 0
	s_waitcnt vmcnt(8)
	s_waitcnt lgkmcnt(0)
	s_setprio 1
	s_barrier
	v_mfma_f32_16x16x32_bf16 v[128:131], v[132:135], v[204:207], v[128:131]
	v_mfma_f32_16x16x32_bf16 v[124:127], v[140:143], v[204:207], v[124:127]
	v_mfma_f32_16x16x32_bf16 v[112:115], v[132:135], v[212:215], v[112:115]
	v_mfma_f32_16x16x32_bf16 v[108:111], v[140:143], v[212:215], v[108:111]
	v_mfma_f32_16x16x32_bf16 v[94:97], v[132:135], v[220:223], v[94:97]
	v_mfma_f32_16x16x32_bf16 v[90:93], v[140:143], v[220:223], v[90:93]
	v_mfma_f32_16x16x32_bf16 v[78:81], v[132:135], v[238:241], v[78:81]
	v_mfma_f32_16x16x32_bf16 v[74:77], v[140:143], v[238:241], v[74:77]
	v_mfma_f32_16x16x32_bf16 v[128:131], v[136:139], v[208:211], v[128:131]
	v_mfma_f32_16x16x32_bf16 v[124:127], v[144:147], v[208:211], v[124:127]
	v_mfma_f32_16x16x32_bf16 v[112:115], v[136:139], v[216:219], v[112:115]
	v_mfma_f32_16x16x32_bf16 v[108:111], v[144:147], v[216:219], v[108:111]
	v_mfma_f32_16x16x32_bf16 v[94:97], v[136:139], v[224:227], v[94:97]
	v_mfma_f32_16x16x32_bf16 v[90:93], v[144:147], v[224:227], v[90:93]
	v_mfma_f32_16x16x32_bf16 v[78:81], v[136:139], v[242:245], v[78:81]
	v_mfma_f32_16x16x32_bf16 v[74:77], v[144:147], v[242:245], v[74:77]
	s_setprio 0
	s_setprio 1
	v_mfma_f32_16x16x32_bf16 v[120:123], v[156:159], v[204:207], v[120:123]
	v_mfma_f32_16x16x32_bf16 v[116:119], v[192:195], v[204:207], v[116:119]
	v_mfma_f32_16x16x32_bf16 v[104:107], v[156:159], v[212:215], v[104:107]
	v_mfma_f32_16x16x32_bf16 v[100:103], v[192:195], v[212:215], v[100:103]
	v_mfma_f32_16x16x32_bf16 v[86:89], v[156:159], v[220:223], v[86:89]
	v_mfma_f32_16x16x32_bf16 v[82:85], v[192:195], v[220:223], v[82:85]
	v_mfma_f32_16x16x32_bf16 v[70:73], v[156:159], v[238:241], v[70:73]
	v_mfma_f32_16x16x32_bf16 v[66:69], v[192:195], v[238:241], v[66:69]
	v_mfma_f32_16x16x32_bf16 v[120:123], v[162:165], v[208:211], v[120:123]
	v_mfma_f32_16x16x32_bf16 v[116:119], v[200:203], v[208:211], v[116:119]
	v_mfma_f32_16x16x32_bf16 v[104:107], v[162:165], v[216:219], v[104:107]
	v_mfma_f32_16x16x32_bf16 v[100:103], v[200:203], v[216:219], v[100:103]
	v_mfma_f32_16x16x32_bf16 v[86:89], v[162:165], v[224:227], v[86:89]
	v_mfma_f32_16x16x32_bf16 v[82:85], v[200:203], v[224:227], v[82:85]
	v_mfma_f32_16x16x32_bf16 v[70:73], v[162:165], v[242:245], v[70:73]
	v_mfma_f32_16x16x32_bf16 v[66:69], v[200:203], v[242:245], v[66:69]
	s_setprio 0
	s_barrier
	s_add_i32 s4, s6, s70
	v_lshl_add_u64 v[166:167], s[56:57], 0, v[148:149]
	s_mov_b32 m0, s4
	ds_read_b128 v[204:207], v191 offset:16384
	ds_read_b128 v[208:211], v191 offset:17408
	ds_read_b128 v[212:215], v191 offset:18432
	ds_read_b128 v[216:219], v191 offset:19456
	ds_read_b128 v[220:223], v191 offset:20480
	ds_read_b128 v[224:227], v191 offset:21504
	ds_read_b128 v[238:241], v191 offset:22528
	ds_read_b128 v[242:245], v191 offset:23552
	global_load_lds_dwordx4 v[166:167], off
	s_add_i32 m0, s4, 0x2000
	s_add_u32 s4, s56, 0x40000
	v_lshl_add_u64 v[170:171], s[56:57], 0, v[152:153]
	s_addc_u32 s5, s57, 0
	s_add_i32 s6, s7, s70
	global_load_lds_dwordx4 v[170:171], off
	v_lshl_add_u64 v[176:177], s[4:5], 0, v[148:149]
	s_mov_b32 m0, s6
	v_lshl_add_u64 v[180:181], s[68:69], 0, v[150:151]
	global_load_lds_dwordx4 v[176:177], off
	v_lshl_add_u64 v[176:177], s[4:5], 0, v[152:153]
	s_add_i32 m0, s6, 0x2000
	s_nop 0
	global_load_lds_dwordx4 v[176:177], off
	v_lshl_add_u64 v[176:177], s[68:69], 0, v[98:99]
	s_mov_b32 m0, s44
	s_nop 0
	global_load_lds_dwordx4 v[176:177], off
	s_add_i32 m0, s44, 0x2000
	s_nop 0
	global_load_lds_dwordx4 v[180:181], off
	s_nop 0
	s_waitcnt vmcnt(8)
	s_waitcnt lgkmcnt(0)
	s_setprio 1
	s_barrier
	v_mfma_f32_16x16x32_bf16 v[62:65], v[132:135], v[204:207], v[62:65]
	v_mfma_f32_16x16x32_bf16 v[58:61], v[140:143], v[204:207], v[58:61]
	v_mfma_f32_16x16x32_bf16 v[46:49], v[132:135], v[212:215], v[46:49]
	v_mfma_f32_16x16x32_bf16 v[42:45], v[140:143], v[212:215], v[42:45]
	v_mfma_f32_16x16x32_bf16 v[30:33], v[132:135], v[220:223], v[30:33]
	v_mfma_f32_16x16x32_bf16 v[26:29], v[140:143], v[220:223], v[26:29]
	v_mfma_f32_16x16x32_bf16 v[14:17], v[132:135], v[238:241], v[14:17]
	v_mfma_f32_16x16x32_bf16 v[10:13], v[140:143], v[238:241], v[10:13]
	v_mfma_f32_16x16x32_bf16 v[62:65], v[136:139], v[208:211], v[62:65]
	v_mfma_f32_16x16x32_bf16 v[58:61], v[144:147], v[208:211], v[58:61]
	v_mfma_f32_16x16x32_bf16 v[46:49], v[136:139], v[216:219], v[46:49]
	v_mfma_f32_16x16x32_bf16 v[42:45], v[144:147], v[216:219], v[42:45]
	v_mfma_f32_16x16x32_bf16 v[30:33], v[136:139], v[224:227], v[30:33]
	v_mfma_f32_16x16x32_bf16 v[26:29], v[144:147], v[224:227], v[26:29]
	v_mfma_f32_16x16x32_bf16 v[14:17], v[136:139], v[242:245], v[14:17]
	v_mfma_f32_16x16x32_bf16 v[10:13], v[144:147], v[242:245], v[10:13]
	s_setprio 0
	s_setprio 1
	v_mfma_f32_16x16x32_bf16 v[54:57], v[156:159], v[204:207], v[54:57]
	v_mfma_f32_16x16x32_bf16 v[50:53], v[192:195], v[204:207], v[50:53]
	v_mfma_f32_16x16x32_bf16 v[38:41], v[156:159], v[212:215], v[38:41]
	v_mfma_f32_16x16x32_bf16 v[34:37], v[192:195], v[212:215], v[34:37]
	v_mfma_f32_16x16x32_bf16 v[22:25], v[156:159], v[220:223], v[22:25]
	v_mfma_f32_16x16x32_bf16 v[18:21], v[192:195], v[220:223], v[18:21]
	v_mfma_f32_16x16x32_bf16 v[6:9], v[156:159], v[238:241], v[6:9]
	v_mfma_f32_16x16x32_bf16 v[2:5], v[192:195], v[238:241], v[2:5]
	v_mfma_f32_16x16x32_bf16 v[54:57], v[162:165], v[208:211], v[54:57]
	v_mfma_f32_16x16x32_bf16 v[50:53], v[200:203], v[208:211], v[50:53]
	v_mfma_f32_16x16x32_bf16 v[38:41], v[162:165], v[216:219], v[38:41]
	v_mfma_f32_16x16x32_bf16 v[34:37], v[200:203], v[216:219], v[34:37]
	v_mfma_f32_16x16x32_bf16 v[22:25], v[162:165], v[224:227], v[22:25]
	v_mfma_f32_16x16x32_bf16 v[18:21], v[200:203], v[224:227], v[18:21]
	v_mfma_f32_16x16x32_bf16 v[6:9], v[162:165], v[242:245], v[6:9]
	v_mfma_f32_16x16x32_bf16 v[2:5], v[200:203], v[242:245], v[2:5]
	s_setprio 0
	s_barrier
	s_add_i32 s6, 0, 0x18000
	s_add_i32 s7, 0, 0x1c000
	v_add_u32_e32 v144, s6, v189
	v_add_u32_e32 v160, s7, v189
	ds_read_b128 v[132:135], v144
	ds_read_b128 v[136:139], v144 offset:1024
	ds_read_b128 v[140:143], v144 offset:2048
	ds_read_b128 v[144:147], v144 offset:3072
	ds_read_b128 v[156:159], v160
	ds_read_b128 v[162:165], v160 offset:1024
	ds_read_b128 v[192:195], v160 offset:2048
	ds_read_b128 v[200:203], v160 offset:3072
	s_add_u32 s4, s68, 0x40000
	s_addc_u32 s5, s69, 0
	v_lshl_add_u64 v[246:247], s[4:5], 0, v[98:99]
	s_add_i32 m0, s44, 0x4000
	ds_read_b128 v[204:207], v191 offset:32768
	ds_read_b128 v[208:211], v191 offset:33792
	ds_read_b128 v[212:215], v191 offset:34816
	ds_read_b128 v[216:219], v191 offset:35840
	ds_read_b128 v[220:223], v191 offset:36864
	ds_read_b128 v[224:227], v191 offset:37888
	ds_read_b128 v[238:241], v191 offset:38912
	ds_read_b128 v[242:245], v191 offset:39936
	global_load_lds_dwordx4 v[246:247], off
	v_lshl_add_u64 v[246:247], s[4:5], 0, v[150:151]
	s_add_i32 m0, s44, 0x6000
	s_nop 0
	global_load_lds_dwordx4 v[246:247], off
	s_waitcnt vmcnt(8)
	s_waitcnt lgkmcnt(0)
	s_setprio 1
	s_barrier
	v_mfma_f32_16x16x32_bf16 v[128:131], v[132:135], v[204:207], v[128:131]
	v_mfma_f32_16x16x32_bf16 v[124:127], v[140:143], v[204:207], v[124:127]
	v_mfma_f32_16x16x32_bf16 v[112:115], v[132:135], v[212:215], v[112:115]
	v_mfma_f32_16x16x32_bf16 v[108:111], v[140:143], v[212:215], v[108:111]
	v_mfma_f32_16x16x32_bf16 v[94:97], v[132:135], v[220:223], v[94:97]
	v_mfma_f32_16x16x32_bf16 v[90:93], v[140:143], v[220:223], v[90:93]
	v_mfma_f32_16x16x32_bf16 v[78:81], v[132:135], v[238:241], v[78:81]
	v_mfma_f32_16x16x32_bf16 v[74:77], v[140:143], v[238:241], v[74:77]
	v_mfma_f32_16x16x32_bf16 v[128:131], v[136:139], v[208:211], v[128:131]
	v_mfma_f32_16x16x32_bf16 v[124:127], v[144:147], v[208:211], v[124:127]
	v_mfma_f32_16x16x32_bf16 v[112:115], v[136:139], v[216:219], v[112:115]
	v_mfma_f32_16x16x32_bf16 v[108:111], v[144:147], v[216:219], v[108:111]
	v_mfma_f32_16x16x32_bf16 v[94:97], v[136:139], v[224:227], v[94:97]
	v_mfma_f32_16x16x32_bf16 v[90:93], v[144:147], v[224:227], v[90:93]
	v_mfma_f32_16x16x32_bf16 v[78:81], v[136:139], v[242:245], v[78:81]
	v_mfma_f32_16x16x32_bf16 v[74:77], v[144:147], v[242:245], v[74:77]
	s_setprio 0
	s_setprio 1
	v_mfma_f32_16x16x32_bf16 v[120:123], v[156:159], v[204:207], v[120:123]
	v_mfma_f32_16x16x32_bf16 v[116:119], v[192:195], v[204:207], v[116:119]
	v_mfma_f32_16x16x32_bf16 v[104:107], v[156:159], v[212:215], v[104:107]
	v_mfma_f32_16x16x32_bf16 v[100:103], v[192:195], v[212:215], v[100:103]
	v_mfma_f32_16x16x32_bf16 v[86:89], v[156:159], v[220:223], v[86:89]
	v_mfma_f32_16x16x32_bf16 v[82:85], v[192:195], v[220:223], v[82:85]
	v_mfma_f32_16x16x32_bf16 v[70:73], v[156:159], v[238:241], v[70:73]
	v_mfma_f32_16x16x32_bf16 v[66:69], v[192:195], v[238:241], v[66:69]
	v_mfma_f32_16x16x32_bf16 v[120:123], v[162:165], v[208:211], v[120:123]
	v_mfma_f32_16x16x32_bf16 v[116:119], v[200:203], v[208:211], v[116:119]
	v_mfma_f32_16x16x32_bf16 v[104:107], v[162:165], v[216:219], v[104:107]
	v_mfma_f32_16x16x32_bf16 v[100:103], v[200:203], v[216:219], v[100:103]
	v_mfma_f32_16x16x32_bf16 v[86:89], v[162:165], v[224:227], v[86:89]
	v_mfma_f32_16x16x32_bf16 v[82:85], v[200:203], v[224:227], v[82:85]
	v_mfma_f32_16x16x32_bf16 v[70:73], v[162:165], v[242:245], v[70:73]
	v_mfma_f32_16x16x32_bf16 v[66:69], v[200:203], v[242:245], v[66:69]
	s_setprio 0
	s_barrier
	s_add_i32 s4, s6, s70
	v_lshl_add_u64 v[166:167], v[166:167], 0, s[42:43]
	s_mov_b32 m0, s4
	ds_read_b128 v[204:207], v191 offset:49152
	ds_read_b128 v[208:211], v191 offset:50176
	ds_read_b128 v[212:215], v191 offset:51200
	ds_read_b128 v[216:219], v191 offset:52224
	ds_read_b128 v[220:223], v191 offset:53248
	ds_read_b128 v[224:227], v191 offset:54272
	ds_read_b128 v[238:241], v191 offset:55296
	ds_read_b128 v[242:245], v191 offset:56320
	global_load_lds_dwordx4 v[166:167], off
	s_add_i32 m0, s4, 0x2000
	s_add_u32 s4, s56, 0x40080
	v_lshl_add_u64 v[166:167], v[170:171], 0, s[42:43]
	s_addc_u32 s5, s57, 0
	s_add_i32 s6, s7, s70
	global_load_lds_dwordx4 v[166:167], off
	v_lshl_add_u64 v[166:167], s[4:5], 0, v[148:149]
	s_mov_b32 m0, s6
	s_nop 0
	global_load_lds_dwordx4 v[166:167], off
	v_lshl_add_u64 v[166:167], s[4:5], 0, v[152:153]
	s_add_i32 m0, s6, 0x2000
	s_nop 0
	global_load_lds_dwordx4 v[166:167], off
	v_lshl_add_u64 v[166:167], v[176:177], 0, s[42:43]
	s_add_i32 m0, s44, 0x8000
	s_nop 0
	global_load_lds_dwordx4 v[166:167], off
	v_lshl_add_u64 v[166:167], v[180:181], 0, s[42:43]
	s_add_i32 m0, s44, 0xa000
	s_nop 0
	global_load_lds_dwordx4 v[166:167], off
	s_nop 0
	s_waitcnt vmcnt(8)
	s_waitcnt lgkmcnt(0)
	s_setprio 1
	s_barrier
	v_mfma_f32_16x16x32_bf16 v[62:65], v[132:135], v[204:207], v[62:65]
	v_mfma_f32_16x16x32_bf16 v[58:61], v[140:143], v[204:207], v[58:61]
	v_mfma_f32_16x16x32_bf16 v[46:49], v[132:135], v[212:215], v[46:49]
	v_mfma_f32_16x16x32_bf16 v[42:45], v[140:143], v[212:215], v[42:45]
	v_mfma_f32_16x16x32_bf16 v[30:33], v[132:135], v[220:223], v[30:33]
	v_mfma_f32_16x16x32_bf16 v[26:29], v[140:143], v[220:223], v[26:29]
	v_mfma_f32_16x16x32_bf16 v[14:17], v[132:135], v[238:241], v[14:17]
	v_mfma_f32_16x16x32_bf16 v[10:13], v[140:143], v[238:241], v[10:13]
	v_mfma_f32_16x16x32_bf16 v[62:65], v[136:139], v[208:211], v[62:65]
	v_mfma_f32_16x16x32_bf16 v[58:61], v[144:147], v[208:211], v[58:61]
	v_mfma_f32_16x16x32_bf16 v[46:49], v[136:139], v[216:219], v[46:49]
	v_mfma_f32_16x16x32_bf16 v[42:45], v[144:147], v[216:219], v[42:45]
	v_mfma_f32_16x16x32_bf16 v[30:33], v[136:139], v[224:227], v[30:33]
	v_mfma_f32_16x16x32_bf16 v[26:29], v[144:147], v[224:227], v[26:29]
	v_mfma_f32_16x16x32_bf16 v[14:17], v[136:139], v[242:245], v[14:17]
	v_mfma_f32_16x16x32_bf16 v[10:13], v[144:147], v[242:245], v[10:13]
	s_setprio 0
	s_setprio 1
	v_mfma_f32_16x16x32_bf16 v[54:57], v[156:159], v[204:207], v[54:57]
	v_mfma_f32_16x16x32_bf16 v[50:53], v[192:195], v[204:207], v[50:53]
	v_mfma_f32_16x16x32_bf16 v[38:41], v[156:159], v[212:215], v[38:41]
	v_mfma_f32_16x16x32_bf16 v[34:37], v[192:195], v[212:215], v[34:37]
	v_mfma_f32_16x16x32_bf16 v[22:25], v[156:159], v[220:223], v[22:25]
	v_mfma_f32_16x16x32_bf16 v[18:21], v[192:195], v[220:223], v[18:21]
	v_mfma_f32_16x16x32_bf16 v[6:9], v[156:159], v[238:241], v[6:9]
	v_mfma_f32_16x16x32_bf16 v[2:5], v[192:195], v[238:241], v[2:5]
	v_mfma_f32_16x16x32_bf16 v[54:57], v[162:165], v[208:211], v[54:57]
	v_mfma_f32_16x16x32_bf16 v[50:53], v[200:203], v[208:211], v[50:53]
	v_mfma_f32_16x16x32_bf16 v[38:41], v[162:165], v[216:219], v[38:41]
	v_mfma_f32_16x16x32_bf16 v[34:37], v[200:203], v[216:219], v[34:37]
	v_mfma_f32_16x16x32_bf16 v[22:25], v[162:165], v[224:227], v[22:25]
	v_mfma_f32_16x16x32_bf16 v[18:21], v[200:203], v[224:227], v[18:21]
	v_mfma_f32_16x16x32_bf16 v[6:9], v[162:165], v[242:245], v[6:9]
	v_mfma_f32_16x16x32_bf16 v[2:5], v[200:203], v[242:245], v[2:5]
	s_setprio 0
	s_barrier
	s_add_i32 s92, s92, 2
	s_add_u32 s40, s40, 0x100
	s_addc_u32 s41, s41, 0
	s_add_u32 s90, s90, 0x100
	s_addc_u32 s91, s91, 0
	s_cmp_gt_u32 s92, 13
	s_cbranch_scc0 .LBB0_1011
	s_mov_b32 s100, 1
	s_and_b64 vcc, exec, s[0:1]
	s_cbranch_vccz .LBB0_1014
	s_lshl_b32 s4, s77, 8
	v_add_u32_e32 v162, s4, v188
	v_ashrrev_i32_e32 v163, 31, v162
	v_or_b32_e32 v180, 16, v162
	v_lshlrev_b64 v[132:133], 6, v[162:163]
	v_ashrrev_i32_e32 v181, 31, v180
	v_or_b32_e32 v176, 32, v162
	v_lshl_add_u64 v[132:133], v[154:155], 0, v[132:133]
	v_lshlrev_b64 v[134:135], 6, v[180:181]
	v_ashrrev_i32_e32 v177, 31, v176
	v_lshl_add_u64 v[134:135], v[154:155], 0, v[134:135]
	global_load_dwordx4 v[192:195], v[132:133], off
	global_load_dwordx4 v[200:203], v[134:135], off
	v_lshlrev_b64 v[132:133], 6, v[176:177]
	v_lshl_add_u64 v[132:133], v[154:155], 0, v[132:133]
	global_load_dwordx4 v[204:207], v[132:133], off
	v_or_b32_e32 v170, 48, v162
	v_ashrrev_i32_e32 v171, 31, v170
	v_lshlrev_b64 v[132:133], 6, v[170:171]
	v_lshl_add_u64 v[132:133], v[154:155], 0, v[132:133]
	global_load_dwordx4 v[208:211], v[132:133], off
	v_add_u32_e32 v166, 0x80, v162
	v_ashrrev_i32_e32 v167, 31, v166
	v_lshlrev_b64 v[132:133], 6, v[166:167]
	v_lshl_add_u64 v[132:133], v[154:155], 0, v[132:133]
	global_load_dwordx4 v[212:215], v[132:133], off
	v_add_u32_e32 v164, 0x90, v162
	v_and_b32_e32 v132, 64, v229
	v_ashrrev_i32_e32 v165, 31, v164
	v_add_u32_e32 v136, 64, v132
	v_lshlrev_b64 v[132:133], 6, v[164:165]
	v_lshl_add_u64 v[132:133], v[154:155], 0, v[132:133]
	global_load_dwordx4 v[216:219], v[132:133], off
	v_add_u32_e32 v158, 0xa0, v162
	v_ashrrev_i32_e32 v159, 31, v158
	v_add_u32_e32 v156, 0xb0, v162
	v_lshlrev_b64 v[132:133], 6, v[158:159]
	v_ashrrev_i32_e32 v157, 31, v156
	v_lshl_add_u64 v[132:133], v[154:155], 0, v[132:133]
	global_load_dwordx4 v[220:223], v[132:133], off
	v_lshlrev_b64 v[132:133], 6, v[156:157]
	v_lshl_add_u64 v[132:133], v[154:155], 0, v[132:133]
	global_load_dwordx4 v[224:227], v[132:133], off
	s_addk_i32 s4, 0xc000
	s_lshr_b32 s4, s4, 12
	s_ashr_i32 s5, s77, 5
	s_add_i32 s4, s4, 2
	s_cmp_lt_i32 s77, 64
	s_cselect_b32 s4, s5, s4
	s_ashr_i32 s5, s4, 31
	v_xor_b32_e32 v134, 16, v229
	s_lshl_b64 s[4:5], s[4:5], 14
	v_lshl_or_b32 v238, s79, 8, v190
	v_xor_b32_e32 v135, 32, v229
	v_cmp_lt_i32_e32 vcc, v134, v136
	s_add_u32 s4, s71, s4
	v_ashrrev_i32_e32 v239, 31, v238
	v_cndmask_b32_e32 v134, v229, v134, vcc
	v_cmp_lt_i32_e32 vcc, v135, v136
	s_addc_u32 s5, s74, s5
	v_lshl_add_u64 v[136:137], v[238:239], 2, s[4:5]
	v_cndmask_b32_e32 v135, v229, v135, vcc
	v_lshlrev_b32_e32 v160, 2, v134
	v_lshlrev_b32_e32 v168, 2, v135
	global_load_dwordx4 v[140:143], v[136:137], off offset:16
	global_load_dwordx4 v[144:147], v[136:137], off
	global_load_dwordx4 v[132:135], v[136:137], off offset:528
	s_nop 0
	global_load_dwordx4 v[136:139], v[136:137], off offset:512
	s_barrier
	s_branch .Lmy_g3_afterload

.Lmy_sk9_pk:
	s_waitcnt lgkmcnt(0)
	s_setprio 1
	s_barrier
	v_mfma_f32_16x16x32_bf16 v[144:147], v[112:115], v[164:167], 0
	v_mfma_f32_16x16x32_bf16 v[140:143], v[124:127], v[164:167], 0
	v_mfma_f32_16x16x32_bf16 v[120:123], v[112:115], v[178:181], 0
	v_mfma_f32_16x16x32_bf16 v[108:111], v[124:127], v[178:181], 0
	v_mfma_f32_16x16x32_bf16 v[94:97], v[112:115], v[186:189], 0
	v_mfma_f32_16x16x32_bf16 v[90:93], v[124:127], v[186:189], 0
	v_mfma_f32_16x16x32_bf16 v[78:81], v[112:115], v[200:203], 0
	v_mfma_f32_16x16x32_bf16 v[74:77], v[124:127], v[200:203], 0
	v_mfma_f32_16x16x32_bf16 v[144:147], v[116:119], v[168:171], v[144:147]
	v_mfma_f32_16x16x32_bf16 v[140:143], v[128:131], v[168:171], v[140:143]
	v_mfma_f32_16x16x32_bf16 v[120:123], v[116:119], v[182:185], v[120:123]
	v_mfma_f32_16x16x32_bf16 v[108:111], v[128:131], v[182:185], v[108:111]
	v_mfma_f32_16x16x32_bf16 v[94:97], v[116:119], v[190:193], v[94:97]
	v_mfma_f32_16x16x32_bf16 v[90:93], v[128:131], v[190:193], v[90:93]
	v_mfma_f32_16x16x32_bf16 v[78:81], v[116:119], v[208:211], v[78:81]
	v_mfma_f32_16x16x32_bf16 v[74:77], v[128:131], v[208:211], v[74:77]
	s_setprio 0
	s_setprio 1
	v_mfma_f32_16x16x32_bf16 v[136:139], v[148:151], v[164:167], 0
	v_mfma_f32_16x16x32_bf16 v[132:135], v[156:159], v[164:167], 0
	v_mfma_f32_16x16x32_bf16 v[104:107], v[148:151], v[178:181], 0
	v_mfma_f32_16x16x32_bf16 v[100:103], v[156:159], v[178:181], 0
	v_mfma_f32_16x16x32_bf16 v[86:89], v[148:151], v[186:189], 0
	v_mfma_f32_16x16x32_bf16 v[82:85], v[156:159], v[186:189], 0
	v_mfma_f32_16x16x32_bf16 v[70:73], v[148:151], v[200:203], 0
	v_mfma_f32_16x16x32_bf16 v[66:69], v[156:159], v[200:203], 0
	v_mfma_f32_16x16x32_bf16 v[136:139], v[152:155], v[168:171], v[136:139]
	v_mfma_f32_16x16x32_bf16 v[132:135], v[160:163], v[168:171], v[132:135]
	v_mfma_f32_16x16x32_bf16 v[104:107], v[152:155], v[182:185], v[104:107]
	v_mfma_f32_16x16x32_bf16 v[100:103], v[160:163], v[182:185], v[100:103]
	v_mfma_f32_16x16x32_bf16 v[86:89], v[152:155], v[190:193], v[86:89]
	v_mfma_f32_16x16x32_bf16 v[82:85], v[160:163], v[190:193], v[82:85]
	v_mfma_f32_16x16x32_bf16 v[70:73], v[152:155], v[208:211], v[70:73]
	v_mfma_f32_16x16x32_bf16 v[66:69], v[160:163], v[208:211], v[66:69]
	s_setprio 0
	s_barrier
	s_add_i32 s4, s6, s91
	v_lshl_add_u64 v[194:195], s[78:79], 0, v[172:173]
	s_mov_b32 m0, s4
	ds_read_b128 v[164:167], v207 offset:16384
	ds_read_b128 v[168:171], v207 offset:17408
	ds_read_b128 v[178:181], v207 offset:18432
	ds_read_b128 v[182:185], v207 offset:19456
	ds_read_b128 v[186:189], v207 offset:20480
	ds_read_b128 v[190:193], v207 offset:21504
	ds_read_b128 v[200:203], v207 offset:22528
	ds_read_b128 v[208:211], v207 offset:23552
	global_load_lds_dwordx4 v[194:195], off
	s_add_i32 m0, s4, 0x2000
	s_add_u32 s4, s78, 0x100000
	v_lshl_add_u64 v[212:213], s[78:79], 0, v[176:177]
	s_addc_u32 s5, s79, 0
	s_add_i32 s6, s7, s91
	global_load_lds_dwordx4 v[212:213], off
	v_lshl_add_u64 v[214:215], s[4:5], 0, v[172:173]
	s_mov_b32 m0, s6
	v_lshl_add_u64 v[216:217], vcc, 0, v[174:175]
	global_load_lds_dwordx4 v[214:215], off
	v_lshl_add_u64 v[214:215], s[4:5], 0, v[176:177]
	s_add_i32 m0, s6, 0x2000
	s_nop 0
	global_load_lds_dwordx4 v[214:215], off
	v_lshl_add_u64 v[214:215], vcc, 0, v[98:99]
	s_mov_b32 m0, s44
	s_nop 0
	global_load_lds_dwordx4 v[214:215], off
	s_add_i32 m0, s44, 0x2000
	s_nop 0
	global_load_lds_dwordx4 v[216:217], off
	s_nop 0
	s_cmp_eq_u32 s100, 1
	s_cbranch_scc1 .Lmy_sk10_pk
	s_waitcnt vmcnt(8)
.Lmy_sk10_pk:
	s_waitcnt lgkmcnt(0)
	s_setprio 1
	s_barrier
	v_mfma_f32_16x16x32_bf16 v[62:65], v[112:115], v[164:167], 0
	v_mfma_f32_16x16x32_bf16 v[58:61], v[124:127], v[164:167], 0
	v_mfma_f32_16x16x32_bf16 v[46:49], v[112:115], v[178:181], 0
	v_mfma_f32_16x16x32_bf16 v[42:45], v[124:127], v[178:181], 0
	v_mfma_f32_16x16x32_bf16 v[30:33], v[112:115], v[186:189], 0
	v_mfma_f32_16x16x32_bf16 v[26:29], v[124:127], v[186:189], 0
	v_mfma_f32_16x16x32_bf16 v[14:17], v[112:115], v[200:203], 0
	v_mfma_f32_16x16x32_bf16 v[10:13], v[124:127], v[200:203], 0
	v_mfma_f32_16x16x32_bf16 v[62:65], v[116:119], v[168:171], v[62:65]
	v_mfma_f32_16x16x32_bf16 v[58:61], v[128:131], v[168:171], v[58:61]
	v_mfma_f32_16x16x32_bf16 v[46:49], v[116:119], v[182:185], v[46:49]
	v_mfma_f32_16x16x32_bf16 v[42:45], v[128:131], v[182:185], v[42:45]
	v_mfma_f32_16x16x32_bf16 v[30:33], v[116:119], v[190:193], v[30:33]
	v_mfma_f32_16x16x32_bf16 v[26:29], v[128:131], v[190:193], v[26:29]
	v_mfma_f32_16x16x32_bf16 v[14:17], v[116:119], v[208:211], v[14:17]
	v_mfma_f32_16x16x32_bf16 v[10:13], v[128:131], v[208:211], v[10:13]
	s_setprio 0
	s_setprio 1
	v_mfma_f32_16x16x32_bf16 v[54:57], v[148:151], v[164:167], 0
	v_mfma_f32_16x16x32_bf16 v[50:53], v[156:159], v[164:167], 0
	v_mfma_f32_16x16x32_bf16 v[38:41], v[148:151], v[178:181], 0
	v_mfma_f32_16x16x32_bf16 v[34:37], v[156:159], v[178:181], 0
	v_mfma_f32_16x16x32_bf16 v[22:25], v[148:151], v[186:189], 0
	v_mfma_f32_16x16x32_bf16 v[18:21], v[156:159], v[186:189], 0
	v_mfma_f32_16x16x32_bf16 v[6:9], v[148:151], v[200:203], 0
	v_mfma_f32_16x16x32_bf16 v[2:5], v[156:159], v[200:203], 0
	v_mfma_f32_16x16x32_bf16 v[54:57], v[152:155], v[168:171], v[54:57]
	v_mfma_f32_16x16x32_bf16 v[50:53], v[160:163], v[168:171], v[50:53]
	v_mfma_f32_16x16x32_bf16 v[38:41], v[152:155], v[182:185], v[38:41]
	v_mfma_f32_16x16x32_bf16 v[34:37], v[160:163], v[182:185], v[34:37]
	v_mfma_f32_16x16x32_bf16 v[22:25], v[152:155], v[190:193], v[22:25]
	v_mfma_f32_16x16x32_bf16 v[18:21], v[160:163], v[190:193], v[18:21]
	v_mfma_f32_16x16x32_bf16 v[6:9], v[152:155], v[208:211], v[6:9]
	v_mfma_f32_16x16x32_bf16 v[2:5], v[160:163], v[208:211], v[2:5]
	s_setprio 0
	s_barrier
	s_add_i32 s6, 0, 0x18000
	s_add_i32 s7, 0, 0x1c000
	v_add_u32_e32 v128, s6, v205
	v_add_u32_e32 v160, s7, v205
	ds_read_b128 v[112:115], v128
	ds_read_b128 v[116:119], v128 offset:1024
	ds_read_b128 v[124:127], v128 offset:2048
	ds_read_b128 v[128:131], v128 offset:3072
	ds_read_b128 v[148:151], v160
	ds_read_b128 v[152:155], v160 offset:1024
	ds_read_b128 v[156:159], v160 offset:2048
	ds_read_b128 v[160:163], v160 offset:3072
	s_add_u32 s4, vcc_lo, 0x100000
	s_addc_u32 s5, vcc_hi, 0
	v_lshl_add_u64 v[218:219], s[4:5], 0, v[98:99]
	s_add_i32 m0, s44, 0x4000
	ds_read_b128 v[164:167], v207 offset:32768
	ds_read_b128 v[168:171], v207 offset:33792
	ds_read_b128 v[178:181], v207 offset:34816
	ds_read_b128 v[182:185], v207 offset:35840
	ds_read_b128 v[186:189], v207 offset:36864
	ds_read_b128 v[190:193], v207 offset:37888
	ds_read_b128 v[200:203], v207 offset:38912
	ds_read_b128 v[208:211], v207 offset:39936
	global_load_lds_dwordx4 v[218:219], off
	v_lshl_add_u64 v[218:219], s[4:5], 0, v[174:175]
	s_add_i32 m0, s44, 0x6000
	s_nop 0
	global_load_lds_dwordx4 v[218:219], off
	s_waitcnt vmcnt(8)
	s_waitcnt lgkmcnt(0)
	s_setprio 1
	s_barrier
	v_mfma_f32_16x16x32_bf16 v[144:147], v[112:115], v[164:167], v[144:147]
	v_mfma_f32_16x16x32_bf16 v[140:143], v[124:127], v[164:167], v[140:143]
	v_mfma_f32_16x16x32_bf16 v[120:123], v[112:115], v[178:181], v[120:123]
	v_mfma_f32_16x16x32_bf16 v[108:111], v[124:127], v[178:181], v[108:111]
	v_mfma_f32_16x16x32_bf16 v[94:97], v[112:115], v[186:189], v[94:97]
	v_mfma_f32_16x16x32_bf16 v[90:93], v[124:127], v[186:189], v[90:93]
	v_mfma_f32_16x16x32_bf16 v[78:81], v[112:115], v[200:203], v[78:81]
	v_mfma_f32_16x16x32_bf16 v[74:77], v[124:127], v[200:203], v[74:77]
	v_mfma_f32_16x16x32_bf16 v[144:147], v[116:119], v[168:171], v[144:147]
	v_mfma_f32_16x16x32_bf16 v[140:143], v[128:131], v[168:171], v[140:143]
	v_mfma_f32_16x16x32_bf16 v[120:123], v[116:119], v[182:185], v[120:123]
	v_mfma_f32_16x16x32_bf16 v[108:111], v[128:131], v[182:185], v[108:111]
	v_mfma_f32_16x16x32_bf16 v[94:97], v[116:119], v[190:193], v[94:97]
	v_mfma_f32_16x16x32_bf16 v[90:93], v[128:131], v[190:193], v[90:93]
	v_mfma_f32_16x16x32_bf16 v[78:81], v[116:119], v[208:211], v[78:81]
	v_mfma_f32_16x16x32_bf16 v[74:77], v[128:131], v[208:211], v[74:77]
	s_setprio 0
	s_setprio 1
	v_mfma_f32_16x16x32_bf16 v[136:139], v[148:151], v[164:167], v[136:139]
	v_mfma_f32_16x16x32_bf16 v[132:135], v[156:159], v[164:167], v[132:135]
	v_mfma_f32_16x16x32_bf16 v[104:107], v[148:151], v[178:181], v[104:107]
	v_mfma_f32_16x16x32_bf16 v[100:103], v[156:159], v[178:181], v[100:103]
	v_mfma_f32_16x16x32_bf16 v[86:89], v[148:151], v[186:189], v[86:89]
	v_mfma_f32_16x16x32_bf16 v[82:85], v[156:159], v[186:189], v[82:85]
	v_mfma_f32_16x16x32_bf16 v[70:73], v[148:151], v[200:203], v[70:73]
	v_mfma_f32_16x16x32_bf16 v[66:69], v[156:159], v[200:203], v[66:69]
	v_mfma_f32_16x16x32_bf16 v[136:139], v[152:155], v[168:171], v[136:139]
	v_mfma_f32_16x16x32_bf16 v[132:135], v[160:163], v[168:171], v[132:135]
	v_mfma_f32_16x16x32_bf16 v[104:107], v[152:155], v[182:185], v[104:107]
	v_mfma_f32_16x16x32_bf16 v[100:103], v[160:163], v[182:185], v[100:103]
	v_mfma_f32_16x16x32_bf16 v[86:89], v[152:155], v[190:193], v[86:89]
	v_mfma_f32_16x16x32_bf16 v[82:85], v[160:163], v[190:193], v[82:85]
	v_mfma_f32_16x16x32_bf16 v[70:73], v[152:155], v[208:211], v[70:73]
	v_mfma_f32_16x16x32_bf16 v[66:69], v[160:163], v[208:211], v[66:69]
	s_setprio 0
	s_barrier
	s_add_i32 s4, s6, s91
	v_lshl_add_u64 v[194:195], v[194:195], 0, s[42:43]
	s_mov_b32 m0, s4
	ds_read_b128 v[164:167], v207 offset:49152
	ds_read_b128 v[168:171], v207 offset:50176
	ds_read_b128 v[178:181], v207 offset:51200
	ds_read_b128 v[182:185], v207 offset:52224
	ds_read_b128 v[186:189], v207 offset:53248
	ds_read_b128 v[190:193], v207 offset:54272
	ds_read_b128 v[200:203], v207 offset:55296
	ds_read_b128 v[208:211], v207 offset:56320
	global_load_lds_dwordx4 v[194:195], off
	s_add_i32 m0, s4, 0x2000
	s_add_u32 s4, s78, 0x100080
	v_lshl_add_u64 v[194:195], v[212:213], 0, s[42:43]
	s_addc_u32 s5, s79, 0
	s_add_i32 s6, s7, s91
	global_load_lds_dwordx4 v[194:195], off
	v_lshl_add_u64 v[194:195], s[4:5], 0, v[172:173]
	s_mov_b32 m0, s6
	s_nop 0
	global_load_lds_dwordx4 v[194:195], off
	v_lshl_add_u64 v[194:195], s[4:5], 0, v[176:177]
	s_add_i32 m0, s6, 0x2000
	s_nop 0
	global_load_lds_dwordx4 v[194:195], off
	v_lshl_add_u64 v[194:195], v[214:215], 0, s[42:43]
	s_add_i32 m0, s44, 0x8000
	s_nop 0
	global_load_lds_dwordx4 v[194:195], off
	v_lshl_add_u64 v[194:195], v[216:217], 0, s[42:43]
	s_add_i32 m0, s44, 0xa000
	s_nop 0
	global_load_lds_dwordx4 v[194:195], off
	s_nop 0
	s_waitcnt vmcnt(8)
	s_waitcnt lgkmcnt(0)
	s_setprio 1
	s_barrier
	v_mfma_f32_16x16x32_bf16 v[62:65], v[112:115], v[164:167], v[62:65]
	v_mfma_f32_16x16x32_bf16 v[58:61], v[124:127], v[164:167], v[58:61]
	v_mfma_f32_16x16x32_bf16 v[46:49], v[112:115], v[178:181], v[46:49]
	v_mfma_f32_16x16x32_bf16 v[42:45], v[124:127], v[178:181], v[42:45]
	v_mfma_f32_16x16x32_bf16 v[30:33], v[112:115], v[186:189], v[30:33]
	v_mfma_f32_16x16x32_bf16 v[26:29], v[124:127], v[186:189], v[26:29]
	v_mfma_f32_16x16x32_bf16 v[14:17], v[112:115], v[200:203], v[14:17]
	v_mfma_f32_16x16x32_bf16 v[10:13], v[124:127], v[200:203], v[10:13]
	v_mfma_f32_16x16x32_bf16 v[62:65], v[116:119], v[168:171], v[62:65]
	v_mfma_f32_16x16x32_bf16 v[58:61], v[128:131], v[168:171], v[58:61]
	v_mfma_f32_16x16x32_bf16 v[46:49], v[116:119], v[182:185], v[46:49]
	v_mfma_f32_16x16x32_bf16 v[42:45], v[128:131], v[182:185], v[42:45]
	v_mfma_f32_16x16x32_bf16 v[30:33], v[116:119], v[190:193], v[30:33]
	v_mfma_f32_16x16x32_bf16 v[26:29], v[128:131], v[190:193], v[26:29]
	v_mfma_f32_16x16x32_bf16 v[14:17], v[116:119], v[208:211], v[14:17]
	v_mfma_f32_16x16x32_bf16 v[10:13], v[128:131], v[208:211], v[10:13]
	s_setprio 0
	s_setprio 1
	v_mfma_f32_16x16x32_bf16 v[54:57], v[148:151], v[164:167], v[54:57]
	v_mfma_f32_16x16x32_bf16 v[50:53], v[156:159], v[164:167], v[50:53]
	v_mfma_f32_16x16x32_bf16 v[38:41], v[148:151], v[178:181], v[38:41]
	v_mfma_f32_16x16x32_bf16 v[34:37], v[156:159], v[178:181], v[34:37]
	v_mfma_f32_16x16x32_bf16 v[22:25], v[148:151], v[186:189], v[22:25]
	v_mfma_f32_16x16x32_bf16 v[18:21], v[156:159], v[186:189], v[18:21]
	v_mfma_f32_16x16x32_bf16 v[6:9], v[148:151], v[200:203], v[6:9]
	v_mfma_f32_16x16x32_bf16 v[2:5], v[156:159], v[200:203], v[2:5]
	v_mfma_f32_16x16x32_bf16 v[54:57], v[152:155], v[168:171], v[54:57]
	v_mfma_f32_16x16x32_bf16 v[50:53], v[160:163], v[168:171], v[50:53]
	v_mfma_f32_16x16x32_bf16 v[38:41], v[152:155], v[182:185], v[38:41]
	v_mfma_f32_16x16x32_bf16 v[34:37], v[160:163], v[182:185], v[34:37]
	v_mfma_f32_16x16x32_bf16 v[22:25], v[152:155], v[190:193], v[22:25]
	v_mfma_f32_16x16x32_bf16 v[18:21], v[160:163], v[190:193], v[18:21]
	v_mfma_f32_16x16x32_bf16 v[6:9], v[152:155], v[208:211], v[6:9]
	v_mfma_f32_16x16x32_bf16 v[2:5], v[160:163], v[208:211], v[2:5]
	s_setprio 0
	s_barrier
	s_mov_b32 s100, 0
	s_add_i32 s95, s95, 2
	s_add_u32 s74, s74, 0x100
	s_addc_u32 s75, s75, 0
	s_add_u32 s71, s71, 0x100
	s_addc_u32 s94, s94, 0
	s_cmp_gt_u32 s95, 61
.LBB0_1116:
	s_add_u32 s4, s74, 0xfff00080
	s_addc_u32 s5, s75, -1
	s_add_i32 s6, 0, 0x10000
	s_cmp_eq_u32 s95, 60
	s_cselect_b32 vcc_hi, s18, s5
	s_cselect_b32 vcc_lo, s21, s4
	s_cselect_b32 s79, s27, s94
	s_cselect_b32 s78, s69, s71
	s_add_i32 s7, 0, 0x14000
	v_add_u32_e32 v128, s6, v205
	v_add_u32_e32 v160, s7, v205
	ds_read_b128 v[112:115], v128
	ds_read_b128 v[116:119], v128 offset:1024
	ds_read_b128 v[124:127], v128 offset:2048
	ds_read_b128 v[128:131], v128 offset:3072
	ds_read_b128 v[148:151], v160
	ds_read_b128 v[152:155], v160 offset:1024
	ds_read_b128 v[156:159], v160 offset:2048
	ds_read_b128 v[160:163], v160 offset:3072
	s_add_i32 s44, s91, 0
	v_lshl_add_u64 v[194:195], s[74:75], 0, v[98:99]
	s_add_i32 m0, s44, 0xc000
	ds_read_b128 v[164:167], v207
	ds_read_b128 v[168:171], v207 offset:1024
	ds_read_b128 v[178:181], v207 offset:2048
	ds_read_b128 v[182:185], v207 offset:3072
	ds_read_b128 v[186:189], v207 offset:4096
	ds_read_b128 v[190:193], v207 offset:5120
	ds_read_b128 v[200:203], v207 offset:6144
	ds_read_b128 v[208:211], v207 offset:7168
	global_load_lds_dwordx4 v[194:195], off
	v_lshl_add_u64 v[194:195], s[74:75], 0, v[174:175]
	s_add_i32 m0, s44, 0xe000
	s_nop 0
	global_load_lds_dwordx4 v[194:195], off
	s_nop 0
	s_waitcnt vmcnt(8)
	s_waitcnt lgkmcnt(0)
	s_setprio 1
	s_barrier
	v_mfma_f32_16x16x32_bf16 v[144:147], v[112:115], v[164:167], v[144:147]
	v_mfma_f32_16x16x32_bf16 v[140:143], v[124:127], v[164:167], v[140:143]
	v_mfma_f32_16x16x32_bf16 v[120:123], v[112:115], v[178:181], v[120:123]
	v_mfma_f32_16x16x32_bf16 v[108:111], v[124:127], v[178:181], v[108:111]
	v_mfma_f32_16x16x32_bf16 v[94:97], v[112:115], v[186:189], v[94:97]
	v_mfma_f32_16x16x32_bf16 v[90:93], v[124:127], v[186:189], v[90:93]
	v_mfma_f32_16x16x32_bf16 v[78:81], v[112:115], v[200:203], v[78:81]
	v_mfma_f32_16x16x32_bf16 v[74:77], v[124:127], v[200:203], v[74:77]
	v_mfma_f32_16x16x32_bf16 v[144:147], v[116:119], v[168:171], v[144:147]
	v_mfma_f32_16x16x32_bf16 v[140:143], v[128:131], v[168:171], v[140:143]
	v_mfma_f32_16x16x32_bf16 v[120:123], v[116:119], v[182:185], v[120:123]
	v_mfma_f32_16x16x32_bf16 v[108:111], v[128:131], v[182:185], v[108:111]
	v_mfma_f32_16x16x32_bf16 v[94:97], v[116:119], v[190:193], v[94:97]
	v_mfma_f32_16x16x32_bf16 v[90:93], v[128:131], v[190:193], v[90:93]
	v_mfma_f32_16x16x32_bf16 v[78:81], v[116:119], v[208:211], v[78:81]
	v_mfma_f32_16x16x32_bf16 v[74:77], v[128:131], v[208:211], v[74:77]
	s_setprio 0
	s_setprio 1
	v_mfma_f32_16x16x32_bf16 v[136:139], v[148:151], v[164:167], v[136:139]
	v_mfma_f32_16x16x32_bf16 v[132:135], v[156:159], v[164:167], v[132:135]
	v_mfma_f32_16x16x32_bf16 v[104:107], v[148:151], v[178:181], v[104:107]
	v_mfma_f32_16x16x32_bf16 v[100:103], v[156:159], v[178:181], v[100:103]
	v_mfma_f32_16x16x32_bf16 v[86:89], v[148:151], v[186:189], v[86:89]
	v_mfma_f32_16x16x32_bf16 v[82:85], v[156:159], v[186:189], v[82:85]
	v_mfma_f32_16x16x32_bf16 v[70:73], v[148:151], v[200:203], v[70:73]
	v_mfma_f32_16x16x32_bf16 v[66:69], v[156:159], v[200:203], v[66:69]
	v_mfma_f32_16x16x32_bf16 v[136:139], v[152:155], v[168:171], v[136:139]
	v_mfma_f32_16x16x32_bf16 v[132:135], v[160:163], v[168:171], v[132:135]
	v_mfma_f32_16x16x32_bf16 v[104:107], v[152:155], v[182:185], v[104:107]
	v_mfma_f32_16x16x32_bf16 v[100:103], v[160:163], v[182:185], v[100:103]
	v_mfma_f32_16x16x32_bf16 v[86:89], v[152:155], v[190:193], v[86:89]
	v_mfma_f32_16x16x32_bf16 v[82:85], v[160:163], v[190:193], v[82:85]
	v_mfma_f32_16x16x32_bf16 v[70:73], v[152:155], v[208:211], v[70:73]
	v_mfma_f32_16x16x32_bf16 v[66:69], v[160:163], v[208:211], v[66:69]
	s_setprio 0
	s_barrier
	s_add_i32 s4, s6, s91
	v_lshl_add_u64 v[194:195], s[78:79], 0, v[172:173]
	s_mov_b32 m0, s4
	ds_read_b128 v[164:167], v207 offset:16384
	ds_read_b128 v[168:171], v207 offset:17408
	ds_read_b128 v[178:181], v207 offset:18432
	ds_read_b128 v[182:185], v207 offset:19456
	ds_read_b128 v[186:189], v207 offset:20480
	ds_read_b128 v[190:193], v207 offset:21504
	ds_read_b128 v[200:203], v207 offset:22528
	ds_read_b128 v[208:211], v207 offset:23552
	global_load_lds_dwordx4 v[194:195], off
	s_add_i32 m0, s4, 0x2000
	s_add_u32 s4, s78, 0x100000
	v_lshl_add_u64 v[212:213], s[78:79], 0, v[176:177]
	s_addc_u32 s5, s79, 0
	s_add_i32 s6, s7, s91
	global_load_lds_dwordx4 v[212:213], off
	v_lshl_add_u64 v[214:215], s[4:5], 0, v[172:173]
	s_mov_b32 m0, s6
	v_lshl_add_u64 v[216:217], vcc, 0, v[174:175]
	global_load_lds_dwordx4 v[214:215], off
	v_lshl_add_u64 v[214:215], s[4:5], 0, v[176:177]
	s_add_i32 m0, s6, 0x2000
	s_nop 0
	global_load_lds_dwordx4 v[214:215], off
	v_lshl_add_u64 v[214:215], vcc, 0, v[98:99]
	s_mov_b32 m0, s44
	s_nop 0
	global_load_lds_dwordx4 v[214:215], off
	s_add_i32 m0, s44, 0x2000
	s_nop 0
	global_load_lds_dwordx4 v[216:217], off
	s_nop 0
	s_waitcnt vmcnt(8)
	s_waitcnt lgkmcnt(0)
	s_setprio 1
	s_barrier
	v_mfma_f32_16x16x32_bf16 v[62:65], v[112:115], v[164:167], v[62:65]
	v_mfma_f32_16x16x32_bf16 v[58:61], v[124:127], v[164:167], v[58:61]
	v_mfma_f32_16x16x32_bf16 v[46:49], v[112:115], v[178:181], v[46:49]
	v_mfma_f32_16x16x32_bf16 v[42:45], v[124:127], v[178:181], v[42:45]
	v_mfma_f32_16x16x32_bf16 v[30:33], v[112:115], v[186:189], v[30:33]
	v_mfma_f32_16x16x32_bf16 v[26:29], v[124:127], v[186:189], v[26:29]
	v_mfma_f32_16x16x32_bf16 v[14:17], v[112:115], v[200:203], v[14:17]
	v_mfma_f32_16x16x32_bf16 v[10:13], v[124:127], v[200:203], v[10:13]
	v_mfma_f32_16x16x32_bf16 v[62:65], v[116:119], v[168:171], v[62:65]
	v_mfma_f32_16x16x32_bf16 v[58:61], v[128:131], v[168:171], v[58:61]
	v_mfma_f32_16x16x32_bf16 v[46:49], v[116:119], v[182:185], v[46:49]
	v_mfma_f32_16x16x32_bf16 v[42:45], v[128:131], v[182:185], v[42:45]
	v_mfma_f32_16x16x32_bf16 v[30:33], v[116:119], v[190:193], v[30:33]
	v_mfma_f32_16x16x32_bf16 v[26:29], v[128:131], v[190:193], v[26:29]
	v_mfma_f32_16x16x32_bf16 v[14:17], v[116:119], v[208:211], v[14:17]
	v_mfma_f32_16x16x32_bf16 v[10:13], v[128:131], v[208:211], v[10:13]
	s_setprio 0
	s_setprio 1
	v_mfma_f32_16x16x32_bf16 v[54:57], v[148:151], v[164:167], v[54:57]
	v_mfma_f32_16x16x32_bf16 v[50:53], v[156:159], v[164:167], v[50:53]
	v_mfma_f32_16x16x32_bf16 v[38:41], v[148:151], v[178:181], v[38:41]
	v_mfma_f32_16x16x32_bf16 v[34:37], v[156:159], v[178:181], v[34:37]
	v_mfma_f32_16x16x32_bf16 v[22:25], v[148:151], v[186:189], v[22:25]
	v_mfma_f32_16x16x32_bf16 v[18:21], v[156:159], v[186:189], v[18:21]
	v_mfma_f32_16x16x32_bf16 v[6:9], v[148:151], v[200:203], v[6:9]
	v_mfma_f32_16x16x32_bf16 v[2:5], v[156:159], v[200:203], v[2:5]
	v_mfma_f32_16x16x32_bf16 v[54:57], v[152:155], v[168:171], v[54:57]
	v_mfma_f32_16x16x32_bf16 v[50:53], v[160:163], v[168:171], v[50:53]
	v_mfma_f32_16x16x32_bf16 v[38:41], v[152:155], v[182:185], v[38:41]
	v_mfma_f32_16x16x32_bf16 v[34:37], v[160:163], v[182:185], v[34:37]
	v_mfma_f32_16x16x32_bf16 v[22:25], v[152:155], v[190:193], v[22:25]
	v_mfma_f32_16x16x32_bf16 v[18:21], v[160:163], v[190:193], v[18:21]
	v_mfma_f32_16x16x32_bf16 v[6:9], v[152:155], v[208:211], v[6:9]
	v_mfma_f32_16x16x32_bf16 v[2:5], v[160:163], v[208:211], v[2:5]
	s_setprio 0
	s_barrier
	s_add_i32 s6, 0, 0x18000
	s_add_i32 s7, 0, 0x1c000
	v_add_u32_e32 v128, s6, v205
	v_add_u32_e32 v160, s7, v205
	ds_read_b128 v[112:115], v128
	ds_read_b128 v[116:119], v128 offset:1024
	ds_read_b128 v[124:127], v128 offset:2048
	ds_read_b128 v[128:131], v128 offset:3072
	ds_read_b128 v[148:151], v160
	ds_read_b128 v[152:155], v160 offset:1024
	ds_read_b128 v[156:159], v160 offset:2048
	ds_read_b128 v[160:163], v160 offset:3072
	s_add_u32 s4, vcc_lo, 0x100000
	s_addc_u32 s5, vcc_hi, 0
	v_lshl_add_u64 v[218:219], s[4:5], 0, v[98:99]
	s_add_i32 m0, s44, 0x4000
	ds_read_b128 v[164:167], v207 offset:32768
	ds_read_b128 v[168:171], v207 offset:33792
	ds_read_b128 v[178:181], v207 offset:34816
	ds_read_b128 v[182:185], v207 offset:35840
	ds_read_b128 v[186:189], v207 offset:36864
	ds_read_b128 v[190:193], v207 offset:37888
	ds_read_b128 v[200:203], v207 offset:38912
	ds_read_b128 v[208:211], v207 offset:39936
	global_load_lds_dwordx4 v[218:219], off
	v_lshl_add_u64 v[218:219], s[4:5], 0, v[174:175]
	s_add_i32 m0, s44, 0x6000
	s_nop 0
	global_load_lds_dwordx4 v[218:219], off
	s_waitcnt vmcnt(8)
	s_waitcnt lgkmcnt(0)
	s_setprio 1
	s_barrier
	v_mfma_f32_16x16x32_bf16 v[144:147], v[112:115], v[164:167], v[144:147]
	v_mfma_f32_16x16x32_bf16 v[140:143], v[124:127], v[164:167], v[140:143]
	v_mfma_f32_16x16x32_bf16 v[120:123], v[112:115], v[178:181], v[120:123]
	v_mfma_f32_16x16x32_bf16 v[108:111], v[124:127], v[178:181], v[108:111]
	v_mfma_f32_16x16x32_bf16 v[94:97], v[112:115], v[186:189], v[94:97]
	v_mfma_f32_16x16x32_bf16 v[90:93], v[124:127], v[186:189], v[90:93]
	v_mfma_f32_16x16x32_bf16 v[78:81], v[112:115], v[200:203], v[78:81]
	v_mfma_f32_16x16x32_bf16 v[74:77], v[124:127], v[200:203], v[74:77]
	v_mfma_f32_16x16x32_bf16 v[144:147], v[116:119], v[168:171], v[144:147]
	v_mfma_f32_16x16x32_bf16 v[140:143], v[128:131], v[168:171], v[140:143]
	v_mfma_f32_16x16x32_bf16 v[120:123], v[116:119], v[182:185], v[120:123]
	v_mfma_f32_16x16x32_bf16 v[108:111], v[128:131], v[182:185], v[108:111]
	v_mfma_f32_16x16x32_bf16 v[94:97], v[116:119], v[190:193], v[94:97]
	v_mfma_f32_16x16x32_bf16 v[90:93], v[128:131], v[190:193], v[90:93]
	v_mfma_f32_16x16x32_bf16 v[78:81], v[116:119], v[208:211], v[78:81]
	v_mfma_f32_16x16x32_bf16 v[74:77], v[128:131], v[208:211], v[74:77]
	s_setprio 0
	s_setprio 1
	v_mfma_f32_16x16x32_bf16 v[136:139], v[148:151], v[164:167], v[136:139]
	v_mfma_f32_16x16x32_bf16 v[132:135], v[156:159], v[164:167], v[132:135]
	v_mfma_f32_16x16x32_bf16 v[104:107], v[148:151], v[178:181], v[104:107]
	v_mfma_f32_16x16x32_bf16 v[100:103], v[156:159], v[178:181], v[100:103]
	v_mfma_f32_16x16x32_bf16 v[86:89], v[148:151], v[186:189], v[86:89]
	v_mfma_f32_16x16x32_bf16 v[82:85], v[156:159], v[186:189], v[82:85]
	v_mfma_f32_16x16x32_bf16 v[70:73], v[148:151], v[200:203], v[70:73]
	v_mfma_f32_16x16x32_bf16 v[66:69], v[156:159], v[200:203], v[66:69]
	v_mfma_f32_16x16x32_bf16 v[136:139], v[152:155], v[168:171], v[136:139]
	v_mfma_f32_16x16x32_bf16 v[132:135], v[160:163], v[168:171], v[132:135]
	v_mfma_f32_16x16x32_bf16 v[104:107], v[152:155], v[182:185], v[104:107]
	v_mfma_f32_16x16x32_bf16 v[100:103], v[160:163], v[182:185], v[100:103]
	v_mfma_f32_16x16x32_bf16 v[86:89], v[152:155], v[190:193], v[86:89]
	v_mfma_f32_16x16x32_bf16 v[82:85], v[160:163], v[190:193], v[82:85]
	v_mfma_f32_16x16x32_bf16 v[70:73], v[152:155], v[208:211], v[70:73]
	v_mfma_f32_16x16x32_bf16 v[66:69], v[160:163], v[208:211], v[66:69]
	s_setprio 0
	s_barrier
	s_add_i32 s4, s6, s91
	v_lshl_add_u64 v[194:195], v[194:195], 0, s[42:43]
	s_mov_b32 m0, s4
	ds_read_b128 v[164:167], v207 offset:49152
	ds_read_b128 v[168:171], v207 offset:50176
	ds_read_b128 v[178:181], v207 offset:51200
	ds_read_b128 v[182:185], v207 offset:52224
	ds_read_b128 v[186:189], v207 offset:53248
	ds_read_b128 v[190:193], v207 offset:54272
	ds_read_b128 v[200:203], v207 offset:55296
	ds_read_b128 v[208:211], v207 offset:56320
	global_load_lds_dwordx4 v[194:195], off
	s_add_i32 m0, s4, 0x2000
	s_add_u32 s4, s78, 0x100080
	v_lshl_add_u64 v[194:195], v[212:213], 0, s[42:43]
	s_addc_u32 s5, s79, 0
	s_add_i32 s6, s7, s91
	global_load_lds_dwordx4 v[194:195], off
	v_lshl_add_u64 v[194:195], s[4:5], 0, v[172:173]
	s_mov_b32 m0, s6
	s_nop 0
	global_load_lds_dwordx4 v[194:195], off
	v_lshl_add_u64 v[194:195], s[4:5], 0, v[176:177]
	s_add_i32 m0, s6, 0x2000
	s_nop 0
	global_load_lds_dwordx4 v[194:195], off
	v_lshl_add_u64 v[194:195], v[214:215], 0, s[42:43]
	s_add_i32 m0, s44, 0x8000
	s_nop 0
	global_load_lds_dwordx4 v[194:195], off
	v_lshl_add_u64 v[194:195], v[216:217], 0, s[42:43]
	s_add_i32 m0, s44, 0xa000
	s_nop 0
	global_load_lds_dwordx4 v[194:195], off
	s_nop 0
	s_waitcnt vmcnt(8)
	s_waitcnt lgkmcnt(0)
	s_setprio 1
	s_barrier
	v_mfma_f32_16x16x32_bf16 v[62:65], v[112:115], v[164:167], v[62:65]
	v_mfma_f32_16x16x32_bf16 v[58:61], v[124:127], v[164:167], v[58:61]
	v_mfma_f32_16x16x32_bf16 v[46:49], v[112:115], v[178:181], v[46:49]
	v_mfma_f32_16x16x32_bf16 v[42:45], v[124:127], v[178:181], v[42:45]
	v_mfma_f32_16x16x32_bf16 v[30:33], v[112:115], v[186:189], v[30:33]
	v_mfma_f32_16x16x32_bf16 v[26:29], v[124:127], v[186:189], v[26:29]
	v_mfma_f32_16x16x32_bf16 v[14:17], v[112:115], v[200:203], v[14:17]
	v_mfma_f32_16x16x32_bf16 v[10:13], v[124:127], v[200:203], v[10:13]
	v_mfma_f32_16x16x32_bf16 v[62:65], v[116:119], v[168:171], v[62:65]
	v_mfma_f32_16x16x32_bf16 v[58:61], v[128:131], v[168:171], v[58:61]
	v_mfma_f32_16x16x32_bf16 v[46:49], v[116:119], v[182:185], v[46:49]
	v_mfma_f32_16x16x32_bf16 v[42:45], v[128:131], v[182:185], v[42:45]
	v_mfma_f32_16x16x32_bf16 v[30:33], v[116:119], v[190:193], v[30:33]
	v_mfma_f32_16x16x32_bf16 v[26:29], v[128:131], v[190:193], v[26:29]
	v_mfma_f32_16x16x32_bf16 v[14:17], v[116:119], v[208:211], v[14:17]
	v_mfma_f32_16x16x32_bf16 v[10:13], v[128:131], v[208:211], v[10:13]
	s_setprio 0
	s_setprio 1
	v_mfma_f32_16x16x32_bf16 v[54:57], v[148:151], v[164:167], v[54:57]
	v_mfma_f32_16x16x32_bf16 v[50:53], v[156:159], v[164:167], v[50:53]
	v_mfma_f32_16x16x32_bf16 v[38:41], v[148:151], v[178:181], v[38:41]
	v_mfma_f32_16x16x32_bf16 v[34:37], v[156:159], v[178:181], v[34:37]
	v_mfma_f32_16x16x32_bf16 v[22:25], v[148:151], v[186:189], v[22:25]
	v_mfma_f32_16x16x32_bf16 v[18:21], v[156:159], v[186:189], v[18:21]
	v_mfma_f32_16x16x32_bf16 v[6:9], v[148:151], v[200:203], v[6:9]
	v_mfma_f32_16x16x32_bf16 v[2:5], v[156:159], v[200:203], v[2:5]
	v_mfma_f32_16x16x32_bf16 v[54:57], v[152:155], v[168:171], v[54:57]
	v_mfma_f32_16x16x32_bf16 v[50:53], v[160:163], v[168:171], v[50:53]
	v_mfma_f32_16x16x32_bf16 v[38:41], v[152:155], v[182:185], v[38:41]
	v_mfma_f32_16x16x32_bf16 v[34:37], v[160:163], v[182:185], v[34:37]
	v_mfma_f32_16x16x32_bf16 v[22:25], v[152:155], v[190:193], v[22:25]
	v_mfma_f32_16x16x32_bf16 v[18:21], v[160:163], v[190:193], v[18:21]
	v_mfma_f32_16x16x32_bf16 v[6:9], v[152:155], v[208:211], v[6:9]
	v_mfma_f32_16x16x32_bf16 v[2:5], v[160:163], v[208:211], v[2:5]
	s_setprio 0
	s_barrier
	s_add_i32 s95, s95, 2
	s_add_u32 s74, s74, 0x100
	s_addc_u32 s75, s75, 0
	s_add_u32 s71, s71, 0x100
	s_addc_u32 s94, s94, 0
	s_cmp_gt_u32 s95, 61
	s_cbranch_scc0 .LBB0_1116
	s_mov_b32 s100, 1
	s_and_b64 vcc, exec, s[10:11]
	s_cbranch_vccz .LBB0_1119
	s_lshl_b32 s4, s70, 8
	v_add_u32_e32 v194, s4, v204
	s_addk_i32 s4, 0xc000
	s_lshr_b32 s4, s4, 12
	s_ashr_i32 s5, s70, 5
	s_add_i32 s4, s4, 2
	s_cmp_lt_i32 s70, 64
	v_lshl_or_b32 v178, s20, 8, v206
	s_cselect_b32 s4, s5, s4
	v_ashrrev_i32_e32 v179, 31, v178
	s_ashr_i32 s5, s4, 31
	v_lshlrev_b64 v[180:181], 1, v[178:179]
	v_ashrrev_i32_e32 v195, 31, v194
	s_lshl_b64 s[4:5], s[4:5], 14
	v_lshl_add_u64 v[148:149], s[82:83], 0, v[180:181]
	v_lshlrev_b64 v[214:215], 11, v[194:195]
	s_add_u32 s4, s89, s4
	v_lshl_add_u64 v[112:113], v[148:149], 0, v[214:215]
	s_addc_u32 s5, s90, s5
	global_load_dwordx4 v[200:203], v[112:113], off
	global_load_dwordx4 v[210:213], v[112:113], off offset:256
	v_lshl_add_u64 v[112:113], v[178:179], 2, s[4:5]
	global_load_dwordx4 v[128:131], v[112:113], off
	global_load_dwordx4 v[124:127], v[112:113], off offset:16
	global_load_dwordx4 v[116:119], v[112:113], off offset:512
	s_nop 0
	global_load_dwordx4 v[112:115], v[112:113], off offset:528
	v_or_b32_e32 v190, 16, v194
	v_or_b32_e32 v186, 32, v194
	v_or_b32_e32 v182, 48, v194
	v_ashrrev_i32_e32 v191, 31, v190
	v_ashrrev_i32_e32 v187, 31, v186
	v_ashrrev_i32_e32 v183, 31, v182
	v_lshlrev_b64 v[192:193], 11, v[190:191]
	v_lshlrev_b64 v[188:189], 11, v[186:187]
	v_lshlrev_b64 v[184:185], 11, v[182:183]
	v_lshl_add_u64 v[150:151], v[148:149], 0, v[192:193]
	v_lshl_add_u64 v[152:153], v[148:149], 0, v[188:189]
	v_lshl_add_u64 v[148:149], v[148:149], 0, v[184:185]
	global_load_dwordx4 v[168:171], v[150:151], off
	global_load_dwordx4 v[164:167], v[150:151], off offset:256
	global_load_dwordx4 v[160:163], v[152:153], off
	global_load_dwordx4 v[156:159], v[152:153], off offset:256
	s_nop 0
	global_load_dwordx4 v[152:155], v[148:149], off
	s_nop 0
	global_load_dwordx4 v[148:151], v[148:149], off offset:256
	s_barrier
	s_branch .Lmy_g4a_afterload

.Lmy_sk11_pk:
	s_waitcnt lgkmcnt(0)
	s_setprio 1
	s_barrier
	v_mfma_f32_16x16x32_bf16 v[160:163], v[90:93], v[164:167], 0
	v_mfma_f32_16x16x32_bf16 v[156:159], v[100:103], v[164:167], 0
	v_mfma_f32_16x16x32_bf16 v[144:147], v[90:93], v[172:175], 0
	v_mfma_f32_16x16x32_bf16 v[140:143], v[100:103], v[172:175], 0
	v_mfma_f32_16x16x32_bf16 v[124:127], v[90:93], v[180:183], 0
	v_mfma_f32_16x16x32_bf16 v[116:119], v[100:103], v[180:183], 0
	v_mfma_f32_16x16x32_bf16 v[78:81], v[90:93], v[188:191], 0
	v_mfma_f32_16x16x32_bf16 v[74:77], v[100:103], v[188:191], 0
	v_mfma_f32_16x16x32_bf16 v[160:163], v[94:97], v[168:171], v[160:163]
	v_mfma_f32_16x16x32_bf16 v[156:159], v[104:107], v[168:171], v[156:159]
	v_mfma_f32_16x16x32_bf16 v[144:147], v[94:97], v[176:179], v[144:147]
	v_mfma_f32_16x16x32_bf16 v[140:143], v[104:107], v[176:179], v[140:143]
	v_mfma_f32_16x16x32_bf16 v[124:127], v[94:97], v[184:187], v[124:127]
	v_mfma_f32_16x16x32_bf16 v[116:119], v[104:107], v[184:187], v[116:119]
	v_mfma_f32_16x16x32_bf16 v[78:81], v[94:97], v[192:195], v[78:81]
	v_mfma_f32_16x16x32_bf16 v[74:77], v[104:107], v[192:195], v[74:77]
	s_setprio 0
	s_setprio 1
	v_mfma_f32_16x16x32_bf16 v[152:155], v[108:111], v[164:167], 0
	v_mfma_f32_16x16x32_bf16 v[148:151], v[120:123], v[164:167], 0
	v_mfma_f32_16x16x32_bf16 v[136:139], v[108:111], v[172:175], 0
	v_mfma_f32_16x16x32_bf16 v[132:135], v[120:123], v[172:175], 0
	v_mfma_f32_16x16x32_bf16 v[86:89], v[108:111], v[180:183], 0
	v_mfma_f32_16x16x32_bf16 v[82:85], v[120:123], v[180:183], 0
	v_mfma_f32_16x16x32_bf16 v[70:73], v[108:111], v[188:191], 0
	v_mfma_f32_16x16x32_bf16 v[66:69], v[120:123], v[188:191], 0
	v_mfma_f32_16x16x32_bf16 v[152:155], v[112:115], v[168:171], v[152:155]
	v_mfma_f32_16x16x32_bf16 v[148:151], v[128:131], v[168:171], v[148:151]
	v_mfma_f32_16x16x32_bf16 v[136:139], v[112:115], v[176:179], v[136:139]
	v_mfma_f32_16x16x32_bf16 v[132:135], v[128:131], v[176:179], v[132:135]
	v_mfma_f32_16x16x32_bf16 v[86:89], v[112:115], v[184:187], v[86:89]
	v_mfma_f32_16x16x32_bf16 v[82:85], v[128:131], v[184:187], v[82:85]
	v_mfma_f32_16x16x32_bf16 v[70:73], v[112:115], v[192:195], v[70:73]
	v_mfma_f32_16x16x32_bf16 v[66:69], v[128:131], v[192:195], v[66:69]
	s_setprio 0
	s_barrier
	s_add_i32 s4, s6, s91
	v_lshl_add_u64 v[200:201], s[74:75], 0, v[204:205]
	s_mov_b32 m0, s4
	ds_read_b128 v[164:167], v241 offset:16384
	ds_read_b128 v[168:171], v241 offset:17408
	ds_read_b128 v[172:175], v241 offset:18432
	ds_read_b128 v[176:179], v241 offset:19456
	ds_read_b128 v[180:183], v241 offset:20480
	ds_read_b128 v[184:187], v241 offset:21504
	ds_read_b128 v[188:191], v241 offset:22528
	ds_read_b128 v[192:195], v241 offset:23552
	global_load_lds_dwordx4 v[200:201], off
	s_add_i32 m0, s4, 0x2000
	s_add_u32 s4, s74, 0x100000
	v_lshl_add_u64 v[202:203], s[74:75], 0, v[208:209]
	s_addc_u32 s5, s75, 0
	s_add_i32 s6, s7, s91
	global_load_lds_dwordx4 v[202:203], off
	v_lshl_add_u64 v[210:211], s[4:5], 0, v[204:205]
	s_mov_b32 m0, s6
	v_lshl_add_u64 v[212:213], s[78:79], 0, v[206:207]
	global_load_lds_dwordx4 v[210:211], off
	v_lshl_add_u64 v[210:211], s[4:5], 0, v[208:209]
	s_add_i32 m0, s6, 0x2000
	s_nop 0
	global_load_lds_dwordx4 v[210:211], off
	v_lshl_add_u64 v[210:211], s[78:79], 0, v[98:99]
	s_mov_b32 m0, s44
	s_nop 0
	global_load_lds_dwordx4 v[210:211], off
	s_add_i32 m0, s44, 0x2000
	s_nop 0
	global_load_lds_dwordx4 v[212:213], off
	s_nop 0
	s_cmp_eq_u32 s100, 1
	s_cbranch_scc1 .Lmy_sk12_pk
	s_waitcnt vmcnt(8)
.Lmy_sk12_pk:
	s_waitcnt lgkmcnt(0)
	s_setprio 1
	s_barrier
	v_mfma_f32_16x16x32_bf16 v[62:65], v[90:93], v[164:167], 0
	v_mfma_f32_16x16x32_bf16 v[58:61], v[100:103], v[164:167], 0
	v_mfma_f32_16x16x32_bf16 v[46:49], v[90:93], v[172:175], 0
	v_mfma_f32_16x16x32_bf16 v[42:45], v[100:103], v[172:175], 0
	v_mfma_f32_16x16x32_bf16 v[30:33], v[90:93], v[180:183], 0
	v_mfma_f32_16x16x32_bf16 v[26:29], v[100:103], v[180:183], 0
	v_mfma_f32_16x16x32_bf16 v[14:17], v[90:93], v[188:191], 0
	v_mfma_f32_16x16x32_bf16 v[10:13], v[100:103], v[188:191], 0
	v_mfma_f32_16x16x32_bf16 v[62:65], v[94:97], v[168:171], v[62:65]
	v_mfma_f32_16x16x32_bf16 v[58:61], v[104:107], v[168:171], v[58:61]
	v_mfma_f32_16x16x32_bf16 v[46:49], v[94:97], v[176:179], v[46:49]
	v_mfma_f32_16x16x32_bf16 v[42:45], v[104:107], v[176:179], v[42:45]
	v_mfma_f32_16x16x32_bf16 v[30:33], v[94:97], v[184:187], v[30:33]
	v_mfma_f32_16x16x32_bf16 v[26:29], v[104:107], v[184:187], v[26:29]
	v_mfma_f32_16x16x32_bf16 v[14:17], v[94:97], v[192:195], v[14:17]
	v_mfma_f32_16x16x32_bf16 v[10:13], v[104:107], v[192:195], v[10:13]
	s_setprio 0
	s_setprio 1
	v_mfma_f32_16x16x32_bf16 v[54:57], v[108:111], v[164:167], 0
	v_mfma_f32_16x16x32_bf16 v[50:53], v[120:123], v[164:167], 0
	v_mfma_f32_16x16x32_bf16 v[38:41], v[108:111], v[172:175], 0
	v_mfma_f32_16x16x32_bf16 v[34:37], v[120:123], v[172:175], 0
	v_mfma_f32_16x16x32_bf16 v[22:25], v[108:111], v[180:183], 0
	v_mfma_f32_16x16x32_bf16 v[18:21], v[120:123], v[180:183], 0
	v_mfma_f32_16x16x32_bf16 v[6:9], v[108:111], v[188:191], 0
	v_mfma_f32_16x16x32_bf16 v[2:5], v[120:123], v[188:191], 0
	v_mfma_f32_16x16x32_bf16 v[54:57], v[112:115], v[168:171], v[54:57]
	v_mfma_f32_16x16x32_bf16 v[50:53], v[128:131], v[168:171], v[50:53]
	v_mfma_f32_16x16x32_bf16 v[38:41], v[112:115], v[176:179], v[38:41]
	v_mfma_f32_16x16x32_bf16 v[34:37], v[128:131], v[176:179], v[34:37]
	v_mfma_f32_16x16x32_bf16 v[22:25], v[112:115], v[184:187], v[22:25]
	v_mfma_f32_16x16x32_bf16 v[18:21], v[128:131], v[184:187], v[18:21]
	v_mfma_f32_16x16x32_bf16 v[6:9], v[112:115], v[192:195], v[6:9]
	v_mfma_f32_16x16x32_bf16 v[2:5], v[128:131], v[192:195], v[2:5]
	s_setprio 0
	s_barrier
	s_add_i32 s6, 0, 0x18000
	s_add_i32 s7, 0, 0x1c000
	v_add_u32_e32 v104, s6, v239
	v_add_u32_e32 v128, s7, v239
	ds_read_b128 v[90:93], v104
	ds_read_b128 v[94:97], v104 offset:1024
	ds_read_b128 v[100:103], v104 offset:2048
	ds_read_b128 v[104:107], v104 offset:3072
	ds_read_b128 v[108:111], v128
	ds_read_b128 v[112:115], v128 offset:1024
	ds_read_b128 v[120:123], v128 offset:2048
	ds_read_b128 v[128:131], v128 offset:3072
	s_add_u32 s4, s78, 0x100000
	s_addc_u32 s5, s79, 0
	v_lshl_add_u64 v[214:215], s[4:5], 0, v[98:99]
	s_add_i32 m0, s44, 0x4000
	ds_read_b128 v[164:167], v241 offset:32768
	ds_read_b128 v[168:171], v241 offset:33792
	ds_read_b128 v[172:175], v241 offset:34816
	ds_read_b128 v[176:179], v241 offset:35840
	ds_read_b128 v[180:183], v241 offset:36864
	ds_read_b128 v[184:187], v241 offset:37888
	ds_read_b128 v[188:191], v241 offset:38912
	ds_read_b128 v[192:195], v241 offset:39936
	global_load_lds_dwordx4 v[214:215], off
	v_lshl_add_u64 v[214:215], s[4:5], 0, v[206:207]
	s_add_i32 m0, s44, 0x6000
	s_nop 0
	global_load_lds_dwordx4 v[214:215], off
	s_waitcnt vmcnt(8)
	s_waitcnt lgkmcnt(0)
	s_setprio 1
	s_barrier
	v_mfma_f32_16x16x32_bf16 v[160:163], v[90:93], v[164:167], v[160:163]
	v_mfma_f32_16x16x32_bf16 v[156:159], v[100:103], v[164:167], v[156:159]
	v_mfma_f32_16x16x32_bf16 v[144:147], v[90:93], v[172:175], v[144:147]
	v_mfma_f32_16x16x32_bf16 v[140:143], v[100:103], v[172:175], v[140:143]
	v_mfma_f32_16x16x32_bf16 v[124:127], v[90:93], v[180:183], v[124:127]
	v_mfma_f32_16x16x32_bf16 v[116:119], v[100:103], v[180:183], v[116:119]
	v_mfma_f32_16x16x32_bf16 v[78:81], v[90:93], v[188:191], v[78:81]
	v_mfma_f32_16x16x32_bf16 v[74:77], v[100:103], v[188:191], v[74:77]
	v_mfma_f32_16x16x32_bf16 v[160:163], v[94:97], v[168:171], v[160:163]
	v_mfma_f32_16x16x32_bf16 v[156:159], v[104:107], v[168:171], v[156:159]
	v_mfma_f32_16x16x32_bf16 v[144:147], v[94:97], v[176:179], v[144:147]
	v_mfma_f32_16x16x32_bf16 v[140:143], v[104:107], v[176:179], v[140:143]
	v_mfma_f32_16x16x32_bf16 v[124:127], v[94:97], v[184:187], v[124:127]
	v_mfma_f32_16x16x32_bf16 v[116:119], v[104:107], v[184:187], v[116:119]
	v_mfma_f32_16x16x32_bf16 v[78:81], v[94:97], v[192:195], v[78:81]
	v_mfma_f32_16x16x32_bf16 v[74:77], v[104:107], v[192:195], v[74:77]
	s_setprio 0
	s_setprio 1
	v_mfma_f32_16x16x32_bf16 v[152:155], v[108:111], v[164:167], v[152:155]
	v_mfma_f32_16x16x32_bf16 v[148:151], v[120:123], v[164:167], v[148:151]
	v_mfma_f32_16x16x32_bf16 v[136:139], v[108:111], v[172:175], v[136:139]
	v_mfma_f32_16x16x32_bf16 v[132:135], v[120:123], v[172:175], v[132:135]
	v_mfma_f32_16x16x32_bf16 v[86:89], v[108:111], v[180:183], v[86:89]
	v_mfma_f32_16x16x32_bf16 v[82:85], v[120:123], v[180:183], v[82:85]
	v_mfma_f32_16x16x32_bf16 v[70:73], v[108:111], v[188:191], v[70:73]
	v_mfma_f32_16x16x32_bf16 v[66:69], v[120:123], v[188:191], v[66:69]
	v_mfma_f32_16x16x32_bf16 v[152:155], v[112:115], v[168:171], v[152:155]
	v_mfma_f32_16x16x32_bf16 v[148:151], v[128:131], v[168:171], v[148:151]
	v_mfma_f32_16x16x32_bf16 v[136:139], v[112:115], v[176:179], v[136:139]
	v_mfma_f32_16x16x32_bf16 v[132:135], v[128:131], v[176:179], v[132:135]
	v_mfma_f32_16x16x32_bf16 v[86:89], v[112:115], v[184:187], v[86:89]
	v_mfma_f32_16x16x32_bf16 v[82:85], v[128:131], v[184:187], v[82:85]
	v_mfma_f32_16x16x32_bf16 v[70:73], v[112:115], v[192:195], v[70:73]
	v_mfma_f32_16x16x32_bf16 v[66:69], v[128:131], v[192:195], v[66:69]
	s_setprio 0
	s_barrier
	s_add_i32 s4, s6, s91
	v_lshl_add_u64 v[200:201], v[200:201], 0, s[42:43]
	s_mov_b32 m0, s4
	ds_read_b128 v[164:167], v241 offset:49152
	ds_read_b128 v[168:171], v241 offset:50176
	ds_read_b128 v[172:175], v241 offset:51200
	ds_read_b128 v[176:179], v241 offset:52224
	ds_read_b128 v[180:183], v241 offset:53248
	ds_read_b128 v[184:187], v241 offset:54272
	ds_read_b128 v[188:191], v241 offset:55296
	ds_read_b128 v[192:195], v241 offset:56320
	global_load_lds_dwordx4 v[200:201], off
	s_add_i32 m0, s4, 0x2000
	s_add_u32 s4, s74, 0x100080
	v_lshl_add_u64 v[200:201], v[202:203], 0, s[42:43]
	s_addc_u32 s5, s75, 0
	s_add_i32 s6, s7, s91
	global_load_lds_dwordx4 v[200:201], off
	v_lshl_add_u64 v[200:201], s[4:5], 0, v[204:205]
	s_mov_b32 m0, s6
	s_nop 0
	global_load_lds_dwordx4 v[200:201], off
	v_lshl_add_u64 v[200:201], s[4:5], 0, v[208:209]
	s_add_i32 m0, s6, 0x2000
	s_nop 0
	global_load_lds_dwordx4 v[200:201], off
	v_lshl_add_u64 v[200:201], v[210:211], 0, s[42:43]
	s_add_i32 m0, s44, 0x8000
	s_nop 0
	global_load_lds_dwordx4 v[200:201], off
	v_lshl_add_u64 v[200:201], v[212:213], 0, s[42:43]
	s_add_i32 m0, s44, 0xa000
	s_nop 0
	global_load_lds_dwordx4 v[200:201], off
	s_nop 0
	s_waitcnt vmcnt(8)
	s_waitcnt lgkmcnt(0)
	s_setprio 1
	s_barrier
	v_mfma_f32_16x16x32_bf16 v[62:65], v[90:93], v[164:167], v[62:65]
	v_mfma_f32_16x16x32_bf16 v[58:61], v[100:103], v[164:167], v[58:61]
	v_mfma_f32_16x16x32_bf16 v[46:49], v[90:93], v[172:175], v[46:49]
	v_mfma_f32_16x16x32_bf16 v[42:45], v[100:103], v[172:175], v[42:45]
	v_mfma_f32_16x16x32_bf16 v[30:33], v[90:93], v[180:183], v[30:33]
	v_mfma_f32_16x16x32_bf16 v[26:29], v[100:103], v[180:183], v[26:29]
	v_mfma_f32_16x16x32_bf16 v[14:17], v[90:93], v[188:191], v[14:17]
	v_mfma_f32_16x16x32_bf16 v[10:13], v[100:103], v[188:191], v[10:13]
	v_mfma_f32_16x16x32_bf16 v[62:65], v[94:97], v[168:171], v[62:65]
	v_mfma_f32_16x16x32_bf16 v[58:61], v[104:107], v[168:171], v[58:61]
	v_mfma_f32_16x16x32_bf16 v[46:49], v[94:97], v[176:179], v[46:49]
	v_mfma_f32_16x16x32_bf16 v[42:45], v[104:107], v[176:179], v[42:45]
	v_mfma_f32_16x16x32_bf16 v[30:33], v[94:97], v[184:187], v[30:33]
	v_mfma_f32_16x16x32_bf16 v[26:29], v[104:107], v[184:187], v[26:29]
	v_mfma_f32_16x16x32_bf16 v[14:17], v[94:97], v[192:195], v[14:17]
	v_mfma_f32_16x16x32_bf16 v[10:13], v[104:107], v[192:195], v[10:13]
	s_setprio 0
	s_setprio 1
	v_mfma_f32_16x16x32_bf16 v[54:57], v[108:111], v[164:167], v[54:57]
	v_mfma_f32_16x16x32_bf16 v[50:53], v[120:123], v[164:167], v[50:53]
	v_mfma_f32_16x16x32_bf16 v[38:41], v[108:111], v[172:175], v[38:41]
	v_mfma_f32_16x16x32_bf16 v[34:37], v[120:123], v[172:175], v[34:37]
	v_mfma_f32_16x16x32_bf16 v[22:25], v[108:111], v[180:183], v[22:25]
	v_mfma_f32_16x16x32_bf16 v[18:21], v[120:123], v[180:183], v[18:21]
	v_mfma_f32_16x16x32_bf16 v[6:9], v[108:111], v[188:191], v[6:9]
	v_mfma_f32_16x16x32_bf16 v[2:5], v[120:123], v[188:191], v[2:5]
	v_mfma_f32_16x16x32_bf16 v[54:57], v[112:115], v[168:171], v[54:57]
	v_mfma_f32_16x16x32_bf16 v[50:53], v[128:131], v[168:171], v[50:53]
	v_mfma_f32_16x16x32_bf16 v[38:41], v[112:115], v[176:179], v[38:41]
	v_mfma_f32_16x16x32_bf16 v[34:37], v[128:131], v[176:179], v[34:37]
	v_mfma_f32_16x16x32_bf16 v[22:25], v[112:115], v[184:187], v[22:25]
	v_mfma_f32_16x16x32_bf16 v[18:21], v[128:131], v[184:187], v[18:21]
	v_mfma_f32_16x16x32_bf16 v[6:9], v[112:115], v[192:195], v[6:9]
	v_mfma_f32_16x16x32_bf16 v[2:5], v[128:131], v[192:195], v[2:5]
	s_setprio 0
	s_barrier
	s_mov_b32 s100, 0
	s_add_i32 s95, s95, 2
	s_add_u32 s70, s70, 0x100
	s_addc_u32 s71, s71, 0
	s_add_u32 s69, s69, 0x100
	s_addc_u32 s94, s94, 0
	s_cmp_gt_u32 s95, 61
.LBB0_1172:
	s_add_u32 s4, s70, 0xfff00080
	s_addc_u32 s5, s71, -1
	s_add_i32 s6, 0, 0x10000
	s_cmp_eq_u32 s95, 60
	s_cselect_b32 s79, s18, s5
	s_cselect_b32 s78, s27, s4
	s_cselect_b32 s75, s15, s94
	s_cselect_b32 s74, s57, s69
	s_add_i32 s7, 0, 0x14000
	v_add_u32_e32 v104, s6, v239
	v_add_u32_e32 v128, s7, v239
	ds_read_b128 v[90:93], v104
	ds_read_b128 v[94:97], v104 offset:1024
	ds_read_b128 v[100:103], v104 offset:2048
	ds_read_b128 v[104:107], v104 offset:3072
	ds_read_b128 v[108:111], v128
	ds_read_b128 v[112:115], v128 offset:1024
	ds_read_b128 v[120:123], v128 offset:2048
	ds_read_b128 v[128:131], v128 offset:3072
	s_add_i32 s44, s91, 0
	v_lshl_add_u64 v[200:201], s[70:71], 0, v[98:99]
	s_add_i32 m0, s44, 0xc000
	ds_read_b128 v[164:167], v241
	ds_read_b128 v[168:171], v241 offset:1024
	ds_read_b128 v[172:175], v241 offset:2048
	ds_read_b128 v[176:179], v241 offset:3072
	ds_read_b128 v[180:183], v241 offset:4096
	ds_read_b128 v[184:187], v241 offset:5120
	ds_read_b128 v[188:191], v241 offset:6144
	ds_read_b128 v[192:195], v241 offset:7168
	global_load_lds_dwordx4 v[200:201], off
	v_lshl_add_u64 v[200:201], s[70:71], 0, v[206:207]
	s_add_i32 m0, s44, 0xe000
	s_nop 0
	global_load_lds_dwordx4 v[200:201], off
	s_nop 0
	s_waitcnt vmcnt(8)
	s_waitcnt lgkmcnt(0)
	s_setprio 1
	s_barrier
	v_mfma_f32_16x16x32_bf16 v[160:163], v[90:93], v[164:167], v[160:163]
	v_mfma_f32_16x16x32_bf16 v[156:159], v[100:103], v[164:167], v[156:159]
	v_mfma_f32_16x16x32_bf16 v[144:147], v[90:93], v[172:175], v[144:147]
	v_mfma_f32_16x16x32_bf16 v[140:143], v[100:103], v[172:175], v[140:143]
	v_mfma_f32_16x16x32_bf16 v[124:127], v[90:93], v[180:183], v[124:127]
	v_mfma_f32_16x16x32_bf16 v[116:119], v[100:103], v[180:183], v[116:119]
	v_mfma_f32_16x16x32_bf16 v[78:81], v[90:93], v[188:191], v[78:81]
	v_mfma_f32_16x16x32_bf16 v[74:77], v[100:103], v[188:191], v[74:77]
	v_mfma_f32_16x16x32_bf16 v[160:163], v[94:97], v[168:171], v[160:163]
	v_mfma_f32_16x16x32_bf16 v[156:159], v[104:107], v[168:171], v[156:159]
	v_mfma_f32_16x16x32_bf16 v[144:147], v[94:97], v[176:179], v[144:147]
	v_mfma_f32_16x16x32_bf16 v[140:143], v[104:107], v[176:179], v[140:143]
	v_mfma_f32_16x16x32_bf16 v[124:127], v[94:97], v[184:187], v[124:127]
	v_mfma_f32_16x16x32_bf16 v[116:119], v[104:107], v[184:187], v[116:119]
	v_mfma_f32_16x16x32_bf16 v[78:81], v[94:97], v[192:195], v[78:81]
	v_mfma_f32_16x16x32_bf16 v[74:77], v[104:107], v[192:195], v[74:77]
	s_setprio 0
	s_setprio 1
	v_mfma_f32_16x16x32_bf16 v[152:155], v[108:111], v[164:167], v[152:155]
	v_mfma_f32_16x16x32_bf16 v[148:151], v[120:123], v[164:167], v[148:151]
	v_mfma_f32_16x16x32_bf16 v[136:139], v[108:111], v[172:175], v[136:139]
	v_mfma_f32_16x16x32_bf16 v[132:135], v[120:123], v[172:175], v[132:135]
	v_mfma_f32_16x16x32_bf16 v[86:89], v[108:111], v[180:183], v[86:89]
	v_mfma_f32_16x16x32_bf16 v[82:85], v[120:123], v[180:183], v[82:85]
	v_mfma_f32_16x16x32_bf16 v[70:73], v[108:111], v[188:191], v[70:73]
	v_mfma_f32_16x16x32_bf16 v[66:69], v[120:123], v[188:191], v[66:69]
	v_mfma_f32_16x16x32_bf16 v[152:155], v[112:115], v[168:171], v[152:155]
	v_mfma_f32_16x16x32_bf16 v[148:151], v[128:131], v[168:171], v[148:151]
	v_mfma_f32_16x16x32_bf16 v[136:139], v[112:115], v[176:179], v[136:139]
	v_mfma_f32_16x16x32_bf16 v[132:135], v[128:131], v[176:179], v[132:135]
	v_mfma_f32_16x16x32_bf16 v[86:89], v[112:115], v[184:187], v[86:89]
	v_mfma_f32_16x16x32_bf16 v[82:85], v[128:131], v[184:187], v[82:85]
	v_mfma_f32_16x16x32_bf16 v[70:73], v[112:115], v[192:195], v[70:73]
	v_mfma_f32_16x16x32_bf16 v[66:69], v[128:131], v[192:195], v[66:69]
	s_setprio 0
	s_barrier
	s_add_i32 s4, s6, s91
	v_lshl_add_u64 v[200:201], s[74:75], 0, v[204:205]
	s_mov_b32 m0, s4
	ds_read_b128 v[164:167], v241 offset:16384
	ds_read_b128 v[168:171], v241 offset:17408
	ds_read_b128 v[172:175], v241 offset:18432
	ds_read_b128 v[176:179], v241 offset:19456
	ds_read_b128 v[180:183], v241 offset:20480
	ds_read_b128 v[184:187], v241 offset:21504
	ds_read_b128 v[188:191], v241 offset:22528
	ds_read_b128 v[192:195], v241 offset:23552
	global_load_lds_dwordx4 v[200:201], off
	s_add_i32 m0, s4, 0x2000
	s_add_u32 s4, s74, 0x100000
	v_lshl_add_u64 v[202:203], s[74:75], 0, v[208:209]
	s_addc_u32 s5, s75, 0
	s_add_i32 s6, s7, s91
	global_load_lds_dwordx4 v[202:203], off
	v_lshl_add_u64 v[210:211], s[4:5], 0, v[204:205]
	s_mov_b32 m0, s6
	v_lshl_add_u64 v[212:213], s[78:79], 0, v[206:207]
	global_load_lds_dwordx4 v[210:211], off
	v_lshl_add_u64 v[210:211], s[4:5], 0, v[208:209]
	s_add_i32 m0, s6, 0x2000
	s_nop 0
	global_load_lds_dwordx4 v[210:211], off
	v_lshl_add_u64 v[210:211], s[78:79], 0, v[98:99]
	s_mov_b32 m0, s44
	s_nop 0
	global_load_lds_dwordx4 v[210:211], off
	s_add_i32 m0, s44, 0x2000
	s_nop 0
	global_load_lds_dwordx4 v[212:213], off
	s_nop 0
	s_waitcnt vmcnt(8)
	s_waitcnt lgkmcnt(0)
	s_setprio 1
	s_barrier
	v_mfma_f32_16x16x32_bf16 v[62:65], v[90:93], v[164:167], v[62:65]
	v_mfma_f32_16x16x32_bf16 v[58:61], v[100:103], v[164:167], v[58:61]
	v_mfma_f32_16x16x32_bf16 v[46:49], v[90:93], v[172:175], v[46:49]
	v_mfma_f32_16x16x32_bf16 v[42:45], v[100:103], v[172:175], v[42:45]
	v_mfma_f32_16x16x32_bf16 v[30:33], v[90:93], v[180:183], v[30:33]
	v_mfma_f32_16x16x32_bf16 v[26:29], v[100:103], v[180:183], v[26:29]
	v_mfma_f32_16x16x32_bf16 v[14:17], v[90:93], v[188:191], v[14:17]
	v_mfma_f32_16x16x32_bf16 v[10:13], v[100:103], v[188:191], v[10:13]
	v_mfma_f32_16x16x32_bf16 v[62:65], v[94:97], v[168:171], v[62:65]
	v_mfma_f32_16x16x32_bf16 v[58:61], v[104:107], v[168:171], v[58:61]
	v_mfma_f32_16x16x32_bf16 v[46:49], v[94:97], v[176:179], v[46:49]
	v_mfma_f32_16x16x32_bf16 v[42:45], v[104:107], v[176:179], v[42:45]
	v_mfma_f32_16x16x32_bf16 v[30:33], v[94:97], v[184:187], v[30:33]
	v_mfma_f32_16x16x32_bf16 v[26:29], v[104:107], v[184:187], v[26:29]
	v_mfma_f32_16x16x32_bf16 v[14:17], v[94:97], v[192:195], v[14:17]
	v_mfma_f32_16x16x32_bf16 v[10:13], v[104:107], v[192:195], v[10:13]
	s_setprio 0
	s_setprio 1
	v_mfma_f32_16x16x32_bf16 v[54:57], v[108:111], v[164:167], v[54:57]
	v_mfma_f32_16x16x32_bf16 v[50:53], v[120:123], v[164:167], v[50:53]
	v_mfma_f32_16x16x32_bf16 v[38:41], v[108:111], v[172:175], v[38:41]
	v_mfma_f32_16x16x32_bf16 v[34:37], v[120:123], v[172:175], v[34:37]
	v_mfma_f32_16x16x32_bf16 v[22:25], v[108:111], v[180:183], v[22:25]
	v_mfma_f32_16x16x32_bf16 v[18:21], v[120:123], v[180:183], v[18:21]
	v_mfma_f32_16x16x32_bf16 v[6:9], v[108:111], v[188:191], v[6:9]
	v_mfma_f32_16x16x32_bf16 v[2:5], v[120:123], v[188:191], v[2:5]
	v_mfma_f32_16x16x32_bf16 v[54:57], v[112:115], v[168:171], v[54:57]
	v_mfma_f32_16x16x32_bf16 v[50:53], v[128:131], v[168:171], v[50:53]
	v_mfma_f32_16x16x32_bf16 v[38:41], v[112:115], v[176:179], v[38:41]
	v_mfma_f32_16x16x32_bf16 v[34:37], v[128:131], v[176:179], v[34:37]
	v_mfma_f32_16x16x32_bf16 v[22:25], v[112:115], v[184:187], v[22:25]
	v_mfma_f32_16x16x32_bf16 v[18:21], v[128:131], v[184:187], v[18:21]
	v_mfma_f32_16x16x32_bf16 v[6:9], v[112:115], v[192:195], v[6:9]
	v_mfma_f32_16x16x32_bf16 v[2:5], v[128:131], v[192:195], v[2:5]
	s_setprio 0
	s_barrier
	s_add_i32 s6, 0, 0x18000
	s_add_i32 s7, 0, 0x1c000
	v_add_u32_e32 v104, s6, v239
	v_add_u32_e32 v128, s7, v239
	ds_read_b128 v[90:93], v104
	ds_read_b128 v[94:97], v104 offset:1024
	ds_read_b128 v[100:103], v104 offset:2048
	ds_read_b128 v[104:107], v104 offset:3072
	ds_read_b128 v[108:111], v128
	ds_read_b128 v[112:115], v128 offset:1024
	ds_read_b128 v[120:123], v128 offset:2048
	ds_read_b128 v[128:131], v128 offset:3072
	s_add_u32 s4, s78, 0x100000
	s_addc_u32 s5, s79, 0
	v_lshl_add_u64 v[214:215], s[4:5], 0, v[98:99]
	s_add_i32 m0, s44, 0x4000
	ds_read_b128 v[164:167], v241 offset:32768
	ds_read_b128 v[168:171], v241 offset:33792
	ds_read_b128 v[172:175], v241 offset:34816
	ds_read_b128 v[176:179], v241 offset:35840
	ds_read_b128 v[180:183], v241 offset:36864
	ds_read_b128 v[184:187], v241 offset:37888
	ds_read_b128 v[188:191], v241 offset:38912
	ds_read_b128 v[192:195], v241 offset:39936
	global_load_lds_dwordx4 v[214:215], off
	v_lshl_add_u64 v[214:215], s[4:5], 0, v[206:207]
	s_add_i32 m0, s44, 0x6000
	s_nop 0
	global_load_lds_dwordx4 v[214:215], off
	s_waitcnt vmcnt(8)
	s_waitcnt lgkmcnt(0)
	s_setprio 1
	s_barrier
	v_mfma_f32_16x16x32_bf16 v[160:163], v[90:93], v[164:167], v[160:163]
	v_mfma_f32_16x16x32_bf16 v[156:159], v[100:103], v[164:167], v[156:159]
	v_mfma_f32_16x16x32_bf16 v[144:147], v[90:93], v[172:175], v[144:147]
	v_mfma_f32_16x16x32_bf16 v[140:143], v[100:103], v[172:175], v[140:143]
	v_mfma_f32_16x16x32_bf16 v[124:127], v[90:93], v[180:183], v[124:127]
	v_mfma_f32_16x16x32_bf16 v[116:119], v[100:103], v[180:183], v[116:119]
	v_mfma_f32_16x16x32_bf16 v[78:81], v[90:93], v[188:191], v[78:81]
	v_mfma_f32_16x16x32_bf16 v[74:77], v[100:103], v[188:191], v[74:77]
	v_mfma_f32_16x16x32_bf16 v[160:163], v[94:97], v[168:171], v[160:163]
	v_mfma_f32_16x16x32_bf16 v[156:159], v[104:107], v[168:171], v[156:159]
	v_mfma_f32_16x16x32_bf16 v[144:147], v[94:97], v[176:179], v[144:147]
	v_mfma_f32_16x16x32_bf16 v[140:143], v[104:107], v[176:179], v[140:143]
	v_mfma_f32_16x16x32_bf16 v[124:127], v[94:97], v[184:187], v[124:127]
	v_mfma_f32_16x16x32_bf16 v[116:119], v[104:107], v[184:187], v[116:119]
	v_mfma_f32_16x16x32_bf16 v[78:81], v[94:97], v[192:195], v[78:81]
	v_mfma_f32_16x16x32_bf16 v[74:77], v[104:107], v[192:195], v[74:77]
	s_setprio 0
	s_setprio 1
	v_mfma_f32_16x16x32_bf16 v[152:155], v[108:111], v[164:167], v[152:155]
	v_mfma_f32_16x16x32_bf16 v[148:151], v[120:123], v[164:167], v[148:151]
	v_mfma_f32_16x16x32_bf16 v[136:139], v[108:111], v[172:175], v[136:139]
	v_mfma_f32_16x16x32_bf16 v[132:135], v[120:123], v[172:175], v[132:135]
	v_mfma_f32_16x16x32_bf16 v[86:89], v[108:111], v[180:183], v[86:89]
	v_mfma_f32_16x16x32_bf16 v[82:85], v[120:123], v[180:183], v[82:85]
	v_mfma_f32_16x16x32_bf16 v[70:73], v[108:111], v[188:191], v[70:73]
	v_mfma_f32_16x16x32_bf16 v[66:69], v[120:123], v[188:191], v[66:69]
	v_mfma_f32_16x16x32_bf16 v[152:155], v[112:115], v[168:171], v[152:155]
	v_mfma_f32_16x16x32_bf16 v[148:151], v[128:131], v[168:171], v[148:151]
	v_mfma_f32_16x16x32_bf16 v[136:139], v[112:115], v[176:179], v[136:139]
	v_mfma_f32_16x16x32_bf16 v[132:135], v[128:131], v[176:179], v[132:135]
	v_mfma_f32_16x16x32_bf16 v[86:89], v[112:115], v[184:187], v[86:89]
	v_mfma_f32_16x16x32_bf16 v[82:85], v[128:131], v[184:187], v[82:85]
	v_mfma_f32_16x16x32_bf16 v[70:73], v[112:115], v[192:195], v[70:73]
	v_mfma_f32_16x16x32_bf16 v[66:69], v[128:131], v[192:195], v[66:69]
	s_setprio 0
	s_barrier
	s_add_i32 s4, s6, s91
	v_lshl_add_u64 v[200:201], v[200:201], 0, s[42:43]
	s_mov_b32 m0, s4
	ds_read_b128 v[164:167], v241 offset:49152
	ds_read_b128 v[168:171], v241 offset:50176
	ds_read_b128 v[172:175], v241 offset:51200
	ds_read_b128 v[176:179], v241 offset:52224
	ds_read_b128 v[180:183], v241 offset:53248
	ds_read_b128 v[184:187], v241 offset:54272
	ds_read_b128 v[188:191], v241 offset:55296
	ds_read_b128 v[192:195], v241 offset:56320
	global_load_lds_dwordx4 v[200:201], off
	s_add_i32 m0, s4, 0x2000
	s_add_u32 s4, s74, 0x100080
	v_lshl_add_u64 v[200:201], v[202:203], 0, s[42:43]
	s_addc_u32 s5, s75, 0
	s_add_i32 s6, s7, s91
	global_load_lds_dwordx4 v[200:201], off
	v_lshl_add_u64 v[200:201], s[4:5], 0, v[204:205]
	s_mov_b32 m0, s6
	s_nop 0
	global_load_lds_dwordx4 v[200:201], off
	v_lshl_add_u64 v[200:201], s[4:5], 0, v[208:209]
	s_add_i32 m0, s6, 0x2000
	s_nop 0
	global_load_lds_dwordx4 v[200:201], off
	v_lshl_add_u64 v[200:201], v[210:211], 0, s[42:43]
	s_add_i32 m0, s44, 0x8000
	s_nop 0
	global_load_lds_dwordx4 v[200:201], off
	v_lshl_add_u64 v[200:201], v[212:213], 0, s[42:43]
	s_add_i32 m0, s44, 0xa000
	s_nop 0
	global_load_lds_dwordx4 v[200:201], off
	s_nop 0
	s_waitcnt vmcnt(8)
	s_waitcnt lgkmcnt(0)
	s_setprio 1
	s_barrier
	v_mfma_f32_16x16x32_bf16 v[62:65], v[90:93], v[164:167], v[62:65]
	v_mfma_f32_16x16x32_bf16 v[58:61], v[100:103], v[164:167], v[58:61]
	v_mfma_f32_16x16x32_bf16 v[46:49], v[90:93], v[172:175], v[46:49]
	v_mfma_f32_16x16x32_bf16 v[42:45], v[100:103], v[172:175], v[42:45]
	v_mfma_f32_16x16x32_bf16 v[30:33], v[90:93], v[180:183], v[30:33]
	v_mfma_f32_16x16x32_bf16 v[26:29], v[100:103], v[180:183], v[26:29]
	v_mfma_f32_16x16x32_bf16 v[14:17], v[90:93], v[188:191], v[14:17]
	v_mfma_f32_16x16x32_bf16 v[10:13], v[100:103], v[188:191], v[10:13]
	v_mfma_f32_16x16x32_bf16 v[62:65], v[94:97], v[168:171], v[62:65]
	v_mfma_f32_16x16x32_bf16 v[58:61], v[104:107], v[168:171], v[58:61]
	v_mfma_f32_16x16x32_bf16 v[46:49], v[94:97], v[176:179], v[46:49]
	v_mfma_f32_16x16x32_bf16 v[42:45], v[104:107], v[176:179], v[42:45]
	v_mfma_f32_16x16x32_bf16 v[30:33], v[94:97], v[184:187], v[30:33]
	v_mfma_f32_16x16x32_bf16 v[26:29], v[104:107], v[184:187], v[26:29]
	v_mfma_f32_16x16x32_bf16 v[14:17], v[94:97], v[192:195], v[14:17]
	v_mfma_f32_16x16x32_bf16 v[10:13], v[104:107], v[192:195], v[10:13]
	s_setprio 0
	s_setprio 1
	v_mfma_f32_16x16x32_bf16 v[54:57], v[108:111], v[164:167], v[54:57]
	v_mfma_f32_16x16x32_bf16 v[50:53], v[120:123], v[164:167], v[50:53]
	v_mfma_f32_16x16x32_bf16 v[38:41], v[108:111], v[172:175], v[38:41]
	v_mfma_f32_16x16x32_bf16 v[34:37], v[120:123], v[172:175], v[34:37]
	v_mfma_f32_16x16x32_bf16 v[22:25], v[108:111], v[180:183], v[22:25]
	v_mfma_f32_16x16x32_bf16 v[18:21], v[120:123], v[180:183], v[18:21]
	v_mfma_f32_16x16x32_bf16 v[6:9], v[108:111], v[188:191], v[6:9]
	v_mfma_f32_16x16x32_bf16 v[2:5], v[120:123], v[188:191], v[2:5]
	v_mfma_f32_16x16x32_bf16 v[54:57], v[112:115], v[168:171], v[54:57]
	v_mfma_f32_16x16x32_bf16 v[50:53], v[128:131], v[168:171], v[50:53]
	v_mfma_f32_16x16x32_bf16 v[38:41], v[112:115], v[176:179], v[38:41]
	v_mfma_f32_16x16x32_bf16 v[34:37], v[128:131], v[176:179], v[34:37]
	v_mfma_f32_16x16x32_bf16 v[22:25], v[112:115], v[184:187], v[22:25]
	v_mfma_f32_16x16x32_bf16 v[18:21], v[128:131], v[184:187], v[18:21]
	v_mfma_f32_16x16x32_bf16 v[6:9], v[112:115], v[192:195], v[6:9]
	v_mfma_f32_16x16x32_bf16 v[2:5], v[128:131], v[192:195], v[2:5]
	s_setprio 0
	s_barrier
	s_add_i32 s95, s95, 2
	s_add_u32 s70, s70, 0x100
	s_addc_u32 s71, s71, 0
	s_add_u32 s69, s69, 0x100
	s_addc_u32 s94, s94, 0
	s_cmp_gt_u32 s95, 61
	s_cbranch_scc0 .LBB0_1172
	s_mov_b32 s100, 1
	s_and_b64 vcc, exec, s[10:11]
	s_cbranch_vccz .LBB0_1175
	s_lshl_b32 s6, s68, 8
	s_add_i32 s5, s6, 0xffffc000
	s_lshr_b32 s5, s5, 12
	s_ashr_i32 s4, s68, 5
	s_add_i32 s5, s5, 2
	s_cmp_lt_i32 s68, 64
	s_cselect_b32 s4, s4, s5
	s_ashr_i32 s5, s4, 31
	s_lshl_b64 s[4:5], s[4:5], 14
	v_lshl_or_b32 v164, s56, 8, v240
	s_add_u32 s44, s89, s4
	s_addc_u32 s45, s90, s5
	v_ashrrev_i32_e32 v165, 31, v164
	v_add_u32_e32 v222, s6, v238
	s_add_u32 s4, s8, s4
	v_lshlrev_b64 v[210:211], 1, v[164:165]
	v_ashrrev_i32_e32 v223, 31, v222
	v_lshlrev_b64 v[90:91], 2, v[164:165]
	s_addc_u32 s5, s9, s5
	v_lshl_add_u64 v[164:165], s[82:83], 0, v[210:211]
	v_lshlrev_b64 v[226:227], 11, v[222:223]
	v_lshl_add_u64 v[92:93], s[44:45], 0, v[90:91]
	v_lshl_add_u64 v[94:95], s[4:5], 0, v[90:91]
	v_lshl_add_u64 v[166:167], v[164:165], 0, v[226:227]
	global_load_dwordx4 v[120:123], v[92:93], off offset:16
	global_load_dwordx4 v[128:131], v[92:93], off
	global_load_dwordx4 v[108:111], v[94:95], off offset:16
	global_load_dwordx4 v[112:115], v[94:95], off
	global_load_dwordx4 v[100:103], v[92:93], off offset:528
	global_load_dwordx4 v[104:107], v[92:93], off offset:512
	s_nop 0
	global_load_dwordx4 v[90:93], v[94:95], off offset:528
	s_nop 0
	global_load_dwordx4 v[94:97], v[94:95], off offset:512
	s_nop 0
	global_load_dwordx4 v[192:195], v[166:167], off
	global_load_dwordx4 v[188:191], v[166:167], off offset:256
	v_or_b32_e32 v220, 16, v222
	v_ashrrev_i32_e32 v221, 31, v220
	v_or_b32_e32 v216, 32, v222
	v_or_b32_e32 v212, 48, v222
	v_lshlrev_b64 v[224:225], 11, v[220:221]
	v_ashrrev_i32_e32 v217, 31, v216
	v_ashrrev_i32_e32 v213, 31, v212
	v_lshl_add_u64 v[166:167], v[164:165], 0, v[224:225]
	v_lshlrev_b64 v[218:219], 11, v[216:217]
	v_lshlrev_b64 v[214:215], 11, v[212:213]
	global_load_dwordx4 v[184:187], v[166:167], off
	global_load_dwordx4 v[180:183], v[166:167], off offset:256
	v_lshl_add_u64 v[166:167], v[164:165], 0, v[218:219]
	v_lshl_add_u64 v[164:165], v[164:165], 0, v[214:215]
	global_load_dwordx4 v[176:179], v[166:167], off
	global_load_dwordx4 v[172:175], v[166:167], off offset:256
	global_load_dwordx4 v[168:171], v[164:165], off
	s_nop 0
	global_load_dwordx4 v[164:167], v[164:165], off offset:256
	s_barrier
	s_branch .Lmy_g4b_afterload
